# DYN GEMM: no vmcnt(0) drain at unit head (ticket consumed at publish, global_atomic); cvt_tile LDS 16B XOR swizzle; cvt tile-ticket atomic software-pipelined + ds_ broadcast
# speedup vs baseline: 1.0022x; 1.0022x over previous
; __device__ __forceinline__ unsigned hw_xcc_id() { return (unsigned)__builtin_amdgcn_s_getreg((3 << 11) | 20) & 0xFu; }
; template <class Epi, bool DYN = false>
; __device__ __forceinline__ void gemm_phase(LAS unsigned char* lds, const Gemm g, const Epi& E, int wave, unsigned* ctr = nullptr) {
;     ...
;     const int xcd = (int)(hw_xcc_id() & 7u); int ticket = 0;
;     auto rng_cnt = [&](int x) { const int q = S.nwg / NXCD, r = S.nwg % NXCD; return q + (x < r ? 1 : 0); };
;     auto rng_start = [&](int x) { const int q = S.nwg / NXCD, r = S.nwg % NXCD; return x < r ? x * (q + 1) : r * (q + 1) + (x - r) * q; };
;     auto decode = [&](int wgid, Unit& u) { const int nig = WGM * S.nN, gid = wgid / nig, fm = gid * WGM, gsz = (S.nM - fm) < WGM ? (S.nM - fm) : WGM; u.pm = fm + ((wgid % nig) % gsz); u.pn = (wgid % nig) / gsz; u.b = 0; };
;     auto issue = [&]() { if (tid == 0) ticket = (int)__hip_atomic_fetch_add(ctr + xcd * 16, 1u, __ATOMIC_RELAXED, __HIP_MEMORY_SCOPE_AGENT); };
;     auto publish = [&](int si) { if (tid == 0) { int wg = -1;
;             if (ticket < rng_cnt(xcd)) wg = rng_start(xcd) + ticket;
;             else { for (int k = 1; k < 8; ++k) { const int x2 = (xcd + k) & 7; const int t2 = (int)__hip_atomic_fetch_add(ctr + x2 * 16, 1u, __ATOMIC_RELAXED, __HIP_MEMORY_SCOPE_AGENT); if (t2 < rng_cnt(x2)) { wg = rng_start(x2) + t2; break; } } }
;             slot[si] = wg; } };
;     if (DYN) { issue(); publish(0); __syncthreads(); const int w0 = __builtin_amdgcn_readfirstlane(slot[0]); if (w0 < 0) return; decode(w0, cur); issue(); }
.LBB0_30:
	s_andn2_b64 vcc, exec, s[0:1]
	s_cbranch_vccnz .LBB0_101
	v_readlane_b32 s0, v254, 43
	s_mulk_i32 s0, 0x300
	v_mbcnt_hi_u32_b32 v0, -1, v222
	s_add_i32 s44, s0, 0x180
	s_mov_b32 s0, s80
	v_or_b32_e32 v192, s92, v0
	s_getreg_b32 s5, hwreg(HW_REG_XCC_ID, 0, 4)
	v_readlane_b32 s1, v254, 44
	s_ashr_i32 s45, s44, 31
	s_waitcnt vmcnt(0) lgkmcnt(0)
	v_mov_b32_e32 v193, 0
	v_readfirstlane_b32 s17, v192
	s_and_b32 s4, s5, 7
	v_cmp_eq_u32_e64 s[2:3], 0, v192
	s_mov_b64 s[0:1], exec
	s_nop 0
	v_writelane_b32 v255, s2, 0
	s_nop 1
	v_writelane_b32 v255, s3, 1
	s_and_b64 s[2:3], s[0:1], s[2:3]
	s_mov_b64 exec, s[2:3]
	s_cbranch_execz .LBB0_33
	s_lshl_b32 s2, s4, 6
	v_readlane_b32 s3, v254, 47
	s_add_u32 s6, s3, s2
	v_readlane_b32 s2, v254, 48
	s_addc_u32 s7, s2, 0
	s_lshl_b64 s[2:3], s[44:45], 2
	s_add_u32 s2, s6, s2
	s_addc_u32 s3, s7, s3
	s_waitcnt lgkmcnt(0)
	v_mov_b64_e32 v[2:3], s[2:3]
	global_atomic_add v193, v[2:3], v224, off sc0

; template <class Epi, bool DYN = false>
; __device__ __forceinline__ void gemm_phase(LAS unsigned char* lds, const Gemm g, const Epi& E, int wave, unsigned* ctr = nullptr) {
;     ...
;     auto issue = [&]() { if (tid == 0) ticket = (int)__hip_atomic_fetch_add(ctr + xcd * 16, 1u, __ATOMIC_RELAXED, __HIP_MEMORY_SCOPE_AGENT); };
;     auto publish = [&](int si) { if (tid == 0) { int wg = -1;
;             if (ticket < rng_cnt(xcd)) wg = rng_start(xcd) + ticket;
;             else { for (int k = 1; k < 8; ++k) { const int x2 = (xcd + k) & 7; const int t2 = (int)__hip_atomic_fetch_add(ctr + x2 * 16, 1u, __ATOMIC_RELAXED, __HIP_MEMORY_SCOPE_AGENT); if (t2 < rng_cnt(x2)) { wg = rng_start(x2) + t2; break; } } }
;             slot[si] = wg; } };
;     if (DYN) { issue(); publish(0); __syncthreads(); const int w0 = __builtin_amdgcn_readfirstlane(slot[0]); if (w0 < 0) return; decode(w0, cur); issue(); }
.LBB0_65:
	s_or_b64 exec, exec, s[40:41]
	v_readlane_b32 s0, v254, 3
	s_waitcnt lgkmcnt(0)
	s_barrier
	v_mov_b32_e32 v0, s0
	ds_read_b32 v0, v0
	s_waitcnt lgkmcnt(0)
	v_readfirstlane_b32 s2, v0
	s_cmp_lt_i32 s2, 0
	s_cbranch_scc1 .LBB0_101
	s_mov_b64 s[0:1], exec
	v_readlane_b32 s6, v255, 0
	v_readlane_b32 s7, v255, 1
	s_and_b64 s[6:7], s[0:1], s[6:7]
	s_mov_b64 exec, s[6:7]
	s_cbranch_execz .LBB0_68
	s_lshl_b32 s3, s4, 6
	v_readlane_b32 s6, v254, 47
	s_add_u32 s3, s6, s3
	v_readlane_b32 s6, v254, 48
	s_addc_u32 s8, s6, 0
	s_lshl_b64 s[6:7], s[44:45], 2
	s_add_u32 s6, s3, s6
	s_addc_u32 s7, s8, s7
	v_mov_b64_e32 v[2:3], s[6:7]
	s_waitcnt vmcnt(0)
	global_atomic_add v193, v[2:3], v224, off sc0

; template <class Epi, bool DYN = false>
; __device__ __forceinline__ void gemm_phase(LAS unsigned char* lds, const Gemm g, const Epi& E, int wave, unsigned* ctr = nullptr) {
;     ...
;     for (;;) {
;         bool has_next = DYN ? false : S.next(ui + 1, nxt);
;         const char* nA = has_next ? (const char*)(g.A + (size_t)nxt.b * g.sA) + (size_t)nxt.pm * tstepA : cA; const char* nB = has_next ? (const char*)(g.Bt + (size_t)nxt.b * g.sB) + (size_t)nxt.pn * tstepB : cB;
;         for (int t = 0; t < nt; t += 2) {
;             const bool last = (t == nt - 2);
;             if (DYN && last) { const int nw = __builtin_amdgcn_readfirstlane(slot[(ui + 1) & 1]); has_next = nw >= 0;
;                 if (has_next) { decode(nw, nxt); nA = (const char*)g.A + (size_t)nxt.pm * tstepA; nB = (const char*)g.Bt + (size_t)nxt.pn * tstepB; } }
;             const char* a1 = cA + (size_t)(t + 1) * kstepA;
;             const char* a2 = last ? nA : cA + (size_t)(t + 2) * kstepA; const char* b2 = last ? nB : cB + (size_t)(t + 2) * kstepB;
;             const char* a3 = a2 + kstepA; const char* b3 = b2 + kstepB;
.LBB0_73:
	s_andn2_b32 s0, 1, s4
	s_lshl_b32 s0, s0, 2
	s_add_i32 s5, s0, 0
	s_add_i32 s5, s5, 0x20040
	s_add_u32 s6, s46, 0x10000
	s_waitcnt lgkmcnt(0)
	s_addc_u32 s7, s47, 0
	s_mov_b64 s[54:55], 0
	s_mov_b32 s8, -2
	s_mov_b64 s[72:73], 0x100
	v_mov_b64_e32 v[188:189], v[186:187]
	v_mov_b64_e32 v[190:191], v[184:185]
	s_mov_b64 s[64:65], s[46:47]
	s_mov_b64 s[78:79], s[68:69]
	s_branch .LBB0_82

; #define PG8_STAGE(bufoff, gbase, voff) do { _Pragma("unroll") for (int _i = 0; _i < 2; ++_i) \
;         __builtin_amdgcn_global_load_lds((const unsigned*)((const char*)(gbase) + (voff)[_i]), (LAS unsigned*)(lds + (bufoff) + ldsw + _i * 8192), 16, 0, 0); } while (0)
; #define PG8_LDA(dst, b, h) do { _Pragma("unroll") for (int m = 0; m < 4; ++m) _Pragma("unroll") for (int k = 0; k < 2; ++k) dst[m][k] = *(const LAS bf16x8*)(lds + PG8_SA(b, h) + aoff + m * 2048 + k * 1024); } while (0)
; #define PG8_LDB(dst, b, h) do { _Pragma("unroll") for (int n = 0; n < 2; ++n) _Pragma("unroll") for (int k = 0; k < 2; ++k) dst[n][k] = *(const LAS bf16x8*)(lds + PG8_SB(b, h) + boff + n * 2048 + k * 1024); } while (0)
; #define PG8_MMA(ai, bj, At, Bt) do { __builtin_amdgcn_s_setprio(1); _Pragma("unroll") for (int m = 0; m < 4; ++m) _Pragma("unroll") for (int n = 0; n < 2; ++n) _Pragma("unroll") for (int k = 0; k < 2; ++k) \
;         acc[ai][bj][m][n] = __builtin_amdgcn_mfma_f32_16x16x32_bf16(Bt[n][k], At[m][k], acc[ai][bj][m][n], 0, 0, 0); __builtin_amdgcn_s_setprio(0); } while (0)
; #define PG8_WAIT_L(n) asm volatile("s_waitcnt lgkmcnt(" #n ")" ::: "memory")
; #define PG8_BAR __builtin_amdgcn_s_barrier()
; #define PG8_SCHED __builtin_amdgcn_sched_barrier(0)
; template <class Epi, bool DYN = false>
; __device__ __forceinline__ void gemm_phase(LAS unsigned char* lds, const Gemm g, const Epi& E, int wave, unsigned* ctr = nullptr) {
;     ...
;             const char* a1 = cA + (size_t)(t + 1) * kstepA;
;             const char* a2 = last ? nA : cA + (size_t)(t + 2) * kstepA; const char* b2 = last ? nB : cB + (size_t)(t + 2) * kstepB;
;             const char* a3 = a2 + kstepA; const char* b3 = b2 + kstepB;
;             PG8_LDB(B0, 0, 0); PG8_SCHED; PG8_LDA(At, 0, 0); PG8_STAGE(PG8_SA(1, 1), a1 + hstepA, voffA);
;             PG8_WAIT_L(8); PG8_BAR; PG8_WAIT_L(0); PG8_MMA(0, 0, At, B0); PG8_BAR; PG8_SCHED;
;             PG8_LDB(B1, 0, 1); PG8_STAGE(PG8_SB(0, 0), b2, voffB);
;             PG8_BAR; PG8_WAIT_L(0); PG8_MMA(0, 1, At, B1); PG8_BAR;
;             PG8_LDA(At, 0, 1); PG8_STAGE(PG8_SA(0, 0), a2, voffA);
;             PG8_BAR; PG8_WAIT_L(0); PG8_MMA(1, 0, At, B0); PG8_BAR; PG8_SCHED;
.LBB0_86:
	s_add_i32 s8, s8, 2
	s_add_u32 s9, s68, s72
	s_addc_u32 s10, s69, s73
	s_and_b64 s[0:1], s[38:39], exec
	s_cselect_b32 s75, s79, s10
	s_cselect_b32 s74, s78, s9
	s_add_i32 s9, 0, 0x10000
	v_add_u32_e32 v142, s9, v200
	ds_read_b128 v[130:133], v142
	ds_read_b128 v[134:137], v142 offset:1024
	ds_read_b128 v[138:141], v142 offset:2048
	ds_read_b128 v[142:145], v142 offset:3072
	s_and_b64 s[0:1], s[38:39], exec
	s_cselect_b32 s71, s65, s7
	s_cselect_b32 s70, s64, s6
	v_lshl_add_u64 v[196:197], s[68:69], 0, v[188:189]
	s_add_i32 m0, s18, 0xc000
	ds_read_b128 v[146:149], v202
	ds_read_b128 v[150:153], v202 offset:1024
	ds_read_b128 v[154:157], v202 offset:2048
	ds_read_b128 v[158:161], v202 offset:3072
	ds_read_b128 v[162:165], v202 offset:4096
	ds_read_b128 v[166:169], v202 offset:5120
	ds_read_b128 v[170:173], v202 offset:6144
	ds_read_b128 v[174:177], v202 offset:7168
	global_load_lds_dwordx4 v[196:197], off
	v_lshl_add_u64 v[196:197], s[68:69], 0, v[190:191]
	s_add_i32 m0, s18, 0xe000
	s_nop 0
	global_load_lds_dwordx4 v[196:197], off
	s_waitcnt lgkmcnt(8)
	s_barrier
	s_waitcnt lgkmcnt(0)
	s_setprio 1
	s_waitcnt lgkmcnt(0)
	v_mfma_f32_16x16x32_bf16 v[126:129], v[130:133], v[146:149], v[126:129]
	v_mfma_f32_16x16x32_bf16 v[122:125], v[138:141], v[146:149], v[122:125]
	v_mfma_f32_16x16x32_bf16 v[118:121], v[130:133], v[154:157], v[118:121]
	v_mfma_f32_16x16x32_bf16 v[114:117], v[138:141], v[154:157], v[114:117]
	v_mfma_f32_16x16x32_bf16 v[110:113], v[130:133], v[162:165], v[110:113]
	v_mfma_f32_16x16x32_bf16 v[106:109], v[138:141], v[162:165], v[106:109]
	v_mfma_f32_16x16x32_bf16 v[102:105], v[130:133], v[170:173], v[102:105]
	v_mfma_f32_16x16x32_bf16 v[94:97], v[138:141], v[170:173], v[94:97]
	v_mfma_f32_16x16x32_bf16 v[126:129], v[134:137], v[150:153], v[126:129]
	v_mfma_f32_16x16x32_bf16 v[122:125], v[142:145], v[150:153], v[122:125]
	v_mfma_f32_16x16x32_bf16 v[118:121], v[134:137], v[158:161], v[118:121]
	v_mfma_f32_16x16x32_bf16 v[114:117], v[142:145], v[158:161], v[114:117]
	v_mfma_f32_16x16x32_bf16 v[110:113], v[134:137], v[166:169], v[110:113]
	v_mfma_f32_16x16x32_bf16 v[106:109], v[142:145], v[166:169], v[106:109]
	v_mfma_f32_16x16x32_bf16 v[102:105], v[134:137], v[174:177], v[102:105]
	v_mfma_f32_16x16x32_bf16 v[94:97], v[142:145], v[174:177], v[94:97]
	s_setprio 0
	s_barrier
	s_add_i32 s10, 0, 0x14000
	s_add_i32 s0, s9, s17
	v_add_u32_e32 v212, s10, v200
	v_lshl_add_u64 v[216:217], s[70:71], 0, v[178:179]
	s_mov_b32 m0, s0
	ds_read_b128 v[196:199], v212
	ds_read_b128 v[204:207], v212 offset:1024
	ds_read_b128 v[208:211], v212 offset:2048
	ds_read_b128 v[212:215], v212 offset:3072
	global_load_lds_dwordx4 v[216:217], off
	v_lshl_add_u64 v[216:217], s[70:71], 0, v[182:183]
	s_add_i32 m0, s0, 0x2000
	s_nop 0
	global_load_lds_dwordx4 v[216:217], off
	s_barrier
	s_waitcnt lgkmcnt(0)
	s_setprio 1
	s_waitcnt lgkmcnt(0)
	v_mfma_f32_16x16x32_bf16 v[86:89], v[196:199], v[146:149], v[86:89]
	v_mfma_f32_16x16x32_bf16 v[78:81], v[208:211], v[146:149], v[78:81]
	v_mfma_f32_16x16x32_bf16 v[70:73], v[196:199], v[154:157], v[70:73]
	v_mfma_f32_16x16x32_bf16 v[62:65], v[208:211], v[154:157], v[62:65]
	v_mfma_f32_16x16x32_bf16 v[54:57], v[196:199], v[162:165], v[54:57]
	v_mfma_f32_16x16x32_bf16 v[46:49], v[208:211], v[162:165], v[46:49]
	v_mfma_f32_16x16x32_bf16 v[42:45], v[196:199], v[170:173], v[42:45]
	v_mfma_f32_16x16x32_bf16 v[38:41], v[208:211], v[170:173], v[38:41]
	v_mfma_f32_16x16x32_bf16 v[86:89], v[204:207], v[150:153], v[86:89]
	v_mfma_f32_16x16x32_bf16 v[78:81], v[212:215], v[150:153], v[78:81]
	v_mfma_f32_16x16x32_bf16 v[70:73], v[204:207], v[158:161], v[70:73]
	v_mfma_f32_16x16x32_bf16 v[62:65], v[212:215], v[158:161], v[62:65]
	v_mfma_f32_16x16x32_bf16 v[54:57], v[204:207], v[166:169], v[54:57]
	v_mfma_f32_16x16x32_bf16 v[46:49], v[212:215], v[166:169], v[46:49]
	v_mfma_f32_16x16x32_bf16 v[42:45], v[204:207], v[174:177], v[42:45]
	v_mfma_f32_16x16x32_bf16 v[38:41], v[212:215], v[174:177], v[38:41]
	s_setprio 0
	s_mov_b32 m0, s18
	v_lshl_add_u64 v[216:217], s[74:75], 0, v[0:1]
	s_barrier
	ds_read_b128 v[146:149], v202 offset:16384
	ds_read_b128 v[150:153], v202 offset:17408
	ds_read_b128 v[154:157], v202 offset:18432
	ds_read_b128 v[158:161], v202 offset:19456
	ds_read_b128 v[162:165], v202 offset:20480
	ds_read_b128 v[166:169], v202 offset:21504
	ds_read_b128 v[170:173], v202 offset:22528
	ds_read_b128 v[174:177], v202 offset:23552
	global_load_lds_dwordx4 v[216:217], off
	v_lshl_add_u64 v[218:219], s[74:75], 0, v[180:181]
	s_mov_b32 m0, s19
	s_nop 0
	global_load_lds_dwordx4 v[218:219], off
	s_barrier
	s_waitcnt lgkmcnt(0)
	s_setprio 1
	s_waitcnt lgkmcnt(0)
	v_mfma_f32_16x16x32_bf16 v[34:37], v[130:133], v[146:149], v[34:37]
	v_mfma_f32_16x16x32_bf16 v[26:29], v[138:141], v[146:149], v[26:29]
	v_mfma_f32_16x16x32_bf16 v[22:25], v[130:133], v[154:157], v[22:25]
	v_mfma_f32_16x16x32_bf16 v[18:21], v[138:141], v[154:157], v[18:21]
	v_mfma_f32_16x16x32_bf16 v[14:17], v[130:133], v[162:165], v[14:17]
	v_mfma_f32_16x16x32_bf16 v[10:13], v[138:141], v[162:165], v[10:13]
	v_mfma_f32_16x16x32_bf16 v[6:9], v[130:133], v[170:173], v[6:9]
	v_mfma_f32_16x16x32_bf16 v[2:5], v[138:141], v[170:173], v[2:5]
	v_mfma_f32_16x16x32_bf16 v[34:37], v[134:137], v[150:153], v[34:37]
	v_mfma_f32_16x16x32_bf16 v[26:29], v[142:145], v[150:153], v[26:29]
	v_mfma_f32_16x16x32_bf16 v[22:25], v[134:137], v[158:161], v[22:25]
	v_mfma_f32_16x16x32_bf16 v[18:21], v[142:145], v[158:161], v[18:21]
	v_mfma_f32_16x16x32_bf16 v[14:17], v[134:137], v[166:169], v[14:17]
	v_mfma_f32_16x16x32_bf16 v[10:13], v[142:145], v[166:169], v[10:13]
	v_mfma_f32_16x16x32_bf16 v[6:9], v[134:137], v[174:177], v[6:9]
	v_mfma_f32_16x16x32_bf16 v[2:5], v[142:145], v[174:177], v[2:5]
	s_setprio 0
	s_barrier
; #define PG8_STAGE(bufoff, gbase, voff) do { _Pragma("unroll") for (int _i = 0; _i < 2; ++_i) \
;         __builtin_amdgcn_global_load_lds((const unsigned*)((const char*)(gbase) + (voff)[_i]), (LAS unsigned*)(lds + (bufoff) + ldsw + _i * 8192), 16, 0, 0); } while (0)
; #define PG8_LDA(dst, b, h) do { _Pragma("unroll") for (int m = 0; m < 4; ++m) _Pragma("unroll") for (int k = 0; k < 2; ++k) dst[m][k] = *(const LAS bf16x8*)(lds + PG8_SA(b, h) + aoff + m * 2048 + k * 1024); } while (0)
; #define PG8_LDB(dst, b, h) do { _Pragma("unroll") for (int n = 0; n < 2; ++n) _Pragma("unroll") for (int k = 0; k < 2; ++k) dst[n][k] = *(const LAS bf16x8*)(lds + PG8_SB(b, h) + boff + n * 2048 + k * 1024); } while (0)
; #define PG8_MMA(ai, bj, At, Bt) do { __builtin_amdgcn_s_setprio(1); _Pragma("unroll") for (int m = 0; m < 4; ++m) _Pragma("unroll") for (int n = 0; n < 2; ++n) _Pragma("unroll") for (int k = 0; k < 2; ++k) \
;         acc[ai][bj][m][n] = __builtin_amdgcn_mfma_f32_16x16x32_bf16(Bt[n][k], At[m][k], acc[ai][bj][m][n], 0, 0, 0); __builtin_amdgcn_s_setprio(0); } while (0)
; #define PG8_WAIT_V(n) asm volatile("s_waitcnt vmcnt(" #n ")" ::: "memory")
; #define PG8_WAIT_L(n) asm volatile("s_waitcnt lgkmcnt(" #n ")" ::: "memory")
; #define PG8_BAR __builtin_amdgcn_s_barrier()
; #define PG8_SCHED __builtin_amdgcn_sched_barrier(0)
; template <class Epi, bool DYN = false>
; __device__ __forceinline__ void gemm_phase(LAS unsigned char* lds, const Gemm g, const Epi& E, int wave, unsigned* ctr = nullptr) {
;     ...
;             PG8_STAGE(PG8_SB(0, 1), b2 + hstepB, voffB);
;             PG8_WAIT_V(6); PG8_BAR; PG8_MMA(1, 1, At, B1); PG8_BAR;
;             PG8_LDB(B0, 1, 0); PG8_SCHED; PG8_LDA(At, 1, 0); PG8_STAGE(PG8_SA(0, 1), a2 + hstepA, voffA);
;             PG8_WAIT_L(8); PG8_BAR; PG8_WAIT_L(0); PG8_MMA(0, 0, At, B0); PG8_BAR; PG8_SCHED;
;             PG8_LDB(B1, 1, 1); PG8_STAGE(PG8_SB(1, 0), b3, voffB);
;             PG8_BAR; PG8_WAIT_L(0); PG8_MMA(0, 1, At, B1); PG8_BAR;
	s_add_u32 s0, s70, 0x4000
	s_addc_u32 s1, s71, 0
	s_add_i32 s9, s10, s17
	v_lshl_add_u64 v[130:131], s[0:1], 0, v[178:179]
	s_mov_b32 m0, s9
	s_nop 0
	global_load_lds_dwordx4 v[130:131], off
	v_lshl_add_u64 v[130:131], s[0:1], 0, v[182:183]
	s_add_i32 m0, s9, 0x2000
	s_nop 0
	global_load_lds_dwordx4 v[130:131], off
	s_waitcnt vmcnt(6)
	s_barrier
	s_setprio 1
	v_mfma_f32_16x16x32_bf16 v[98:101], v[196:199], v[146:149], v[98:101]
	v_mfma_f32_16x16x32_bf16 v[90:93], v[208:211], v[146:149], v[90:93]
	v_mfma_f32_16x16x32_bf16 v[82:85], v[196:199], v[154:157], v[82:85]
	v_mfma_f32_16x16x32_bf16 v[74:77], v[208:211], v[154:157], v[74:77]
	v_mfma_f32_16x16x32_bf16 v[66:69], v[196:199], v[162:165], v[66:69]
	v_mfma_f32_16x16x32_bf16 v[58:61], v[208:211], v[162:165], v[58:61]
	v_mfma_f32_16x16x32_bf16 v[50:53], v[196:199], v[170:173], v[50:53]
	v_mfma_f32_16x16x32_bf16 v[30:33], v[208:211], v[170:173], v[30:33]
	v_mfma_f32_16x16x32_bf16 v[98:101], v[204:207], v[150:153], v[98:101]
	v_mfma_f32_16x16x32_bf16 v[90:93], v[212:215], v[150:153], v[90:93]
	v_mfma_f32_16x16x32_bf16 v[82:85], v[204:207], v[158:161], v[82:85]
	v_mfma_f32_16x16x32_bf16 v[74:77], v[212:215], v[158:161], v[74:77]
	v_mfma_f32_16x16x32_bf16 v[66:69], v[204:207], v[166:169], v[66:69]
	v_mfma_f32_16x16x32_bf16 v[58:61], v[212:215], v[166:169], v[58:61]
	v_mfma_f32_16x16x32_bf16 v[50:53], v[204:207], v[174:177], v[50:53]
	v_mfma_f32_16x16x32_bf16 v[30:33], v[212:215], v[174:177], v[30:33]
	s_setprio 0
	s_add_i32 s9, 0, 0x18000
	v_add_u32_e32 v130, s9, v200
	s_barrier
	ds_read_b128 v[196:199], v130
	ds_read_b128 v[204:207], v130 offset:1024
	ds_read_b128 v[208:211], v130 offset:2048
	ds_read_b128 v[212:215], v130 offset:3072
	s_add_u32 s0, s74, 0x80000
	s_addc_u32 s1, s75, 0
	s_mov_b32 m0, s28
	v_lshl_add_u64 v[130:131], s[0:1], 0, v[0:1]
	ds_read_b128 v[146:149], v202 offset:32768
	ds_read_b128 v[150:153], v202 offset:33792
	ds_read_b128 v[154:157], v202 offset:34816
	ds_read_b128 v[158:161], v202 offset:35840
	ds_read_b128 v[162:165], v202 offset:36864
	ds_read_b128 v[166:169], v202 offset:37888
	ds_read_b128 v[170:173], v202 offset:38912
	ds_read_b128 v[174:177], v202 offset:39936
	global_load_lds_dwordx4 v[130:131], off
	v_lshl_add_u64 v[130:131], s[0:1], 0, v[180:181]
	s_mov_b32 m0, s33
	s_nop 0
	global_load_lds_dwordx4 v[130:131], off
	s_waitcnt lgkmcnt(8)
	s_barrier
	s_waitcnt lgkmcnt(0)
	s_setprio 1
	s_waitcnt lgkmcnt(0)
	v_mfma_f32_16x16x32_bf16 v[126:129], v[196:199], v[146:149], v[126:129]
	v_mfma_f32_16x16x32_bf16 v[122:125], v[208:211], v[146:149], v[122:125]
	v_mfma_f32_16x16x32_bf16 v[118:121], v[196:199], v[154:157], v[118:121]
	v_mfma_f32_16x16x32_bf16 v[114:117], v[208:211], v[154:157], v[114:117]
	v_mfma_f32_16x16x32_bf16 v[110:113], v[196:199], v[162:165], v[110:113]
	v_mfma_f32_16x16x32_bf16 v[106:109], v[208:211], v[162:165], v[106:109]
	v_mfma_f32_16x16x32_bf16 v[102:105], v[196:199], v[170:173], v[102:105]
	v_mfma_f32_16x16x32_bf16 v[94:97], v[208:211], v[170:173], v[94:97]
	v_mfma_f32_16x16x32_bf16 v[126:129], v[204:207], v[150:153], v[126:129]
	v_mfma_f32_16x16x32_bf16 v[122:125], v[212:215], v[150:153], v[122:125]
	v_mfma_f32_16x16x32_bf16 v[118:121], v[204:207], v[158:161], v[118:121]
	v_mfma_f32_16x16x32_bf16 v[114:117], v[212:215], v[158:161], v[114:117]
	v_mfma_f32_16x16x32_bf16 v[110:113], v[204:207], v[166:169], v[110:113]
	v_mfma_f32_16x16x32_bf16 v[106:109], v[212:215], v[166:169], v[106:109]
	v_mfma_f32_16x16x32_bf16 v[102:105], v[204:207], v[174:177], v[102:105]
	v_mfma_f32_16x16x32_bf16 v[94:97], v[212:215], v[174:177], v[94:97]
	s_setprio 0
	s_barrier
	s_add_u32 s0, s70, 0x8000
	v_add_u32_e32 v130, 0, v200
	s_addc_u32 s1, s71, 0
	s_add_i32 s9, s9, s17
	v_add_u32_e32 v142, 0x1c000, v130
	v_lshl_add_u64 v[220:221], s[0:1], 0, v[178:179]
	s_mov_b32 m0, s9
	ds_read_b128 v[130:133], v142
	ds_read_b128 v[134:137], v142 offset:1024
	ds_read_b128 v[138:141], v142 offset:2048
	ds_read_b128 v[142:145], v142 offset:3072
	global_load_lds_dwordx4 v[220:221], off
	v_lshl_add_u64 v[220:221], s[0:1], 0, v[182:183]
	s_add_i32 m0, s9, 0x2000
	s_nop 0
	global_load_lds_dwordx4 v[220:221], off
	s_barrier
	s_waitcnt lgkmcnt(0)
	s_setprio 1
	s_waitcnt lgkmcnt(0)
	v_mfma_f32_16x16x32_bf16 v[86:89], v[130:133], v[146:149], v[86:89]
	v_mfma_f32_16x16x32_bf16 v[78:81], v[138:141], v[146:149], v[78:81]
	v_mfma_f32_16x16x32_bf16 v[70:73], v[130:133], v[154:157], v[70:73]
	v_mfma_f32_16x16x32_bf16 v[62:65], v[138:141], v[154:157], v[62:65]
	v_mfma_f32_16x16x32_bf16 v[54:57], v[130:133], v[162:165], v[54:57]
	v_mfma_f32_16x16x32_bf16 v[46:49], v[138:141], v[162:165], v[46:49]
	v_mfma_f32_16x16x32_bf16 v[42:45], v[130:133], v[170:173], v[42:45]
	v_mfma_f32_16x16x32_bf16 v[38:41], v[138:141], v[170:173], v[38:41]
	v_mfma_f32_16x16x32_bf16 v[86:89], v[134:137], v[150:153], v[86:89]
	v_mfma_f32_16x16x32_bf16 v[78:81], v[142:145], v[150:153], v[78:81]
	v_mfma_f32_16x16x32_bf16 v[70:73], v[134:137], v[158:161], v[70:73]
	v_mfma_f32_16x16x32_bf16 v[62:65], v[142:145], v[158:161], v[62:65]
	v_mfma_f32_16x16x32_bf16 v[54:57], v[134:137], v[166:169], v[54:57]
	v_mfma_f32_16x16x32_bf16 v[46:49], v[142:145], v[166:169], v[46:49]
	v_mfma_f32_16x16x32_bf16 v[42:45], v[134:137], v[174:177], v[42:45]
	v_mfma_f32_16x16x32_bf16 v[38:41], v[142:145], v[174:177], v[38:41]
	s_setprio 0
	s_mov_b32 m0, s41
	v_lshl_add_u64 v[216:217], v[216:217], 0, s[52:53]
	s_barrier
; #define PG8_STAGE(bufoff, gbase, voff) do { _Pragma("unroll") for (int _i = 0; _i < 2; ++_i) \
;         __builtin_amdgcn_global_load_lds((const unsigned*)((const char*)(gbase) + (voff)[_i]), (LAS unsigned*)(lds + (bufoff) + ldsw + _i * 8192), 16, 0, 0); } while (0)
; #define PG8_LDA(dst, b, h) do { _Pragma("unroll") for (int m = 0; m < 4; ++m) _Pragma("unroll") for (int k = 0; k < 2; ++k) dst[m][k] = *(const LAS bf16x8*)(lds + PG8_SA(b, h) + aoff + m * 2048 + k * 1024); } while (0)
; #define PG8_MMA(ai, bj, At, Bt) do { __builtin_amdgcn_s_setprio(1); _Pragma("unroll") for (int m = 0; m < 4; ++m) _Pragma("unroll") for (int n = 0; n < 2; ++n) _Pragma("unroll") for (int k = 0; k < 2; ++k) \
;         acc[ai][bj][m][n] = __builtin_amdgcn_mfma_f32_16x16x32_bf16(Bt[n][k], At[m][k], acc[ai][bj][m][n], 0, 0, 0); __builtin_amdgcn_s_setprio(0); } while (0)
; #define PG8_WAIT_L(n) asm volatile("s_waitcnt lgkmcnt(" #n ")" ::: "memory")
; #define PG8_BAR __builtin_amdgcn_s_barrier()
; #define PG8_SCHED __builtin_amdgcn_sched_barrier(0)
; template <class Epi, bool DYN = false>
; __device__ __forceinline__ void gemm_phase(LAS unsigned char* lds, const Gemm g, const Epi& E, int wave, unsigned* ctr = nullptr) {
;     ...
;     auto publish = [&](int si) { if (tid == 0) { int wg = -1;
;             if (ticket < rng_cnt(xcd)) wg = rng_start(xcd) + ticket;
;             else { for (int k = 1; k < 8; ++k) { const int x2 = (xcd + k) & 7; const int t2 = (int)__hip_atomic_fetch_add(ctr + x2 * 16, 1u, __ATOMIC_RELAXED, __HIP_MEMORY_SCOPE_AGENT); if (t2 < rng_cnt(x2)) { wg = rng_start(x2) + t2; break; } } }
;     ...
;             PG8_LDA(At, 1, 1); PG8_STAGE(PG8_SA(1, 0), a3, voffA);
;             PG8_BAR; PG8_WAIT_L(0); PG8_MMA(1, 0, At, B0); PG8_BAR; PG8_SCHED;
;             if (DYN && t == 0) publish((ui + 1) & 1);
	ds_read_b128 v[170:173], v202 offset:49152
	ds_read_b128 v[174:177], v202 offset:50176
	ds_read_b128 v[162:165], v202 offset:51200
	ds_read_b128 v[166:169], v202 offset:52224
	ds_read_b128 v[154:157], v202 offset:53248
	ds_read_b128 v[158:161], v202 offset:54272
	ds_read_b128 v[146:149], v202 offset:55296
	ds_read_b128 v[150:153], v202 offset:56320
	global_load_lds_dwordx4 v[216:217], off
	v_lshl_add_u64 v[216:217], v[218:219], 0, s[52:53]
	s_mov_b32 m0, s43
	s_nop 0
	global_load_lds_dwordx4 v[216:217], off
	s_barrier
	s_waitcnt lgkmcnt(0)
	s_setprio 1
	s_waitcnt lgkmcnt(0)
	v_mfma_f32_16x16x32_bf16 v[34:37], v[196:199], v[170:173], v[34:37]
	v_mfma_f32_16x16x32_bf16 v[26:29], v[208:211], v[170:173], v[26:29]
	v_mfma_f32_16x16x32_bf16 v[22:25], v[196:199], v[162:165], v[22:25]
	v_mfma_f32_16x16x32_bf16 v[18:21], v[208:211], v[162:165], v[18:21]
	v_mfma_f32_16x16x32_bf16 v[14:17], v[196:199], v[154:157], v[14:17]
	v_mfma_f32_16x16x32_bf16 v[10:13], v[208:211], v[154:157], v[10:13]
	v_mfma_f32_16x16x32_bf16 v[6:9], v[196:199], v[146:149], v[6:9]
	v_mfma_f32_16x16x32_bf16 v[2:5], v[208:211], v[146:149], v[2:5]
	v_mfma_f32_16x16x32_bf16 v[34:37], v[204:207], v[174:177], v[34:37]
	v_mfma_f32_16x16x32_bf16 v[26:29], v[212:215], v[174:177], v[26:29]
	v_mfma_f32_16x16x32_bf16 v[22:25], v[204:207], v[166:169], v[22:25]
	v_mfma_f32_16x16x32_bf16 v[18:21], v[212:215], v[166:169], v[18:21]
	v_mfma_f32_16x16x32_bf16 v[14:17], v[204:207], v[158:161], v[14:17]
	v_mfma_f32_16x16x32_bf16 v[10:13], v[212:215], v[158:161], v[10:13]
	v_mfma_f32_16x16x32_bf16 v[6:9], v[204:207], v[150:153], v[6:9]
	v_mfma_f32_16x16x32_bf16 v[2:5], v[212:215], v[150:153], v[2:5]
	s_setprio 0
	s_barrier
	v_or_b32_e32 v196, s8, v192
	v_cmp_eq_u32_e64 s[38:39], 0, v196
	s_and_saveexec_b64 s[74:75], s[38:39]
	s_cbranch_execz .LBB0_81
	v_cmp_lt_i32_e32 vcc, s91, v193
	v_add_u32_e32 v203, s23, v193
	v_mov_b32_e32 v204, v203
	s_and_saveexec_b64 s[36:37], vcc
	s_cbranch_execz .LBB0_80
	v_mov_b64_e32 v[196:197], s[44:45]
	s_waitcnt vmcnt(0)
	flat_atomic_add v196, v[196:197], v224 sc0
	s_waitcnt vmcnt(0) lgkmcnt(0)
	v_cmp_lt_i32_e64 s[38:39], s91, v196
	v_add_u32_e32 v204, s2, v196
	s_and_saveexec_b64 s[0:1], s[38:39]
	s_cbranch_execz .LBB0_79
	v_mov_b64_e32 v[196:197], s[58:59]
	flat_atomic_add v196, v[196:197], v224 sc0
	s_waitcnt vmcnt(0) lgkmcnt(0)
	v_cmp_lt_i32_e64 s[38:39], s91, v196
	v_add_u32_e32 v204, s66, v196
	s_and_saveexec_b64 s[80:81], s[38:39]
	s_cbranch_execz .LBB0_78
	v_mov_b64_e32 v[196:197], s[60:61]
	flat_atomic_add v196, v[196:197], v224 sc0
	s_movk_i32 s9, 0x60
	s_waitcnt vmcnt(0) lgkmcnt(0)
	v_cmp_lt_i32_e64 s[38:39], s91, v196
	v_add_u32_e32 v204, s67, v196
	s_and_saveexec_b64 s[82:83], s[38:39]
	s_cbranch_execz .LBB0_77
	v_mov_b64_e32 v[196:197], s[62:63]
	flat_atomic_add v196, v[196:197], v224 sc0
	s_waitcnt vmcnt(0) lgkmcnt(0)
	v_cmp_lt_i32_e64 s[38:39], s91, v196
	v_add_u32_e32 v204, s22, v196
	s_and_saveexec_b64 s[84:85], s[38:39]
	s_cbranch_execz .LBB0_76
	v_mov_b64_e32 v[196:197], s[92:93]
	flat_atomic_add v196, v[196:197], v224 sc0
	v_readlane_b32 s10, v255, 2
	s_waitcnt vmcnt(0) lgkmcnt(0)
	v_cmp_lt_i32_e64 s[38:39], s91, v196
	v_add_u32_e32 v204, s10, v196
	s_and_saveexec_b64 s[86:87], s[38:39]
	s_cbranch_execz .LBB0_75
	v_readlane_b32 s38, v255, 4
	v_readlane_b32 s39, v255, 5
	v_readlane_b32 s10, v255, 6
	s_nop 0
	v_mov_b64_e32 v[196:197], s[38:39]
	flat_atomic_add v196, v[196:197], v224 sc0
	s_waitcnt vmcnt(0) lgkmcnt(0)
	v_cmp_lt_i32_e64 s[38:39], s91, v196
	v_add_u32_e32 v204, s10, v196
	s_and_saveexec_b64 s[88:89], s[38:39]
	s_cbranch_execz .LBB0_74
	v_readlane_b32 s38, v255, 8
	v_readlane_b32 s39, v255, 9
	v_readlane_b32 s10, v255, 10
	s_nop 0
	v_mov_b64_e32 v[196:197], s[38:39]
	flat_atomic_add v196, v[196:197], v224 sc0
	s_waitcnt vmcnt(0) lgkmcnt(0)
	v_add_u32_e32 v197, s10, v196
	v_cmp_gt_i32_e64 s[38:39], s9, v196
	s_nop 1
	v_cndmask_b32_e64 v204, -1, v197, s[38:39]
	s_branch .LBB0_74
; __device__ __forceinline__ u32x4 pack8(f32x4 v0, f32x4 v1) { u32x4 w; w.x = cvt_pk_bf16(v0[0], v0[1]); w.y = cvt_pk_bf16(v0[2], v0[3]); w.z = cvt_pk_bf16(v1[0], v1[1]); w.w = cvt_pk_bf16(v1[2], v1[3]); return w; }
; template <class Epi, bool DYN = false>
; __device__ __forceinline__ void gemm_phase(LAS unsigned char* lds, const Gemm g, const Epi& E, int wave, unsigned* ctr = nullptr) {
;     ...
;         if (!has_next) break;
; #pragma unroll
;         for (int a = 0; a < 2; ++a)
; #pragma unroll
;             for (int b = 0; b < 2; ++b)
; #pragma unroll
;                 for (int m = 0; m < 4; ++m)
; #pragma unroll
;                     for (int n = 0; n < 2; ++n) acc[a][b][m][n] = (f32x4){0.f, 0.f, 0.f, 0.f};
;         cur = nxt; cA = nA; cB = nB; ++ui;
;         if (DYN) issue();
;     __device__ __forceinline__ void operator()(AccRef acc, const Unit& u, int wr, int wc, int fr, int fq, const float (&pre)[8]) const {
;         const int row0 = u.pm * BM + wr * 64 + fr, col0 = u.pn * BM + wc * 32 + 8 * fq;
; #pragma unroll
;         for (int ai = 0; ai < 2; ++ai)
; #pragma unroll
;             for (int m = 0; m < 4; ++m)
; #pragma unroll
;                 for (int bj = 0; bj < 2; ++bj)
;                     gst16(O + (size_t)(row0 + ai * HALF + m * 16) * ldc + col0 + bj * HALF, pack8(acc[ai][bj][m][0], acc[ai][bj][m][1]));
;     }
.LBB0_95:
	v_lshl_add_u32 v136, s42, 8, v194
	v_lshl_or_b32 v130, s40, 8, v201
	v_ashrrev_i32_e32 v137, 31, v136
	v_readlane_b32 s0, v254, 39
	v_ashrrev_i32_e32 v131, 31, v130
	v_lshlrev_b64 v[132:133], 12, v[136:137]
	v_readlane_b32 s1, v254, 40
	v_lshlrev_b64 v[138:139], 1, v[130:131]
	v_cvt_pk_bf16_f32 v134, v122, v123
	v_cvt_pk_bf16_f32 v135, v124, v125
	s_nop 0
	v_lshl_add_u64 v[132:133], s[0:1], 0, v[132:133]
	v_lshl_add_u64 v[130:131], v[132:133], 0, v[138:139]
	v_cvt_pk_bf16_f32 v132, v126, v127
	v_cvt_pk_bf16_f32 v133, v128, v129
	global_store_dwordx4 v[130:131], v[132:135], off
	s_nop 1
	v_cvt_pk_bf16_f32 v132, v86, v87
	v_cvt_pk_bf16_f32 v133, v88, v89
	v_cvt_pk_bf16_f32 v134, v78, v79
	v_cvt_pk_bf16_f32 v135, v80, v81
	global_store_dwordx4 v[130:131], v[132:135], off offset:256
	s_nop 1
	v_or_b32_e32 v132, 16, v136
	v_ashrrev_i32_e32 v133, 31, v132
	v_lshlrev_b64 v[132:133], 12, v[132:133]
	v_lshl_add_u64 v[132:133], s[0:1], 0, v[132:133]
	v_lshl_add_u64 v[140:141], v[132:133], 0, v[138:139]
	v_cvt_pk_bf16_f32 v132, v118, v119
	v_cvt_pk_bf16_f32 v133, v120, v121
	v_cvt_pk_bf16_f32 v134, v114, v115
	v_cvt_pk_bf16_f32 v135, v116, v117
	global_store_dwordx4 v[140:141], v[132:135], off
	s_nop 1
	v_cvt_pk_bf16_f32 v132, v70, v71
	v_cvt_pk_bf16_f32 v133, v72, v73
	v_cvt_pk_bf16_f32 v134, v62, v63
	v_cvt_pk_bf16_f32 v135, v64, v65
	global_store_dwordx4 v[140:141], v[132:135], off offset:256
	s_nop 1
	v_or_b32_e32 v132, 32, v136
	v_ashrrev_i32_e32 v133, 31, v132
	v_lshlrev_b64 v[132:133], 12, v[132:133]
	v_lshl_add_u64 v[132:133], s[0:1], 0, v[132:133]
	v_lshl_add_u64 v[140:141], v[132:133], 0, v[138:139]
	v_cvt_pk_bf16_f32 v132, v110, v111
	v_cvt_pk_bf16_f32 v133, v112, v113
	v_cvt_pk_bf16_f32 v134, v106, v107
	v_cvt_pk_bf16_f32 v135, v108, v109
	global_store_dwordx4 v[140:141], v[132:135], off
	s_nop 1
	v_cvt_pk_bf16_f32 v132, v54, v55
	v_cvt_pk_bf16_f32 v133, v56, v57
	v_cvt_pk_bf16_f32 v134, v46, v47
	v_cvt_pk_bf16_f32 v135, v48, v49
	global_store_dwordx4 v[140:141], v[132:135], off offset:256
	s_nop 1
	v_or_b32_e32 v132, 48, v136
	v_ashrrev_i32_e32 v133, 31, v132
	v_lshlrev_b64 v[132:133], 12, v[132:133]
	v_lshl_add_u64 v[132:133], s[0:1], 0, v[132:133]
	v_lshl_add_u64 v[136:137], v[132:133], 0, v[138:139]
	v_cvt_pk_bf16_f32 v132, v102, v103
	v_cvt_pk_bf16_f32 v133, v104, v105
	v_cvt_pk_bf16_f32 v134, v94, v95
	v_cvt_pk_bf16_f32 v135, v96, v97
	s_mov_b64 s[0:1], 0x80000
	global_store_dwordx4 v[136:137], v[132:135], off
	s_nop 1
	v_cvt_pk_bf16_f32 v132, v42, v43
	v_cvt_pk_bf16_f32 v133, v44, v45
	v_cvt_pk_bf16_f32 v134, v38, v39
	v_cvt_pk_bf16_f32 v135, v40, v41
	global_store_dwordx4 v[136:137], v[132:135], off offset:256
	v_lshl_add_u64 v[136:137], v[130:131], 0, s[0:1]
	s_mov_b32 s0, 0x80000
	v_add_co_u32_e32 v138, vcc, s0, v130
	v_cvt_pk_bf16_f32 v132, v34, v35
	v_cvt_pk_bf16_f32 v133, v36, v37
	v_cvt_pk_bf16_f32 v134, v26, v27
	v_cvt_pk_bf16_f32 v135, v28, v29
	s_nop 1
	v_addc_co_u32_e32 v139, vcc, 0, v131, vcc
	s_mov_b64 s[0:1], 0x90000
	global_store_dwordx4 v[138:139], v[132:135], off
	s_nop 1
	v_cvt_pk_bf16_f32 v132, v98, v99
	v_cvt_pk_bf16_f32 v133, v100, v101
	v_cvt_pk_bf16_f32 v134, v90, v91
	v_cvt_pk_bf16_f32 v135, v92, v93
	global_store_dwordx4 v[136:137], v[132:135], off offset:256
	v_lshl_add_u64 v[136:137], v[130:131], 0, s[0:1]
	s_mov_b32 s0, 0x90000
	v_add_co_u32_e32 v138, vcc, s0, v130
	v_cvt_pk_bf16_f32 v132, v22, v23
	v_cvt_pk_bf16_f32 v133, v24, v25
	v_cvt_pk_bf16_f32 v134, v18, v19
	v_cvt_pk_bf16_f32 v135, v20, v21
	s_nop 1
	v_addc_co_u32_e32 v139, vcc, 0, v131, vcc
	s_mov_b64 s[0:1], 0xa0000
	global_store_dwordx4 v[138:139], v[132:135], off
	s_nop 1
	v_cvt_pk_bf16_f32 v132, v82, v83
	v_cvt_pk_bf16_f32 v133, v84, v85
	v_cvt_pk_bf16_f32 v134, v74, v75
	v_cvt_pk_bf16_f32 v135, v76, v77
	global_store_dwordx4 v[136:137], v[132:135], off offset:256
	v_lshl_add_u64 v[136:137], v[130:131], 0, s[0:1]
	s_mov_b32 s0, 0xa0000
	v_add_co_u32_e32 v138, vcc, s0, v130
	v_cvt_pk_bf16_f32 v132, v14, v15
	v_cvt_pk_bf16_f32 v133, v16, v17
	v_cvt_pk_bf16_f32 v134, v10, v11
	v_cvt_pk_bf16_f32 v135, v12, v13
	s_nop 1
	v_addc_co_u32_e32 v139, vcc, 0, v131, vcc
	s_mov_b64 s[0:1], 0xb0000
	global_store_dwordx4 v[138:139], v[132:135], off
	s_nop 1
	v_cvt_pk_bf16_f32 v132, v66, v67
	v_cvt_pk_bf16_f32 v133, v68, v69
	v_cvt_pk_bf16_f32 v134, v58, v59
	v_cvt_pk_bf16_f32 v135, v60, v61
	global_store_dwordx4 v[136:137], v[132:135], off offset:256
	v_lshl_add_u64 v[136:137], v[130:131], 0, s[0:1]
	s_mov_b32 s0, 0xb0000
	v_add_co_u32_e32 v130, vcc, s0, v130
	v_cvt_pk_bf16_f32 v132, v6, v7
	v_cvt_pk_bf16_f32 v133, v8, v9
	v_cvt_pk_bf16_f32 v134, v2, v3
	v_cvt_pk_bf16_f32 v135, v4, v5
	s_nop 1
	v_addc_co_u32_e32 v131, vcc, 0, v131, vcc
	s_andn2_b64 vcc, exec, s[54:55]
	global_store_dwordx4 v[130:131], v[132:135], off
	v_cvt_pk_bf16_f32 v130, v50, v51
	v_cvt_pk_bf16_f32 v131, v52, v53
	s_nop 1
	v_cvt_pk_bf16_f32 v132, v30, v31
	v_cvt_pk_bf16_f32 v133, v32, v33
	global_store_dwordx4 v[136:137], v[130:133], off offset:256
	s_cbranch_vccnz .LBB0_72
	s_mov_b64 s[0:1], exec
	v_readlane_b32 s6, v255, 0
	v_readlane_b32 s7, v255, 1
	s_and_b64 s[6:7], s[0:1], s[6:7]
	s_mov_b64 exec, s[6:7]
	s_cbranch_execz .LBB0_71
	v_readlane_b32 s6, v255, 12
	v_readlane_b32 s7, v255, 13
	s_nop 1
	v_mov_b64_e32 v[2:3], s[6:7]
	global_atomic_add v193, v[2:3], v224, off sc0
	s_branch .LBB0_71

; __device__ __forceinline__ unsigned hw_xcc_id() { return (unsigned)__builtin_amdgcn_s_getreg((3 << 11) | 20) & 0xFu; }
; template <class Epi, bool DYN = false>
; __device__ __forceinline__ void gemm_phase(LAS unsigned char* lds, const Gemm g, const Epi& E, int wave, unsigned* ctr = nullptr) {
;     ...
;     const int xcd = (int)(hw_xcc_id() & 7u); int ticket = 0;
;     auto rng_cnt = [&](int x) { const int q = S.nwg / NXCD, r = S.nwg % NXCD; return q + (x < r ? 1 : 0); };
;     auto rng_start = [&](int x) { const int q = S.nwg / NXCD, r = S.nwg % NXCD; return x < r ? x * (q + 1) : r * (q + 1) + (x - r) * q; };
;     auto decode = [&](int wgid, Unit& u) { const int nig = WGM * S.nN, gid = wgid / nig, fm = gid * WGM, gsz = (S.nM - fm) < WGM ? (S.nM - fm) : WGM; u.pm = fm + ((wgid % nig) % gsz); u.pn = (wgid % nig) / gsz; u.b = 0; };
;     auto issue = [&]() { if (tid == 0) ticket = (int)__hip_atomic_fetch_add(ctr + xcd * 16, 1u, __ATOMIC_RELAXED, __HIP_MEMORY_SCOPE_AGENT); };
;     auto publish = [&](int si) { if (tid == 0) { int wg = -1;
;             if (ticket < rng_cnt(xcd)) wg = rng_start(xcd) + ticket;
;             else { for (int k = 1; k < 8; ++k) { const int x2 = (xcd + k) & 7; const int t2 = (int)__hip_atomic_fetch_add(ctr + x2 * 16, 1u, __ATOMIC_RELAXED, __HIP_MEMORY_SCOPE_AGENT); if (t2 < rng_cnt(x2)) { wg = rng_start(x2) + t2; break; } } }
;             slot[si] = wg; } };
;     if (DYN) { issue(); publish(0); __syncthreads(); const int w0 = __builtin_amdgcn_readfirstlane(slot[0]); if (w0 < 0) return; decode(w0, cur); issue(); }
.LBB0_455:
	v_readlane_b32 s0, v254, 51
	s_cmp_gt_i32 s0, 3
	s_mov_b64 s[0:1], -1
	s_cbranch_scc0 .LBB0_770
	v_readlane_b32 s0, v254, 43
	v_mbcnt_hi_u32_b32 v0, -1, v222
	s_mulk_i32 s0, 0x300
	v_or_b32_e32 v185, s92, v0
	s_add_i32 s40, s0, 0x100
	s_mov_b32 s0, s80
	v_mov_b32_e32 v187, v185
	s_getreg_b32 s3, hwreg(HW_REG_XCC_ID, 0, 4)
	v_readlane_b32 s1, v254, 44
	s_ashr_i32 s41, s40, 31
	v_mov_b32_e32 v189, 0
	v_readfirstlane_b32 s28, v187
	s_and_b32 s2, s3, 7
	v_cmp_eq_u32_e64 s[4:5], 0, v187
	s_mov_b64 s[0:1], exec
	s_nop 0
	v_writelane_b32 v254, s4, 37
	s_nop 1
	v_writelane_b32 v254, s5, 38
	s_and_b64 s[4:5], s[0:1], s[4:5]
	s_mov_b64 exec, s[4:5]
	s_cbranch_execz .LBB0_458
	s_lshl_b32 s4, s2, 6
	v_readlane_b32 s5, v254, 47
	s_add_u32 s6, s5, s4
	v_readlane_b32 s4, v254, 48
	s_addc_u32 s7, s4, 0
	s_lshl_b64 s[4:5], s[40:41], 2
	s_add_u32 s4, s6, s4
	s_addc_u32 s5, s7, s5
	s_waitcnt lgkmcnt(0)
	v_mov_b64_e32 v[2:3], s[4:5]
	s_waitcnt vmcnt(0)
	global_atomic_add v189, v[2:3], v224, off sc0

; template <class Epi, bool DYN = false>
; __device__ __forceinline__ void gemm_phase(LAS unsigned char* lds, const Gemm g, const Epi& E, int wave, unsigned* ctr = nullptr) {
;     ...
;     auto issue = [&]() { if (tid == 0) ticket = (int)__hip_atomic_fetch_add(ctr + xcd * 16, 1u, __ATOMIC_RELAXED, __HIP_MEMORY_SCOPE_AGENT); };
;     auto publish = [&](int si) { if (tid == 0) { int wg = -1;
;             if (ticket < rng_cnt(xcd)) wg = rng_start(xcd) + ticket;
;             else { for (int k = 1; k < 8; ++k) { const int x2 = (xcd + k) & 7; const int t2 = (int)__hip_atomic_fetch_add(ctr + x2 * 16, 1u, __ATOMIC_RELAXED, __HIP_MEMORY_SCOPE_AGENT); if (t2 < rng_cnt(x2)) { wg = rng_start(x2) + t2; break; } } }
;             slot[si] = wg; } };
;     if (DYN) { issue(); publish(0); __syncthreads(); const int w0 = __builtin_amdgcn_readfirstlane(slot[0]); if (w0 < 0) return; decode(w0, cur); issue(); }
.LBB0_490:
	s_or_b64 exec, exec, s[36:37]
	v_readlane_b32 s0, v254, 3
	s_waitcnt vmcnt(0) lgkmcnt(0)
	s_barrier
	v_mov_b32_e32 v0, s0
	ds_read_b32 v0, v0
	s_waitcnt lgkmcnt(0)
	v_readfirstlane_b32 s4, v0
	s_cmp_lt_i32 s4, 0
	s_cbranch_scc1 .LBB0_747
	s_mov_b64 s[0:1], exec
	v_readlane_b32 s6, v254, 37
	v_readlane_b32 s7, v254, 38
	s_and_b64 s[6:7], s[0:1], s[6:7]
	s_mov_b64 exec, s[6:7]
	s_cbranch_execz .LBB0_493
	s_lshl_b32 s5, s2, 6
	v_readlane_b32 s6, v254, 47
	s_add_u32 s5, s6, s5
	v_readlane_b32 s6, v254, 48
	s_addc_u32 s8, s6, 0
	s_lshl_b64 s[6:7], s[40:41], 2
	s_add_u32 s6, s5, s6
	s_addc_u32 s7, s8, s7
	v_mov_b64_e32 v[2:3], s[6:7]
	global_atomic_add v189, v[2:3], v224, off sc0

; template <class Epi, bool DYN = false>
; __device__ __forceinline__ void gemm_phase(LAS unsigned char* lds, const Gemm g, const Epi& E, int wave, unsigned* ctr = nullptr) {
;     ...
;     for (;;) {
;         bool has_next = DYN ? false : S.next(ui + 1, nxt);
;         const char* nA = has_next ? (const char*)(g.A + (size_t)nxt.b * g.sA) + (size_t)nxt.pm * tstepA : cA; const char* nB = has_next ? (const char*)(g.Bt + (size_t)nxt.b * g.sB) + (size_t)nxt.pn * tstepB : cB;
;         for (int t = 0; t < nt; t += 2) {
;             const bool last = (t == nt - 2);
;             if (DYN && last) { const int nw = __builtin_amdgcn_readfirstlane(slot[(ui + 1) & 1]); has_next = nw >= 0;
;                 if (has_next) { decode(nw, nxt); nA = (const char*)g.A + (size_t)nxt.pm * tstepA; nB = (const char*)g.Bt + (size_t)nxt.pn * tstepB; } }
;             const char* a1 = cA + (size_t)(t + 1) * kstepA;
;             const char* a2 = last ? nA : cA + (size_t)(t + 2) * kstepA; const char* b2 = last ? nB : cB + (size_t)(t + 2) * kstepB;
;             const char* a3 = a2 + kstepA; const char* b3 = b2 + kstepB;
.LBB0_497:
	s_add_u32 s19, s66, 0x10000
	s_addc_u32 s15, s67, 0
	s_andn2_b32 s0, 1, s18
	s_lshl_b32 s0, s0, 2
	s_add_i32 s2, s0, 0
	s_movk_i32 s0, 0x287
	s_add_i32 s2, s2, 0x20040
	s_waitcnt lgkmcnt(0)
	s_mov_b64 s[78:79], 0
	s_mov_b32 s3, -2
	s_add_u32 s0, s74, 0xc000
	s_addc_u32 s1, s75, 0
	v_lshl_add_u64 v[208:209], s[0:1], 0, v[204:205]
	v_lshl_add_u64 v[210:211], s[0:1], 0, v[206:207]
	s_mov_b64 s[40:41], 0
	s_branch .LBB0_506

; #define PG8_STAGE(bufoff, gbase, voff) do { _Pragma("unroll") for (int _i = 0; _i < 2; ++_i) \
;         __builtin_amdgcn_global_load_lds((const unsigned*)((const char*)(gbase) + (voff)[_i]), (LAS unsigned*)(lds + (bufoff) + ldsw + _i * 8192), 16, 0, 0); } while (0)
; #define PG8_LDA(dst, b, h) do { _Pragma("unroll") for (int m = 0; m < 4; ++m) _Pragma("unroll") for (int k = 0; k < 2; ++k) dst[m][k] = *(const LAS bf16x8*)(lds + PG8_SA(b, h) + aoff + m * 2048 + k * 1024); } while (0)
; #define PG8_LDB(dst, b, h) do { _Pragma("unroll") for (int n = 0; n < 2; ++n) _Pragma("unroll") for (int k = 0; k < 2; ++k) dst[n][k] = *(const LAS bf16x8*)(lds + PG8_SB(b, h) + boff + n * 2048 + k * 1024); } while (0)
; #define PG8_MMA(ai, bj, At, Bt) do { __builtin_amdgcn_s_setprio(1); _Pragma("unroll") for (int m = 0; m < 4; ++m) _Pragma("unroll") for (int n = 0; n < 2; ++n) _Pragma("unroll") for (int k = 0; k < 2; ++k) \
;         acc[ai][bj][m][n] = __builtin_amdgcn_mfma_f32_16x16x32_bf16(Bt[n][k], At[m][k], acc[ai][bj][m][n], 0, 0, 0); __builtin_amdgcn_s_setprio(0); } while (0)
; #define PG8_WAIT_L(n) asm volatile("s_waitcnt lgkmcnt(" #n ")" ::: "memory")
; #define PG8_BAR __builtin_amdgcn_s_barrier()
; #define PG8_SCHED __builtin_amdgcn_sched_barrier(0)
; template <class Epi, bool DYN = false>
; __device__ __forceinline__ void gemm_phase(LAS unsigned char* lds, const Gemm g, const Epi& E, int wave, unsigned* ctr = nullptr) {
;     ...
;             const char* a1 = cA + (size_t)(t + 1) * kstepA;
;             const char* a2 = last ? nA : cA + (size_t)(t + 2) * kstepA; const char* b2 = last ? nB : cB + (size_t)(t + 2) * kstepB;
;             const char* a3 = a2 + kstepA; const char* b3 = b2 + kstepB;
;             PG8_LDB(B0, 0, 0); PG8_SCHED; PG8_LDA(At, 0, 0); PG8_STAGE(PG8_SA(1, 1), a1 + hstepA, voffA);
;             PG8_WAIT_L(8); PG8_BAR; PG8_WAIT_L(0); PG8_MMA(0, 0, At, B0); PG8_BAR; PG8_SCHED;
;             PG8_LDB(B1, 0, 1); PG8_STAGE(PG8_SB(0, 0), b2, voffB);
;             PG8_BAR; PG8_WAIT_L(0); PG8_MMA(0, 1, At, B1); PG8_BAR;
;             PG8_LDA(At, 0, 1); PG8_STAGE(PG8_SA(0, 0), a2, voffA);
;             PG8_BAR; PG8_WAIT_L(0); PG8_MMA(1, 0, At, B0); PG8_BAR; PG8_SCHED;
.LBB0_510:
	s_add_i32 s3, s3, 2
	s_add_u32 s0, s74, s40
	s_addc_u32 s1, s75, s41
	s_add_u32 s4, s0, 0x10000
	s_addc_u32 s5, s1, 0
	s_and_b64 s[0:1], s[36:37], exec
	s_cselect_b32 s43, s77, s5
	s_cselect_b32 s42, s76, s4
	s_add_u32 s4, s19, s40
	s_addc_u32 s5, s15, s41
	s_add_u32 s38, s42, 0x8000
	s_addc_u32 s39, s43, 0
	s_add_i32 s6, 0, 0x10000
	v_add_u32_e32 v142, s6, v201
	ds_read_b128 v[130:133], v142
	ds_read_b128 v[134:137], v142 offset:1024
	ds_read_b128 v[138:141], v142 offset:2048
	ds_read_b128 v[142:145], v142 offset:3072
	s_and_b64 s[0:1], s[36:37], exec
	s_cselect_b32 s37, s67, s5
	s_cselect_b32 s36, s66, s4
	v_lshl_add_u64 v[196:197], v[210:211], 0, s[40:41]
	s_add_i32 m0, s45, 0xc000
	ds_read_b128 v[146:149], v212
	ds_read_b128 v[150:153], v212 offset:1024
	ds_read_b128 v[154:157], v212 offset:2048
	ds_read_b128 v[158:161], v212 offset:3072
	ds_read_b128 v[162:165], v212 offset:4096
	ds_read_b128 v[166:169], v212 offset:5120
	ds_read_b128 v[170:173], v212 offset:6144
	ds_read_b128 v[174:177], v212 offset:7168
	global_load_lds_dwordx4 v[196:197], off
	v_lshl_add_u64 v[196:197], v[208:209], 0, s[40:41]
	s_add_i32 m0, s45, 0xe000
	s_nop 0
	global_load_lds_dwordx4 v[196:197], off
	s_waitcnt lgkmcnt(8)
	s_barrier
	s_waitcnt lgkmcnt(0)
	s_setprio 1
	s_waitcnt lgkmcnt(0)
	v_mfma_f32_16x16x32_bf16 v[2:5], v[130:133], v[146:149], v[2:5]
	v_mfma_f32_16x16x32_bf16 v[30:33], v[138:141], v[146:149], v[30:33]
	v_mfma_f32_16x16x32_bf16 v[26:29], v[130:133], v[154:157], v[26:29]
	v_mfma_f32_16x16x32_bf16 v[22:25], v[138:141], v[154:157], v[22:25]
	v_mfma_f32_16x16x32_bf16 v[18:21], v[130:133], v[162:165], v[18:21]
	v_mfma_f32_16x16x32_bf16 v[14:17], v[138:141], v[162:165], v[14:17]
	v_mfma_f32_16x16x32_bf16 v[10:13], v[130:133], v[170:173], v[10:13]
	v_mfma_f32_16x16x32_bf16 v[6:9], v[138:141], v[170:173], v[6:9]
	v_mfma_f32_16x16x32_bf16 v[2:5], v[134:137], v[150:153], v[2:5]
	v_mfma_f32_16x16x32_bf16 v[30:33], v[142:145], v[150:153], v[30:33]
	v_mfma_f32_16x16x32_bf16 v[26:29], v[134:137], v[158:161], v[26:29]
	v_mfma_f32_16x16x32_bf16 v[22:25], v[142:145], v[158:161], v[22:25]
	v_mfma_f32_16x16x32_bf16 v[18:21], v[134:137], v[166:169], v[18:21]
	v_mfma_f32_16x16x32_bf16 v[14:17], v[142:145], v[166:169], v[14:17]
	v_mfma_f32_16x16x32_bf16 v[10:13], v[134:137], v[174:177], v[10:13]
	v_mfma_f32_16x16x32_bf16 v[6:9], v[142:145], v[174:177], v[6:9]
	s_setprio 0
	s_barrier
	s_add_i32 s4, 0, 0x14000
	s_add_i32 s0, s6, s81
	v_add_u32_e32 v232, s4, v201
	v_lshl_add_u64 v[244:245], s[36:37], 0, v[0:1]
	s_mov_b32 m0, s0
	ds_read_b128 v[196:199], v232
	ds_read_b128 v[214:217], v232 offset:1024
	ds_read_b128 v[218:221], v232 offset:2048
	ds_read_b128 v[232:235], v232 offset:3072
	global_load_lds_dwordx4 v[244:245], off
	v_lshl_add_u64 v[244:245], s[36:37], 0, v[182:183]
	s_add_i32 m0, s0, 0x2000
	s_nop 0
	global_load_lds_dwordx4 v[244:245], off
	s_barrier
	s_waitcnt lgkmcnt(0)
	s_setprio 1
	s_waitcnt lgkmcnt(0)
	v_mfma_f32_16x16x32_bf16 v[94:97], v[196:199], v[146:149], v[94:97]
	v_mfma_f32_16x16x32_bf16 v[90:93], v[218:221], v[146:149], v[90:93]
	v_mfma_f32_16x16x32_bf16 v[86:89], v[196:199], v[154:157], v[86:89]
	v_mfma_f32_16x16x32_bf16 v[82:85], v[218:221], v[154:157], v[82:85]
	v_mfma_f32_16x16x32_bf16 v[78:81], v[196:199], v[162:165], v[78:81]
	v_mfma_f32_16x16x32_bf16 v[74:77], v[218:221], v[162:165], v[74:77]
	v_mfma_f32_16x16x32_bf16 v[70:73], v[196:199], v[170:173], v[70:73]
	v_mfma_f32_16x16x32_bf16 v[66:69], v[218:221], v[170:173], v[66:69]
	v_mfma_f32_16x16x32_bf16 v[94:97], v[214:217], v[150:153], v[94:97]
	v_mfma_f32_16x16x32_bf16 v[90:93], v[232:235], v[150:153], v[90:93]
	v_mfma_f32_16x16x32_bf16 v[86:89], v[214:217], v[158:161], v[86:89]
	v_mfma_f32_16x16x32_bf16 v[82:85], v[232:235], v[158:161], v[82:85]
	v_mfma_f32_16x16x32_bf16 v[78:81], v[214:217], v[166:169], v[78:81]
	v_mfma_f32_16x16x32_bf16 v[74:77], v[232:235], v[166:169], v[74:77]
	v_mfma_f32_16x16x32_bf16 v[70:73], v[214:217], v[174:177], v[70:73]
	v_mfma_f32_16x16x32_bf16 v[66:69], v[232:235], v[174:177], v[66:69]
	s_setprio 0
	s_mov_b32 m0, s45
	v_lshl_add_u64 v[244:245], s[42:43], 0, v[178:179]
	s_barrier
	ds_read_b128 v[146:149], v212 offset:16384
	ds_read_b128 v[150:153], v212 offset:17408
	ds_read_b128 v[154:157], v212 offset:18432
	ds_read_b128 v[158:161], v212 offset:19456
	ds_read_b128 v[162:165], v212 offset:20480
	ds_read_b128 v[166:169], v212 offset:21504
	ds_read_b128 v[170:173], v212 offset:22528
	ds_read_b128 v[174:177], v212 offset:23552
	global_load_lds_dwordx4 v[244:245], off
	v_lshl_add_u64 v[244:245], s[42:43], 0, v[180:181]
	s_mov_b32 m0, s83
	s_nop 0
	global_load_lds_dwordx4 v[244:245], off
	s_barrier
	s_waitcnt lgkmcnt(0)
	s_setprio 1
	s_waitcnt lgkmcnt(0)
	v_mfma_f32_16x16x32_bf16 v[62:65], v[130:133], v[146:149], v[62:65]
	v_mfma_f32_16x16x32_bf16 v[58:61], v[138:141], v[146:149], v[58:61]
	v_mfma_f32_16x16x32_bf16 v[54:57], v[130:133], v[154:157], v[54:57]
	v_mfma_f32_16x16x32_bf16 v[50:53], v[138:141], v[154:157], v[50:53]
	v_mfma_f32_16x16x32_bf16 v[46:49], v[130:133], v[162:165], v[46:49]
	v_mfma_f32_16x16x32_bf16 v[42:45], v[138:141], v[162:165], v[42:45]
	v_mfma_f32_16x16x32_bf16 v[38:41], v[130:133], v[170:173], v[38:41]
	v_mfma_f32_16x16x32_bf16 v[34:37], v[138:141], v[170:173], v[34:37]
	v_mfma_f32_16x16x32_bf16 v[62:65], v[134:137], v[150:153], v[62:65]
	v_mfma_f32_16x16x32_bf16 v[58:61], v[142:145], v[150:153], v[58:61]
	v_mfma_f32_16x16x32_bf16 v[54:57], v[134:137], v[158:161], v[54:57]
	v_mfma_f32_16x16x32_bf16 v[50:53], v[142:145], v[158:161], v[50:53]
	v_mfma_f32_16x16x32_bf16 v[46:49], v[134:137], v[166:169], v[46:49]
	v_mfma_f32_16x16x32_bf16 v[42:45], v[142:145], v[166:169], v[42:45]
	v_mfma_f32_16x16x32_bf16 v[38:41], v[134:137], v[174:177], v[38:41]
	v_mfma_f32_16x16x32_bf16 v[34:37], v[142:145], v[174:177], v[34:37]
	s_setprio 0
	s_barrier
; #define PG8_STAGE(bufoff, gbase, voff) do { _Pragma("unroll") for (int _i = 0; _i < 2; ++_i) \
;         __builtin_amdgcn_global_load_lds((const unsigned*)((const char*)(gbase) + (voff)[_i]), (LAS unsigned*)(lds + (bufoff) + ldsw + _i * 8192), 16, 0, 0); } while (0)
; #define PG8_LDA(dst, b, h) do { _Pragma("unroll") for (int m = 0; m < 4; ++m) _Pragma("unroll") for (int k = 0; k < 2; ++k) dst[m][k] = *(const LAS bf16x8*)(lds + PG8_SA(b, h) + aoff + m * 2048 + k * 1024); } while (0)
; #define PG8_LDB(dst, b, h) do { _Pragma("unroll") for (int n = 0; n < 2; ++n) _Pragma("unroll") for (int k = 0; k < 2; ++k) dst[n][k] = *(const LAS bf16x8*)(lds + PG8_SB(b, h) + boff + n * 2048 + k * 1024); } while (0)
; #define PG8_MMA(ai, bj, At, Bt) do { __builtin_amdgcn_s_setprio(1); _Pragma("unroll") for (int m = 0; m < 4; ++m) _Pragma("unroll") for (int n = 0; n < 2; ++n) _Pragma("unroll") for (int k = 0; k < 2; ++k) \
;         acc[ai][bj][m][n] = __builtin_amdgcn_mfma_f32_16x16x32_bf16(Bt[n][k], At[m][k], acc[ai][bj][m][n], 0, 0, 0); __builtin_amdgcn_s_setprio(0); } while (0)
; #define PG8_WAIT_V(n) asm volatile("s_waitcnt vmcnt(" #n ")" ::: "memory")
; #define PG8_WAIT_L(n) asm volatile("s_waitcnt lgkmcnt(" #n ")" ::: "memory")
; #define PG8_BAR __builtin_amdgcn_s_barrier()
; #define PG8_SCHED __builtin_amdgcn_sched_barrier(0)
; template <class Epi, bool DYN = false>
; __device__ __forceinline__ void gemm_phase(LAS unsigned char* lds, const Gemm g, const Epi& E, int wave, unsigned* ctr = nullptr) {
;     ...
;             PG8_STAGE(PG8_SB(0, 1), b2 + hstepB, voffB);
;             PG8_WAIT_V(6); PG8_BAR; PG8_MMA(1, 1, At, B1); PG8_BAR;
;             PG8_LDB(B0, 1, 0); PG8_SCHED; PG8_LDA(At, 1, 0); PG8_STAGE(PG8_SA(0, 1), a2 + hstepA, voffA);
;             PG8_WAIT_L(8); PG8_BAR; PG8_WAIT_L(0); PG8_MMA(0, 0, At, B0); PG8_BAR; PG8_SCHED;
;             PG8_LDB(B1, 1, 1); PG8_STAGE(PG8_SB(1, 0), b3, voffB);
;             PG8_BAR; PG8_WAIT_L(0); PG8_MMA(0, 1, At, B1); PG8_BAR;
	s_add_u32 s0, s36, 0x4000
	s_addc_u32 s1, s37, 0
	s_add_i32 s4, s4, s81
	v_lshl_add_u64 v[130:131], s[0:1], 0, v[0:1]
	s_mov_b32 m0, s4
	s_nop 0
	global_load_lds_dwordx4 v[130:131], off
	v_lshl_add_u64 v[130:131], s[0:1], 0, v[182:183]
	s_add_i32 m0, s4, 0x2000
	s_nop 0
	global_load_lds_dwordx4 v[130:131], off
	s_waitcnt vmcnt(6)
	s_barrier
	s_setprio 1
	v_mfma_f32_16x16x32_bf16 v[126:129], v[196:199], v[146:149], v[126:129]
	v_mfma_f32_16x16x32_bf16 v[122:125], v[218:221], v[146:149], v[122:125]
	v_mfma_f32_16x16x32_bf16 v[118:121], v[196:199], v[154:157], v[118:121]
	v_mfma_f32_16x16x32_bf16 v[114:117], v[218:221], v[154:157], v[114:117]
	v_mfma_f32_16x16x32_bf16 v[110:113], v[196:199], v[162:165], v[110:113]
	v_mfma_f32_16x16x32_bf16 v[106:109], v[218:221], v[162:165], v[106:109]
	v_mfma_f32_16x16x32_bf16 v[102:105], v[196:199], v[170:173], v[102:105]
	v_mfma_f32_16x16x32_bf16 v[98:101], v[218:221], v[170:173], v[98:101]
	v_mfma_f32_16x16x32_bf16 v[126:129], v[214:217], v[150:153], v[126:129]
	v_mfma_f32_16x16x32_bf16 v[122:125], v[232:235], v[150:153], v[122:125]
	v_mfma_f32_16x16x32_bf16 v[118:121], v[214:217], v[158:161], v[118:121]
	v_mfma_f32_16x16x32_bf16 v[114:117], v[232:235], v[158:161], v[114:117]
	v_mfma_f32_16x16x32_bf16 v[110:113], v[214:217], v[166:169], v[110:113]
	v_mfma_f32_16x16x32_bf16 v[106:109], v[232:235], v[166:169], v[106:109]
	v_mfma_f32_16x16x32_bf16 v[102:105], v[214:217], v[174:177], v[102:105]
	v_mfma_f32_16x16x32_bf16 v[98:101], v[232:235], v[174:177], v[98:101]
	s_setprio 0
	s_add_i32 s4, 0, 0x18000
	v_add_u32_e32 v130, s4, v201
	s_barrier
	ds_read_b128 v[196:199], v130
	ds_read_b128 v[214:217], v130 offset:1024
	ds_read_b128 v[218:221], v130 offset:2048
	ds_read_b128 v[232:235], v130 offset:3072
	s_add_u32 s0, s42, 0x4000
	s_addc_u32 s1, s43, 0
	s_mov_b32 m0, s84
	v_lshl_add_u64 v[130:131], s[0:1], 0, v[178:179]
	ds_read_b128 v[146:149], v212 offset:32768
	ds_read_b128 v[150:153], v212 offset:33792
	ds_read_b128 v[154:157], v212 offset:34816
	ds_read_b128 v[158:161], v212 offset:35840
	ds_read_b128 v[162:165], v212 offset:36864
	ds_read_b128 v[166:169], v212 offset:37888
	ds_read_b128 v[170:173], v212 offset:38912
	ds_read_b128 v[174:177], v212 offset:39936
	global_load_lds_dwordx4 v[130:131], off
	v_lshl_add_u64 v[130:131], s[0:1], 0, v[180:181]
	s_mov_b32 m0, s85
	s_nop 0
	global_load_lds_dwordx4 v[130:131], off
	s_waitcnt lgkmcnt(8)
	s_barrier
	s_waitcnt lgkmcnt(0)
	s_setprio 1
	s_waitcnt lgkmcnt(0)
	v_mfma_f32_16x16x32_bf16 v[2:5], v[196:199], v[146:149], v[2:5]
	v_mfma_f32_16x16x32_bf16 v[30:33], v[218:221], v[146:149], v[30:33]
	v_mfma_f32_16x16x32_bf16 v[26:29], v[196:199], v[154:157], v[26:29]
	v_mfma_f32_16x16x32_bf16 v[22:25], v[218:221], v[154:157], v[22:25]
	v_mfma_f32_16x16x32_bf16 v[18:21], v[196:199], v[162:165], v[18:21]
	v_mfma_f32_16x16x32_bf16 v[14:17], v[218:221], v[162:165], v[14:17]
	v_mfma_f32_16x16x32_bf16 v[10:13], v[196:199], v[170:173], v[10:13]
	v_mfma_f32_16x16x32_bf16 v[6:9], v[218:221], v[170:173], v[6:9]
	v_mfma_f32_16x16x32_bf16 v[2:5], v[214:217], v[150:153], v[2:5]
	v_mfma_f32_16x16x32_bf16 v[30:33], v[232:235], v[150:153], v[30:33]
	v_mfma_f32_16x16x32_bf16 v[26:29], v[214:217], v[158:161], v[26:29]
	v_mfma_f32_16x16x32_bf16 v[22:25], v[232:235], v[158:161], v[22:25]
	v_mfma_f32_16x16x32_bf16 v[18:21], v[214:217], v[166:169], v[18:21]
	v_mfma_f32_16x16x32_bf16 v[14:17], v[232:235], v[166:169], v[14:17]
	v_mfma_f32_16x16x32_bf16 v[10:13], v[214:217], v[174:177], v[10:13]
	v_mfma_f32_16x16x32_bf16 v[6:9], v[232:235], v[174:177], v[6:9]
	s_setprio 0
	s_barrier
	s_add_u32 s0, s36, 0x8000
	v_add_u32_e32 v130, 0, v201
	s_addc_u32 s1, s37, 0
	s_add_i32 s4, s4, s81
	v_add_u32_e32 v142, 0x1c000, v130
	v_lshl_add_u64 v[244:245], s[0:1], 0, v[0:1]
	s_mov_b32 m0, s4
	ds_read_b128 v[130:133], v142
	ds_read_b128 v[134:137], v142 offset:1024
	ds_read_b128 v[138:141], v142 offset:2048
	ds_read_b128 v[142:145], v142 offset:3072
	global_load_lds_dwordx4 v[244:245], off
	v_lshl_add_u64 v[244:245], s[0:1], 0, v[182:183]
	s_add_i32 m0, s4, 0x2000
	s_nop 0
	global_load_lds_dwordx4 v[244:245], off
	s_barrier
	s_waitcnt lgkmcnt(0)
	s_setprio 1
	s_waitcnt lgkmcnt(0)
	v_mfma_f32_16x16x32_bf16 v[94:97], v[130:133], v[146:149], v[94:97]
	v_mfma_f32_16x16x32_bf16 v[90:93], v[138:141], v[146:149], v[90:93]
	v_mfma_f32_16x16x32_bf16 v[86:89], v[130:133], v[154:157], v[86:89]
	v_mfma_f32_16x16x32_bf16 v[82:85], v[138:141], v[154:157], v[82:85]
	v_mfma_f32_16x16x32_bf16 v[78:81], v[130:133], v[162:165], v[78:81]
	v_mfma_f32_16x16x32_bf16 v[74:77], v[138:141], v[162:165], v[74:77]
	v_mfma_f32_16x16x32_bf16 v[70:73], v[130:133], v[170:173], v[70:73]
	v_mfma_f32_16x16x32_bf16 v[66:69], v[138:141], v[170:173], v[66:69]
	v_mfma_f32_16x16x32_bf16 v[94:97], v[134:137], v[150:153], v[94:97]
	v_mfma_f32_16x16x32_bf16 v[90:93], v[142:145], v[150:153], v[90:93]
	v_mfma_f32_16x16x32_bf16 v[86:89], v[134:137], v[158:161], v[86:89]
	v_mfma_f32_16x16x32_bf16 v[82:85], v[142:145], v[158:161], v[82:85]
	v_mfma_f32_16x16x32_bf16 v[78:81], v[134:137], v[166:169], v[78:81]
	v_mfma_f32_16x16x32_bf16 v[74:77], v[142:145], v[166:169], v[74:77]
	v_mfma_f32_16x16x32_bf16 v[70:73], v[134:137], v[174:177], v[70:73]
	v_mfma_f32_16x16x32_bf16 v[66:69], v[142:145], v[174:177], v[66:69]
	s_setprio 0
	s_mov_b32 m0, s86
	v_lshl_add_u64 v[244:245], s[38:39], 0, v[178:179]
	s_barrier
; #define PG8_STAGE(bufoff, gbase, voff) do { _Pragma("unroll") for (int _i = 0; _i < 2; ++_i) \
;         __builtin_amdgcn_global_load_lds((const unsigned*)((const char*)(gbase) + (voff)[_i]), (LAS unsigned*)(lds + (bufoff) + ldsw + _i * 8192), 16, 0, 0); } while (0)
; #define PG8_LDA(dst, b, h) do { _Pragma("unroll") for (int m = 0; m < 4; ++m) _Pragma("unroll") for (int k = 0; k < 2; ++k) dst[m][k] = *(const LAS bf16x8*)(lds + PG8_SA(b, h) + aoff + m * 2048 + k * 1024); } while (0)
; #define PG8_MMA(ai, bj, At, Bt) do { __builtin_amdgcn_s_setprio(1); _Pragma("unroll") for (int m = 0; m < 4; ++m) _Pragma("unroll") for (int n = 0; n < 2; ++n) _Pragma("unroll") for (int k = 0; k < 2; ++k) \
;         acc[ai][bj][m][n] = __builtin_amdgcn_mfma_f32_16x16x32_bf16(Bt[n][k], At[m][k], acc[ai][bj][m][n], 0, 0, 0); __builtin_amdgcn_s_setprio(0); } while (0)
; #define PG8_WAIT_L(n) asm volatile("s_waitcnt lgkmcnt(" #n ")" ::: "memory")
; #define PG8_BAR __builtin_amdgcn_s_barrier()
; #define PG8_SCHED __builtin_amdgcn_sched_barrier(0)
; template <class Epi, bool DYN = false>
; __device__ __forceinline__ void gemm_phase(LAS unsigned char* lds, const Gemm g, const Epi& E, int wave, unsigned* ctr = nullptr) {
;     ...
;     auto publish = [&](int si) { if (tid == 0) { int wg = -1;
;             if (ticket < rng_cnt(xcd)) wg = rng_start(xcd) + ticket;
;             else { for (int k = 1; k < 8; ++k) { const int x2 = (xcd + k) & 7; const int t2 = (int)__hip_atomic_fetch_add(ctr + x2 * 16, 1u, __ATOMIC_RELAXED, __HIP_MEMORY_SCOPE_AGENT); if (t2 < rng_cnt(x2)) { wg = rng_start(x2) + t2; break; } } }
;     ...
;             PG8_LDA(At, 1, 1); PG8_STAGE(PG8_SA(1, 0), a3, voffA);
;             PG8_BAR; PG8_WAIT_L(0); PG8_MMA(1, 0, At, B0); PG8_BAR; PG8_SCHED;
;             if (DYN && t == 0) publish((ui + 1) & 1);
	ds_read_b128 v[170:173], v212 offset:49152
	ds_read_b128 v[174:177], v212 offset:50176
	ds_read_b128 v[162:165], v212 offset:51200
	ds_read_b128 v[166:169], v212 offset:52224
	ds_read_b128 v[154:157], v212 offset:53248
	ds_read_b128 v[158:161], v212 offset:54272
	ds_read_b128 v[146:149], v212 offset:55296
	ds_read_b128 v[150:153], v212 offset:56320
	global_load_lds_dwordx4 v[244:245], off
	v_lshl_add_u64 v[244:245], s[38:39], 0, v[180:181]
	s_mov_b32 m0, s87
	s_nop 0
	global_load_lds_dwordx4 v[244:245], off
	s_barrier
	s_waitcnt lgkmcnt(0)
	s_setprio 1
	s_waitcnt lgkmcnt(0)
	v_mfma_f32_16x16x32_bf16 v[62:65], v[196:199], v[170:173], v[62:65]
	v_mfma_f32_16x16x32_bf16 v[58:61], v[218:221], v[170:173], v[58:61]
	v_mfma_f32_16x16x32_bf16 v[54:57], v[196:199], v[162:165], v[54:57]
	v_mfma_f32_16x16x32_bf16 v[50:53], v[218:221], v[162:165], v[50:53]
	v_mfma_f32_16x16x32_bf16 v[46:49], v[196:199], v[154:157], v[46:49]
	v_mfma_f32_16x16x32_bf16 v[42:45], v[218:221], v[154:157], v[42:45]
	v_mfma_f32_16x16x32_bf16 v[38:41], v[196:199], v[146:149], v[38:41]
	v_mfma_f32_16x16x32_bf16 v[34:37], v[218:221], v[146:149], v[34:37]
	v_mfma_f32_16x16x32_bf16 v[62:65], v[214:217], v[174:177], v[62:65]
	v_mfma_f32_16x16x32_bf16 v[58:61], v[232:235], v[174:177], v[58:61]
	v_mfma_f32_16x16x32_bf16 v[54:57], v[214:217], v[166:169], v[54:57]
	v_mfma_f32_16x16x32_bf16 v[50:53], v[232:235], v[166:169], v[50:53]
	v_mfma_f32_16x16x32_bf16 v[46:49], v[214:217], v[158:161], v[46:49]
	v_mfma_f32_16x16x32_bf16 v[42:45], v[232:235], v[158:161], v[42:45]
	v_mfma_f32_16x16x32_bf16 v[38:41], v[214:217], v[150:153], v[38:41]
	v_mfma_f32_16x16x32_bf16 v[34:37], v[232:235], v[150:153], v[34:37]
	s_setprio 0
	s_barrier
	v_or_b32_e32 v196, s3, v187
	v_cmp_eq_u32_e64 s[38:39], 0, v196
	s_and_saveexec_b64 s[42:43], s[38:39]
	s_cbranch_execz .LBB0_505
	v_readlane_b32 s0, v254, 49
	v_cmp_lt_i32_e32 vcc, 0x287, v189
	s_nop 1
	v_add_u32_e32 v213, s0, v189
	v_mov_b32_e32 v214, v213
	s_and_saveexec_b64 s[46:47], vcc
	s_cbranch_execz .LBB0_504
	v_mov_b64_e32 v[196:197], s[50:51]
	s_waitcnt vmcnt(0)
	flat_atomic_add v196, v[196:197], v224 sc0
	s_movk_i32 s0, 0x287
	s_waitcnt vmcnt(0) lgkmcnt(0)
	v_cmp_lt_i32_e64 s[38:39], s0, v196
	v_add_u32_e32 v214, s80, v196
	s_and_saveexec_b64 s[0:1], s[38:39]
	s_cbranch_execz .LBB0_503
	v_mov_b64_e32 v[196:197], s[54:55]
	flat_atomic_add v196, v[196:197], v224 sc0
	s_movk_i32 s4, 0x287
	s_waitcnt vmcnt(0) lgkmcnt(0)
	v_cmp_lt_i32_e64 s[38:39], s4, v196
	v_add_u32_e32 v214, s82, v196
	s_and_saveexec_b64 s[60:61], s[38:39]
	s_cbranch_execz .LBB0_502
	v_mov_b64_e32 v[196:197], s[58:59]
	flat_atomic_add v196, v[196:197], v224 sc0
	s_waitcnt vmcnt(0) lgkmcnt(0)
	v_cmp_lt_i32_e64 s[38:39], s4, v196
	v_add_u32_e32 v214, s17, v196
	s_and_saveexec_b64 s[62:63], s[38:39]
	s_cbranch_execz .LBB0_501
	v_mov_b64_e32 v[196:197], s[90:91]
	flat_atomic_add v196, v[196:197], v224 sc0
	s_waitcnt vmcnt(0) lgkmcnt(0)
	v_cmp_lt_i32_e64 s[38:39], s4, v196
	v_add_u32_e32 v214, s23, v196
	s_and_saveexec_b64 s[64:65], s[38:39]
	s_cbranch_execz .LBB0_500
	v_readlane_b32 s4, v255, 0
	v_readlane_b32 s5, v255, 1
	s_nop 1
	v_mov_b64_e32 v[196:197], s[4:5]
	flat_atomic_add v196, v[196:197], v224 sc0
	s_movk_i32 s4, 0x287
	s_waitcnt vmcnt(0) lgkmcnt(0)
	v_cmp_lt_i32_e64 s[38:39], s4, v196
	v_readlane_b32 s4, v255, 2
	s_nop 1
	v_add_u32_e32 v214, s4, v196
	s_and_saveexec_b64 s[68:69], s[38:39]
	s_cbranch_execz .LBB0_499
	v_readlane_b32 s4, v255, 4
	v_readlane_b32 s5, v255, 5
	s_nop 1
	v_mov_b64_e32 v[196:197], s[4:5]
	flat_atomic_add v196, v[196:197], v224 sc0
	s_movk_i32 s4, 0x287
	s_waitcnt vmcnt(0) lgkmcnt(0)
	v_cmp_lt_i32_e64 s[38:39], s4, v196
	v_readlane_b32 s4, v255, 6
	s_nop 1
	v_add_u32_e32 v214, s4, v196
	s_and_saveexec_b64 s[70:71], s[38:39]
	s_cbranch_execz .LBB0_498
	v_readlane_b32 s4, v255, 8
	v_readlane_b32 s5, v255, 9
	s_nop 1
	v_mov_b64_e32 v[196:197], s[4:5]
	flat_atomic_add v196, v[196:197], v224 sc0
	v_readlane_b32 s4, v255, 10
	s_waitcnt vmcnt(0) lgkmcnt(0)
	s_nop 0
	v_add_u32_e32 v197, s4, v196
	s_movk_i32 s4, 0x288
	v_cmp_gt_i32_e64 s[38:39], s4, v196
	s_nop 1
	v_cndmask_b32_e64 v214, -1, v197, s[38:39]
	s_branch .LBB0_498

; template <class Epi, bool DYN = false>
; __device__ __forceinline__ void gemm_phase(LAS unsigned char* lds, const Gemm g, const Epi& E, int wave, unsigned* ctr = nullptr) {
;     ...
;         if (!has_next) break;
; #pragma unroll
;         for (int a = 0; a < 2; ++a)
; #pragma unroll
;             for (int b = 0; b < 2; ++b)
; #pragma unroll
;                 for (int m = 0; m < 4; ++m)
; #pragma unroll
;                     for (int n = 0; n < 2; ++n) acc[a][b][m][n] = (f32x4){0.f, 0.f, 0.f, 0.f};
;         cur = nxt; cA = nA; cB = nB; ++ui;
;         if (DYN) issue();
.LBB0_691:
	s_add_u32 s36, s19, 0xffff0000
	s_addc_u32 s37, s15, -1
	v_lshl_add_u64 v[134:135], v[144:145], 1, s[62:63]
	s_andn2_b64 vcc, exec, s[78:79]
	v_cvt_pk_bf16_f32 v130, v138, v139
	v_cvt_pk_bf16_f32 v131, v136, v137
	v_cvt_pk_bf16_f32 v132, v142, v143
	v_cvt_pk_bf16_f32 v133, v140, v141
	global_store_dwordx4 v[134:135], v[130:133], off nt
	s_cbranch_vccnz .LBB0_743
	s_mov_b64 s[0:1], exec
	v_readlane_b32 s2, v254, 37
	v_readlane_b32 s3, v254, 38
	s_and_b64 s[2:3], s[0:1], s[2:3]
	s_mov_b64 exec, s[2:3]
	s_cbranch_execz .LBB0_496
	v_readlane_b32 s2, v255, 12
	v_readlane_b32 s3, v255, 13
	s_nop 1
	v_mov_b64_e32 v[2:3], s[2:3]
	global_atomic_add v189, v[2:3], v224, off sc0
	s_branch .LBB0_496

; __device__ __forceinline__ bf16_t f2bf(float f) { return (bf16_t)(cvt_pk_bf16(f, 0.f) & 0xffffu); }
; __device__ __forceinline__ int ltid(int wave) { int t = (wave << 6) | (int)__builtin_amdgcn_mbcnt_hi(~0u, __builtin_amdgcn_mbcnt_lo(~0u, 0u)); asm volatile("" : "+v"(t)); return t; }
; __device__ __forceinline__ int lbid() { int b = blockIdx.x; asm volatile("" : "+s"(b)); return b; }
; __device__ __forceinline__ void cvt_tile(unsigned char* shm, int tid, const float* src, bf16_t* dst, int K, int N, int mode, const float* kscale, int ldd, int t) {
;     bf16_t* T = (bf16_t*)shm;
;     const int nnt = N / 256, nti = t % nnt, kt = t / nnt;
;     { const int k = tid >> 3, n8 = (tid & 7) * 8;
;       const float* s = src + (size_t)(kt * 64 + k) * N + nti * 256 + n8; const float ks = kscale ? kscale[kt * 64 + k] : 1.0f;
;       f32x4 v[8];
; #pragma unroll
;       for (int q = 0; q < 4; ++q) { v[2 * q] = *(const f32x4*)(s + q * 64); v[2 * q + 1] = *(const f32x4*)(s + q * 64 + 4); }
;       asm volatile("" ::: "memory");
; #pragma unroll
;       for (int q = 0; q < 4; ++q)
; #pragma unroll
;           for (int j = 0; j < 4; ++j) { T[(q * 64 + n8 + j) * 72 + k] = f2bf(v[2 * q][j] * ks); T[(q * 64 + n8 + 4 + j) * 72 + k] = f2bf(v[2 * q + 1][j] * ks); } }
;     __syncthreads();
; #pragma unroll
;     for (int q = 0; q < 4; ++q) { const int n = q * 64 + (tid >> 3), k8 = (tid & 7) * 8; const int nn = nti * 256 + n;
;       const int drow = mode == 0 ? nn : ((nn >> 7) * 256 + (nn & 127) + (mode == 2 ? 128 : 0));
;       *(u32x4*)(dst + ((size_t)((drow >> 8) * (K / 64) + kt) * 256 + (drow & 255)) * 64 + k8) = *(const u32x4*)(T + n * 72 + k8); }
; __device__ void cvt_set(const Params& p, unsigned char* shm, bf16_t* W, int l, int sub  , unsigned* ctr) {
;     const int tid = ltid(p.wave), total = sub == 1 ? CVT_MIXER_TILES : CVT_FFN_TILES;
;     volatile int* tk = (volatile int*)(shm + 131072 + 128);
;     if (ctr == nullptr) {
;         for (int t = lbid(); t < total; t += gridDim.x) { if (sub == 1) cvt_mixer_tile(p, shm, tid, W, l, t); else cvt_ffn_tile(p, shm, tid, W, l, sub == 2 ? 1 : 0, t); }
;         return;
;     }
;     for (;;) {
;         if (tid == 0) *tk = (int)__hip_atomic_fetch_add(ctr, 1u, __ATOMIC_RELAXED, __HIP_MEMORY_SCOPE_AGENT);
;         __syncthreads();
;         const int t = __builtin_amdgcn_readfirstlane(*tk);
.LBB0_747:
	v_readlane_b32 s40, v251, 12
	v_readlane_b32 s46, v251, 18
	s_cmp_gt_i32 s46, 14
	s_mov_b32 s0, 0x8400000
	s_cselect_b32 s2, 3, 0
	s_cselect_b32 s4, s0, 0x2c00000
	s_mov_b32 s0, 0x8000
	s_cselect_b32 s5, 0x14000, s0
	s_bitcmp1_b32 s2, 0
	s_cselect_b32 s0, 0x5000000, 0
	v_readlane_b32 s1, v252, 27
	s_add_u32 s0, s1, s0
	v_readlane_b32 s1, v252, 28
	v_readlane_b32 s44, v251, 16
	s_addc_u32 s1, s1, 0
	s_lshl_b32 s2, s2, 6
	v_readlane_b32 s45, v251, 17
	s_add_u32 s2, s44, s2
	s_addc_u32 s3, s45, 0
	s_add_u32 s26, s2, 0x29c4e40
	s_addc_u32 s27, s3, 0
	s_add_u32 s2, s0, 0x2d60000
	v_readlane_b32 s60, v251, 20
	s_addc_u32 s3, s1, 0
	v_readlane_b32 s64, v251, 24
	s_waitcnt vmcnt(0) lgkmcnt(0)
	s_barrier
	v_readlane_b32 s65, v251, 25
	v_lshlrev_b32_e32 v0, 3, v185
	s_add_u32 s38, s64, s5
	v_and_b32_e32 v2, 56, v0
	v_readlane_b32 s61, v251, 21
	v_readlane_b32 s62, v251, 22
	v_readlane_b32 s63, v251, 23
	v_readlane_b32 s66, v251, 26
	v_readlane_b32 s67, v251, 27
	s_addc_u32 s39, s65, 0
	v_readlane_b32 s41, v251, 13
	v_ashrrev_i32_e32 v3, 3, v185
	v_mul_u32_u24_e32 v4, 0x48, v2
	s_add_u32 s40, s40, s4
	v_readlane_b32 s60, v251, 0
	v_readlane_b32 s42, v251, 14
	v_lshlrev_b32_e32 v0, 1, v3
	v_lshlrev_b32_e32 v26, 1, v2
	v_xor_b32_e32 v0, v0, v26
	v_lshlrev_b32_e32 v4, 1, v4
	v_add_u32_e32 v30, 64, v3
	v_add_u32_e32 v31, 0x80, v3
	v_add_u32_e32 v32, 0xc0, v3
	s_addc_u32 s41, s41, 0
	v_readlane_b32 s66, v251, 6
	v_readlane_b32 s43, v251, 15
	v_add3_u32 v26, 0, v0, v4
	v_add_u32_e32 v4, 0, v4
	v_lshlrev_b32_e32 v12, 7, v3
	v_lshlrev_b32_e32 v14, 7, v30
	v_lshlrev_b32_e32 v8, 7, v31
	v_lshlrev_b32_e32 v16, 7, v32
	v_readlane_b32 s67, v251, 7
	s_add_u32 s42, s66, s4
	v_add_u32_e32 v27, v4, v0
	s_movk_i32 s6, 0xff72
	v_and_b32_e32 v0, 0x7f80, v12
	v_and_b32_e32 v6, 0x7f80, v14
	v_mov_b32_e32 v7, v1
	v_and_b32_e32 v8, 0x7f80, v8
	v_mov_b32_e32 v9, v1
	v_and_b32_e32 v10, 0x7f80, v16
	v_mov_b32_e32 v11, v1
	v_and_b32_e32 v12, 0x3f80, v12
	v_mov_b32_e32 v13, v1
	v_and_b32_e32 v14, 0x3f80, v14
	v_mov_b32_e32 v15, v1
	v_and_b32_e32 v16, 0x3f80, v16
	v_mov_b32_e32 v17, v1
	v_readlane_b32 s64, v251, 4
	s_addc_u32 s43, s67, 0
	v_mad_i32_i24 v28, v2, s6, v4
	v_lshlrev_b32_e32 v33, 1, v3
	v_and_b32_e32 v33, 0x70, v33
	v_xor_b32_e32 v28, v28, v33
	s_movk_i32 s6, 0x90
	v_lshl_add_u64 v[4:5], s[2:3], 0, v[0:1]
	v_lshlrev_b32_e32 v0, 1, v2
	v_lshl_add_u64 v[6:7], s[2:3], 0, v[6:7]
	v_lshl_add_u64 v[8:9], s[2:3], 0, v[8:9]
	v_lshl_add_u64 v[10:11], s[2:3], 0, v[10:11]
	v_lshl_add_u64 v[12:13], s[0:1], 0, v[12:13]
	v_lshl_add_u64 v[14:15], s[0:1], 0, v[14:15]
	v_lshl_add_u64 v[16:17], s[0:1], 0, v[16:17]
	v_readlane_b32 s65, v251, 5
	s_add_u32 s44, s64, s4
	v_cmp_eq_u32_e64 s[36:37], 0, v185
	v_mul_lo_u32 v29, v3, s6
	v_lshl_add_u64 v[4:5], v[4:5], 0, v[0:1]
	v_lshl_add_u64 v[6:7], v[6:7], 0, v[0:1]
	v_lshl_add_u64 v[8:9], v[8:9], 0, v[0:1]
	v_lshl_add_u64 v[10:11], v[10:11], 0, v[0:1]
	v_lshl_add_u64 v[18:19], v[12:13], 0, v[0:1]
	v_lshl_add_u64 v[20:21], v[14:15], 0, v[0:1]
	v_lshl_add_u64 v[22:23], v[16:17], 0, v[0:1]
	s_addc_u32 s45, s65, 0
	v_readlane_b32 s47, v251, 19
	v_readlane_b32 s68, v251, 28
	v_readlane_b32 s69, v251, 29
	v_readlane_b32 s70, v251, 30
	v_readlane_b32 s71, v251, 31
	v_readlane_b32 s72, v251, 32
	v_readlane_b32 s73, v251, 33
	v_readlane_b32 s74, v251, 34
	v_readlane_b32 s75, v251, 35
	v_readlane_b32 s61, v251, 1
	v_readlane_b32 s62, v251, 2
	v_readlane_b32 s63, v251, 3
	s_and_saveexec_b64 s[0:1], s[36:37]
	global_atomic_add v100, v1, v224, s[26:27] sc0
	s_or_b64 exec, exec, s[0:1]
	s_waitcnt vmcnt(0)
	s_branch .LBB0_752

; __device__ __forceinline__ bf16_t f2bf(float f) { return (bf16_t)(cvt_pk_bf16(f, 0.f) & 0xffffu); }
; __device__ __forceinline__ void cvt_tile(unsigned char* shm, int tid, const float* src, bf16_t* dst, int K, int N, int mode, const float* kscale, int ldd, int t) {
;     bf16_t* T = (bf16_t*)shm;
;     const int nnt = N / 256, nti = t % nnt, kt = t / nnt;
;     { const int k = tid >> 3, n8 = (tid & 7) * 8;
;       const float* s = src + (size_t)(kt * 64 + k) * N + nti * 256 + n8; const float ks = kscale ? kscale[kt * 64 + k] : 1.0f;
;       f32x4 v[8];
; #pragma unroll
;       for (int q = 0; q < 4; ++q) { v[2 * q] = *(const f32x4*)(s + q * 64); v[2 * q + 1] = *(const f32x4*)(s + q * 64 + 4); }
;       asm volatile("" ::: "memory");
; #pragma unroll
;       for (int q = 0; q < 4; ++q)
; #pragma unroll
;           for (int j = 0; j < 4; ++j) { T[(q * 64 + n8 + j) * 72 + k] = f2bf(v[2 * q][j] * ks); T[(q * 64 + n8 + 4 + j) * 72 + k] = f2bf(v[2 * q + 1][j] * ks); } }
;     __syncthreads();
; #pragma unroll
;     for (int q = 0; q < 4; ++q) { const int n = q * 64 + (tid >> 3), k8 = (tid & 7) * 8; const int nn = nti * 256 + n;
;       const int drow = mode == 0 ? nn : ((nn >> 7) * 256 + (nn & 127) + (mode == 2 ? 128 : 0));
;       *(u32x4*)(dst + ((size_t)((drow >> 8) * (K / 64) + kt) * 256 + (drow & 255)) * 64 + k8) = *(const u32x4*)(T + n * 72 + k8); }
;     __syncthreads();
; __device__ void cvt_set(const Params& p, unsigned char* shm, bf16_t* W, int l, int sub  , unsigned* ctr) {
;     ...
;     for (;;) {
;         if (tid == 0) *tk = (int)__hip_atomic_fetch_add(ctr, 1u, __ATOMIC_RELAXED, __HIP_MEMORY_SCOPE_AGENT);
;         __syncthreads();
;         const int t = __builtin_amdgcn_readfirstlane(*tk);
;         __syncthreads();
;         if (t >= total) break;
;         if (sub == 1) cvt_mixer_tile(p, shm, tid, W, l, t); else cvt_ffn_tile(p, shm, tid, W, l, sub == 2 ? 1 : 0, t);
.LBB0_755:
	s_or_b64 exec, exec, s[46:47]
	s_mov_b64 s[2:3], src_shared_base
	s_waitcnt vmcnt(4)
	v_readfirstlane_b32 s2, v100
	s_nop 1
	v_add_u32_e32 v0, s2, v0
	s_add_i32 s2, 0, 0x20080
	s_cmp_lg_u32 s2, -1
	s_cselect_b32 s2, s2, 0
	s_cselect_b32 s3, s3, 0
	v_mov_b32_e32 v24, s2
	v_mov_b32_e32 v25, s3
	ds_write_b32 v24, v0
	global_atomic_add v100, v1, v224, s[26:27] sc0
.LBB0_756:
	s_or_b64 exec, exec, s[0:1]
	s_mov_b64 s[0:1], src_shared_base
	s_add_i32 s0, 0, 0x20080
	s_cmp_lg_u32 s0, -1
	s_cselect_b32 s0, s0, 0
	s_cselect_b32 s1, s1, 0
	v_mov_b32_e32 v24, s0
	v_mov_b32_e32 v25, s1
	s_waitcnt lgkmcnt(0)
	s_barrier
	ds_read_b32 v0, v24
	s_mov_b64 s[0:1], -1
	s_waitcnt lgkmcnt(0)
	s_barrier
	v_readfirstlane_b32 s2, v0
	s_cmpk_gt_i32 s2, 0x83f
	s_cbranch_scc1 .LBB0_751
	s_cmpk_gt_i32 s2, 0x2bf
	s_cbranch_scc0 .LBB0_766
	s_cmpk_gt_u32 s2, 0x57f
	s_cbranch_scc0 .LBB0_760
	s_add_i32 s0, s2, 0xfa80
	s_bfe_u32 s1, s0, 0xd0003
	v_lshl_add_u32 v24, s1, 6, v3
	v_ashrrev_i32_e32 v25, 31, v24
	s_lshl_b32 s0, s2, 8
	v_lshlrev_b64 v[24:25], 13, v[24:25]
	s_and_b32 s0, s0, 0x700
	v_lshl_add_u64 v[24:25], s[40:41], 0, v[24:25]
	s_lshl_b32 s48, s0, 2
	v_lshl_add_u64 v[24:25], v[24:25], 0, s[48:49]
	v_lshlrev_b32_e32 v0, 2, v2
	v_lshl_add_u64 v[24:25], v[24:25], 0, v[0:1]
	global_load_dwordx4 v[34:37], v[24:25], off offset:16
	global_load_dwordx4 v[38:41], v[24:25], off
	global_load_dwordx4 v[42:45], v[24:25], off offset:272
	global_load_dwordx4 v[46:49], v[24:25], off offset:256
	global_load_dwordx4 v[50:53], v[24:25], off offset:528
	global_load_dwordx4 v[54:57], v[24:25], off offset:512
	global_load_dwordx4 v[58:61], v[24:25], off offset:784
	global_load_dwordx4 v[62:65], v[24:25], off offset:768
	v_add_u32_e32 v33, v28, v29
	s_waitcnt vmcnt(6)
	v_cvt_pk_bf16_f32 v0, v38, v1
	ds_write_b16 v26, v0
	v_cvt_pk_bf16_f32 v0, v34, v1
	ds_write_b16 v27, v0 offset:576
	v_cvt_pk_bf16_f32 v0, v39, v1
	ds_write_b16 v26, v0 offset:144
	v_cvt_pk_bf16_f32 v0, v35, v1
	ds_write_b16 v27, v0 offset:720
	v_cvt_pk_bf16_f32 v0, v40, v1
	ds_write_b16 v26, v0 offset:288
	v_cvt_pk_bf16_f32 v0, v36, v1
	ds_write_b16 v27, v0 offset:864
	v_cvt_pk_bf16_f32 v0, v41, v1
	ds_write_b16 v26, v0 offset:432
	v_cvt_pk_bf16_f32 v0, v37, v1
	ds_write_b16 v27, v0 offset:1008
	s_waitcnt vmcnt(4)
	v_cvt_pk_bf16_f32 v0, v46, v1
	ds_write_b16 v26, v0 offset:9216
	v_cvt_pk_bf16_f32 v0, v42, v1
	ds_write_b16 v27, v0 offset:9792
	v_cvt_pk_bf16_f32 v0, v47, v1
	ds_write_b16 v26, v0 offset:9360
	v_cvt_pk_bf16_f32 v0, v43, v1
	ds_write_b16 v27, v0 offset:9936
	v_cvt_pk_bf16_f32 v0, v48, v1
	ds_write_b16 v26, v0 offset:9504
	v_cvt_pk_bf16_f32 v0, v44, v1
	ds_write_b16 v27, v0 offset:10080
	v_cvt_pk_bf16_f32 v0, v49, v1
	ds_write_b16 v26, v0 offset:9648
	v_cvt_pk_bf16_f32 v0, v45, v1
	ds_write_b16 v27, v0 offset:10224
	s_waitcnt vmcnt(2)
	v_cvt_pk_bf16_f32 v0, v54, v1
	ds_write_b16 v26, v0 offset:18432
	v_cvt_pk_bf16_f32 v0, v50, v1
	ds_write_b16 v27, v0 offset:19008
	v_cvt_pk_bf16_f32 v0, v55, v1
	ds_write_b16 v26, v0 offset:18576
	v_cvt_pk_bf16_f32 v0, v51, v1
	ds_write_b16 v27, v0 offset:19152
	v_cvt_pk_bf16_f32 v0, v56, v1
	ds_write_b16 v26, v0 offset:18720
	v_cvt_pk_bf16_f32 v0, v52, v1
	ds_write_b16 v27, v0 offset:19296
	v_cvt_pk_bf16_f32 v0, v57, v1
	ds_write_b16 v26, v0 offset:18864
	v_cvt_pk_bf16_f32 v0, v53, v1
	ds_write_b16 v27, v0 offset:19440
	s_waitcnt vmcnt(0)
	v_cvt_pk_bf16_f32 v0, v62, v1
	ds_write_b16 v26, v0 offset:27648
	v_cvt_pk_bf16_f32 v0, v58, v1
	ds_write_b16 v27, v0 offset:28224
	v_cvt_pk_bf16_f32 v0, v63, v1
	ds_write_b16 v26, v0 offset:27792
	v_cvt_pk_bf16_f32 v0, v59, v1
	ds_write_b16 v27, v0 offset:28368
	v_cvt_pk_bf16_f32 v0, v64, v1
	ds_write_b16 v26, v0 offset:27936
	v_cvt_pk_bf16_f32 v0, v60, v1
	ds_write_b16 v27, v0 offset:28512
	v_cvt_pk_bf16_f32 v0, v65, v1
	ds_write_b16 v26, v0 offset:28080
	v_cvt_pk_bf16_f32 v0, v61, v1
	ds_write_b16 v27, v0 offset:28656
	v_add_u32_e32 v0, s0, v3
	s_waitcnt lgkmcnt(0)
	s_barrier
	ds_read_b128 v[34:37], v33
	v_lshrrev_b32_e32 v0, 8, v0
	v_mov_b32_e32 v38, s1
	s_movk_i32 s1, 0x58
	v_mad_i32_i24 v24, v0, s1, v38
	v_ashrrev_i32_e32 v25, 31, v24
	v_lshlrev_b64 v[24:25], 15, v[24:25]
	v_lshl_add_u64 v[24:25], v[4:5], 0, v[24:25]
	v_add_u32_e32 v0, s0, v30
	s_waitcnt lgkmcnt(0)
	global_store_dwordx4 v[24:25], v[34:37], off
	ds_read_b128 v[34:37], v33 offset:9216
	v_lshrrev_b32_e32 v0, 8, v0
	v_mad_i32_i24 v24, v0, s1, v38
	v_ashrrev_i32_e32 v25, 31, v24
	v_lshlrev_b64 v[24:25], 15, v[24:25]
	v_lshl_add_u64 v[24:25], v[6:7], 0, v[24:25]
	v_add_u32_e32 v0, s0, v31
	s_waitcnt lgkmcnt(0)
	global_store_dwordx4 v[24:25], v[34:37], off
	ds_read_b128 v[34:37], v33 offset:18432
	v_lshrrev_b32_e32 v0, 8, v0
	v_mad_i32_i24 v24, v0, s1, v38
	v_ashrrev_i32_e32 v25, 31, v24
	v_lshlrev_b64 v[24:25], 15, v[24:25]
	v_lshl_add_u64 v[24:25], v[8:9], 0, v[24:25]
	v_add_u32_e32 v0, s0, v32
	s_waitcnt lgkmcnt(0)
	global_store_dwordx4 v[24:25], v[34:37], off
	ds_read_b128 v[34:37], v33 offset:27648
	v_lshrrev_b32_e32 v0, 8, v0
	v_mad_i32_i24 v24, v0, s1, v38
	v_ashrrev_i32_e32 v25, 31, v24
	v_lshlrev_b64 v[24:25], 15, v[24:25]
	v_lshl_add_u64 v[24:25], v[10:11], 0, v[24:25]
	s_waitcnt lgkmcnt(0)
	global_store_dwordx4 v[24:25], v[34:37], off
	s_barrier
	s_mov_b64 s[0:1], 0

; __device__ __forceinline__ unsigned hw_xcc_id() { return (unsigned)__builtin_amdgcn_s_getreg((3 << 11) | 20) & 0xFu; }
; template <class Epi, bool DYN = false>
; __device__ __forceinline__ void gemm_phase(LAS unsigned char* lds, const Gemm g, const Epi& E, int wave, unsigned* ctr = nullptr) {
;     ...
;     const int xcd = (int)(hw_xcc_id() & 7u); int ticket = 0;
;     auto rng_cnt = [&](int x) { const int q = S.nwg / NXCD, r = S.nwg % NXCD; return q + (x < r ? 1 : 0); };
;     auto rng_start = [&](int x) { const int q = S.nwg / NXCD, r = S.nwg % NXCD; return x < r ? x * (q + 1) : r * (q + 1) + (x - r) * q; };
;     auto decode = [&](int wgid, Unit& u) { const int nig = WGM * S.nN, gid = wgid / nig, fm = gid * WGM, gsz = (S.nM - fm) < WGM ? (S.nM - fm) : WGM; u.pm = fm + ((wgid % nig) % gsz); u.pn = (wgid % nig) / gsz; u.b = 0; };
;     auto issue = [&]() { if (tid == 0) ticket = (int)__hip_atomic_fetch_add(ctr + xcd * 16, 1u, __ATOMIC_RELAXED, __HIP_MEMORY_SCOPE_AGENT); };
;     auto publish = [&](int si) { if (tid == 0) { int wg = -1;
;             if (ticket < rng_cnt(xcd)) wg = rng_start(xcd) + ticket;
;             else { for (int k = 1; k < 8; ++k) { const int x2 = (xcd + k) & 7; const int t2 = (int)__hip_atomic_fetch_add(ctr + x2 * 16, 1u, __ATOMIC_RELAXED, __HIP_MEMORY_SCOPE_AGENT); if (t2 < rng_cnt(x2)) { wg = rng_start(x2) + t2; break; } } }
;             slot[si] = wg; } };
;     if (DYN) { issue(); publish(0); __syncthreads(); const int w0 = __builtin_amdgcn_readfirstlane(slot[0]); if (w0 < 0) return; decode(w0, cur); issue(); }
.LBB0_797:
	v_readlane_b32 s0, v254, 43
	s_mul_i32 s5, s0, 6
	s_and_b64 vcc, exec, s[2:3]
	v_readlane_b32 s1, v254, 44
	s_cbranch_vccz .LBB0_869
	v_readlane_b32 s0, v254, 51
	s_cmp_eq_u32 s0, 2
	s_cselect_b32 s0, 1, 5
	s_add_i32 s0, s0, s5
	s_lshl_b32 s0, s0, 7
	s_ashr_i32 s1, s0, 31
	s_lshl_b64 s[0:1], s[0:1], 2
	v_readlane_b32 s2, v254, 47
	s_add_u32 s4, s2, s0
	v_readlane_b32 s0, v254, 48
	v_mbcnt_hi_u32_b32 v0, -1, v222
	s_addc_u32 s7, s0, s1
	s_mov_b32 s0, s80
	v_or_b32_e32 v192, s92, v0
	s_getreg_b32 s9, hwreg(HW_REG_XCC_ID, 0, 4)
	s_waitcnt vmcnt(0) lgkmcnt(0)
	v_mov_b32_e32 v193, 0
	v_readfirstlane_b32 s22, v192
	s_and_b32 s8, s9, 7
	v_cmp_eq_u32_e64 s[36:37], 0, v192
	s_and_saveexec_b64 s[0:1], s[36:37]
	s_cbranch_execz .LBB0_800
	s_lshl_b32 s2, s8, 6
	s_add_u32 s2, s4, s2
	s_addc_u32 s3, s7, 0
	v_mov_b64_e32 v[2:3], s[2:3]
	global_atomic_add v193, v[2:3], v224, off sc0

; template <class Epi, bool DYN = false>
; __device__ __forceinline__ void gemm_phase(LAS unsigned char* lds, const Gemm g, const Epi& E, int wave, unsigned* ctr = nullptr) {
;     ...
;     auto issue = [&]() { if (tid == 0) ticket = (int)__hip_atomic_fetch_add(ctr + xcd * 16, 1u, __ATOMIC_RELAXED, __HIP_MEMORY_SCOPE_AGENT); };
;     auto publish = [&](int si) { if (tid == 0) { int wg = -1;
;             if (ticket < rng_cnt(xcd)) wg = rng_start(xcd) + ticket;
;             else { for (int k = 1; k < 8; ++k) { const int x2 = (xcd + k) & 7; const int t2 = (int)__hip_atomic_fetch_add(ctr + x2 * 16, 1u, __ATOMIC_RELAXED, __HIP_MEMORY_SCOPE_AGENT); if (t2 < rng_cnt(x2)) { wg = rng_start(x2) + t2; break; } } }
;             slot[si] = wg; } };
;     if (DYN) { issue(); publish(0); __syncthreads(); const int w0 = __builtin_amdgcn_readfirstlane(slot[0]); if (w0 < 0) return; decode(w0, cur); issue(); }
.LBB0_832:
	s_or_b64 exec, exec, s[26:27]
	v_readlane_b32 s0, v254, 3
	s_waitcnt lgkmcnt(0)
	s_barrier
	v_mov_b32_e32 v0, s0
	ds_read_b32 v0, v0
	s_waitcnt lgkmcnt(0)
	v_readfirstlane_b32 s2, v0
	s_cmp_lt_i32 s2, 0
	s_cbranch_scc1 .LBB0_868
	s_and_saveexec_b64 s[0:1], s[36:37]
	s_cbranch_execz .LBB0_835
	s_lshl_b32 s3, s8, 6
	s_add_u32 s18, s4, s3
	s_addc_u32 s19, s7, 0
	v_mov_b64_e32 v[2:3], s[18:19]
	s_waitcnt vmcnt(0)
	global_atomic_add v193, v[2:3], v224, off sc0

; template <class Epi, bool DYN = false>
; __device__ __forceinline__ void gemm_phase(LAS unsigned char* lds, const Gemm g, const Epi& E, int wave, unsigned* ctr = nullptr) {
;     ...
;     for (;;) {
;         bool has_next = DYN ? false : S.next(ui + 1, nxt);
;         const char* nA = has_next ? (const char*)(g.A + (size_t)nxt.b * g.sA) + (size_t)nxt.pm * tstepA : cA; const char* nB = has_next ? (const char*)(g.Bt + (size_t)nxt.b * g.sB) + (size_t)nxt.pn * tstepB : cB;
;         for (int t = 0; t < nt; t += 2) {
;             const bool last = (t == nt - 2);
;             if (DYN && last) { const int nw = __builtin_amdgcn_readfirstlane(slot[(ui + 1) & 1]); has_next = nw >= 0;
;                 if (has_next) { decode(nw, nxt); nA = (const char*)g.A + (size_t)nxt.pm * tstepA; nB = (const char*)g.Bt + (size_t)nxt.pn * tstepB; } }
;             const char* a1 = cA + (size_t)(t + 1) * kstepA;
;             const char* a2 = last ? nA : cA + (size_t)(t + 2) * kstepA; const char* b2 = last ? nB : cB + (size_t)(t + 2) * kstepB;
;             const char* a3 = a2 + kstepA; const char* b3 = b2 + kstepB;
.LBB0_839:
	s_add_u32 s7, s26, 0x10000
	s_addc_u32 s8, s27, 0
	s_andn2_b32 s0, 1, s4
	s_lshl_b32 s0, s0, 2
	s_add_i32 s9, s0, 0
	s_add_i32 s9, s9, 0x20040
	s_add_u32 s0, s62, 0xc000
	s_addc_u32 s1, s63, 0
	s_waitcnt lgkmcnt(0)
	v_lshl_add_u64 v[188:189], s[0:1], 0, v[184:185]
	v_lshl_add_u64 v[190:191], s[0:1], 0, v[186:187]
	s_mov_b64 s[66:67], 0
	s_mov_b32 s10, -2
	s_mov_b64 s[68:69], 0
	s_mov_b64 s[46:47], s[62:63]
	s_branch .LBB0_848

; #define PG8_STAGE(bufoff, gbase, voff) do { _Pragma("unroll") for (int _i = 0; _i < 2; ++_i) \
;         __builtin_amdgcn_global_load_lds((const unsigned*)((const char*)(gbase) + (voff)[_i]), (LAS unsigned*)(lds + (bufoff) + ldsw + _i * 8192), 16, 0, 0); } while (0)
; #define PG8_LDA(dst, b, h) do { _Pragma("unroll") for (int m = 0; m < 4; ++m) _Pragma("unroll") for (int k = 0; k < 2; ++k) dst[m][k] = *(const LAS bf16x8*)(lds + PG8_SA(b, h) + aoff + m * 2048 + k * 1024); } while (0)
; #define PG8_LDB(dst, b, h) do { _Pragma("unroll") for (int n = 0; n < 2; ++n) _Pragma("unroll") for (int k = 0; k < 2; ++k) dst[n][k] = *(const LAS bf16x8*)(lds + PG8_SB(b, h) + boff + n * 2048 + k * 1024); } while (0)
; #define PG8_MMA(ai, bj, At, Bt) do { __builtin_amdgcn_s_setprio(1); _Pragma("unroll") for (int m = 0; m < 4; ++m) _Pragma("unroll") for (int n = 0; n < 2; ++n) _Pragma("unroll") for (int k = 0; k < 2; ++k) \
;         acc[ai][bj][m][n] = __builtin_amdgcn_mfma_f32_16x16x32_bf16(Bt[n][k], At[m][k], acc[ai][bj][m][n], 0, 0, 0); __builtin_amdgcn_s_setprio(0); } while (0)
; #define PG8_WAIT_L(n) asm volatile("s_waitcnt lgkmcnt(" #n ")" ::: "memory")
; #define PG8_BAR __builtin_amdgcn_s_barrier()
; #define PG8_SCHED __builtin_amdgcn_sched_barrier(0)
; template <class Epi, bool DYN = false>
; __device__ __forceinline__ void gemm_phase(LAS unsigned char* lds, const Gemm g, const Epi& E, int wave, unsigned* ctr = nullptr) {
;     ...
;             const char* a1 = cA + (size_t)(t + 1) * kstepA;
;             const char* a2 = last ? nA : cA + (size_t)(t + 2) * kstepA; const char* b2 = last ? nB : cB + (size_t)(t + 2) * kstepB;
;             const char* a3 = a2 + kstepA; const char* b3 = b2 + kstepB;
;             PG8_LDB(B0, 0, 0); PG8_SCHED; PG8_LDA(At, 0, 0); PG8_STAGE(PG8_SA(1, 1), a1 + hstepA, voffA);
;             PG8_WAIT_L(8); PG8_BAR; PG8_WAIT_L(0); PG8_MMA(0, 0, At, B0); PG8_BAR; PG8_SCHED;
;             PG8_LDB(B1, 0, 1); PG8_STAGE(PG8_SB(0, 0), b2, voffB);
;             PG8_BAR; PG8_WAIT_L(0); PG8_MMA(0, 1, At, B1); PG8_BAR;
;             PG8_LDA(At, 0, 1); PG8_STAGE(PG8_SA(0, 0), a2, voffA);
;             PG8_BAR; PG8_WAIT_L(0); PG8_MMA(1, 0, At, B0); PG8_BAR; PG8_SCHED;
.LBB0_852:
	s_add_i32 s10, s10, 2
	s_add_u32 s0, s62, s68
	s_addc_u32 s1, s63, s69
	s_add_u32 s38, s0, 0x10000
	s_addc_u32 s39, s1, 0
	s_and_b64 s[0:1], s[70:71], exec
	s_cselect_b32 s73, s47, s39
	s_cselect_b32 s72, s46, s38
	s_add_u32 s74, s7, s68
	s_addc_u32 s75, s8, s69
	s_add_u32 s38, s72, 0x8000
	s_addc_u32 s39, s73, 0
	s_add_i32 s76, 0, 0x10000
	v_add_u32_e32 v142, s76, v200
	ds_read_b128 v[130:133], v142
	ds_read_b128 v[134:137], v142 offset:1024
	ds_read_b128 v[138:141], v142 offset:2048
	ds_read_b128 v[142:145], v142 offset:3072
	s_and_b64 s[0:1], s[70:71], exec
	s_cselect_b32 s71, s27, s75
	s_cselect_b32 s70, s26, s74
	v_lshl_add_u64 v[196:197], v[190:191], 0, s[68:69]
	s_add_i32 m0, s33, 0xc000
	ds_read_b128 v[146:149], v202
	ds_read_b128 v[150:153], v202 offset:1024
	ds_read_b128 v[154:157], v202 offset:2048
	ds_read_b128 v[158:161], v202 offset:3072
	ds_read_b128 v[162:165], v202 offset:4096
	ds_read_b128 v[166:169], v202 offset:5120
	ds_read_b128 v[170:173], v202 offset:6144
	ds_read_b128 v[174:177], v202 offset:7168
	global_load_lds_dwordx4 v[196:197], off
	v_lshl_add_u64 v[196:197], v[188:189], 0, s[68:69]
	s_add_i32 m0, s33, 0xe000
	s_nop 0
	global_load_lds_dwordx4 v[196:197], off
	s_waitcnt lgkmcnt(8)
	s_barrier
	s_waitcnt lgkmcnt(0)
	s_setprio 1
	s_waitcnt lgkmcnt(0)
	v_mfma_f32_16x16x32_bf16 v[126:129], v[130:133], v[146:149], v[126:129]
	v_mfma_f32_16x16x32_bf16 v[122:125], v[138:141], v[146:149], v[122:125]
	v_mfma_f32_16x16x32_bf16 v[118:121], v[130:133], v[154:157], v[118:121]
	v_mfma_f32_16x16x32_bf16 v[114:117], v[138:141], v[154:157], v[114:117]
	v_mfma_f32_16x16x32_bf16 v[110:113], v[130:133], v[162:165], v[110:113]
	v_mfma_f32_16x16x32_bf16 v[106:109], v[138:141], v[162:165], v[106:109]
	v_mfma_f32_16x16x32_bf16 v[102:105], v[130:133], v[170:173], v[102:105]
	v_mfma_f32_16x16x32_bf16 v[94:97], v[138:141], v[170:173], v[94:97]
	v_mfma_f32_16x16x32_bf16 v[126:129], v[134:137], v[150:153], v[126:129]
	v_mfma_f32_16x16x32_bf16 v[122:125], v[142:145], v[150:153], v[122:125]
	v_mfma_f32_16x16x32_bf16 v[118:121], v[134:137], v[158:161], v[118:121]
	v_mfma_f32_16x16x32_bf16 v[114:117], v[142:145], v[158:161], v[114:117]
	v_mfma_f32_16x16x32_bf16 v[110:113], v[134:137], v[166:169], v[110:113]
	v_mfma_f32_16x16x32_bf16 v[106:109], v[142:145], v[166:169], v[106:109]
	v_mfma_f32_16x16x32_bf16 v[102:105], v[134:137], v[174:177], v[102:105]
	v_mfma_f32_16x16x32_bf16 v[94:97], v[142:145], v[174:177], v[94:97]
	s_setprio 0
	s_barrier
	s_add_i32 s74, 0, 0x14000
	s_add_i32 s0, s76, s28
	v_add_u32_e32 v212, s74, v200
	v_lshl_add_u64 v[216:217], s[70:71], 0, v[0:1]
	s_mov_b32 m0, s0
	ds_read_b128 v[196:199], v212
	ds_read_b128 v[204:207], v212 offset:1024
	ds_read_b128 v[208:211], v212 offset:2048
	ds_read_b128 v[212:215], v212 offset:3072
	global_load_lds_dwordx4 v[216:217], off
	v_lshl_add_u64 v[216:217], s[70:71], 0, v[182:183]
	s_add_i32 m0, s0, 0x2000
	s_nop 0
	global_load_lds_dwordx4 v[216:217], off
	s_barrier
	s_waitcnt lgkmcnt(0)
	s_setprio 1
	s_waitcnt lgkmcnt(0)
	v_mfma_f32_16x16x32_bf16 v[90:93], v[196:199], v[146:149], v[90:93]
	v_mfma_f32_16x16x32_bf16 v[82:85], v[208:211], v[146:149], v[82:85]
	v_mfma_f32_16x16x32_bf16 v[74:77], v[196:199], v[154:157], v[74:77]
	v_mfma_f32_16x16x32_bf16 v[66:69], v[208:211], v[154:157], v[66:69]
	v_mfma_f32_16x16x32_bf16 v[58:61], v[196:199], v[162:165], v[58:61]
	v_mfma_f32_16x16x32_bf16 v[50:53], v[208:211], v[162:165], v[50:53]
	v_mfma_f32_16x16x32_bf16 v[42:45], v[196:199], v[170:173], v[42:45]
	v_mfma_f32_16x16x32_bf16 v[38:41], v[208:211], v[170:173], v[38:41]
	v_mfma_f32_16x16x32_bf16 v[90:93], v[204:207], v[150:153], v[90:93]
	v_mfma_f32_16x16x32_bf16 v[82:85], v[212:215], v[150:153], v[82:85]
	v_mfma_f32_16x16x32_bf16 v[74:77], v[204:207], v[158:161], v[74:77]
	v_mfma_f32_16x16x32_bf16 v[66:69], v[212:215], v[158:161], v[66:69]
	v_mfma_f32_16x16x32_bf16 v[58:61], v[204:207], v[166:169], v[58:61]
	v_mfma_f32_16x16x32_bf16 v[50:53], v[212:215], v[166:169], v[50:53]
	v_mfma_f32_16x16x32_bf16 v[42:45], v[204:207], v[174:177], v[42:45]
	v_mfma_f32_16x16x32_bf16 v[38:41], v[212:215], v[174:177], v[38:41]
	s_setprio 0
	s_mov_b32 m0, s33
	v_lshl_add_u64 v[216:217], s[72:73], 0, v[178:179]
	s_barrier
	ds_read_b128 v[146:149], v202 offset:16384
	ds_read_b128 v[150:153], v202 offset:17408
	ds_read_b128 v[154:157], v202 offset:18432
	ds_read_b128 v[158:161], v202 offset:19456
	ds_read_b128 v[162:165], v202 offset:20480
	ds_read_b128 v[166:169], v202 offset:21504
	ds_read_b128 v[170:173], v202 offset:22528
	ds_read_b128 v[174:177], v202 offset:23552
	global_load_lds_dwordx4 v[216:217], off
	v_lshl_add_u64 v[216:217], s[72:73], 0, v[180:181]
	s_mov_b32 m0, s48
	s_nop 0
	global_load_lds_dwordx4 v[216:217], off
	s_barrier
	s_waitcnt lgkmcnt(0)
	s_setprio 1
	s_waitcnt lgkmcnt(0)
	v_mfma_f32_16x16x32_bf16 v[34:37], v[130:133], v[146:149], v[34:37]
	v_mfma_f32_16x16x32_bf16 v[26:29], v[138:141], v[146:149], v[26:29]
	v_mfma_f32_16x16x32_bf16 v[22:25], v[130:133], v[154:157], v[22:25]
	v_mfma_f32_16x16x32_bf16 v[18:21], v[138:141], v[154:157], v[18:21]
	v_mfma_f32_16x16x32_bf16 v[14:17], v[130:133], v[162:165], v[14:17]
	v_mfma_f32_16x16x32_bf16 v[10:13], v[138:141], v[162:165], v[10:13]
	v_mfma_f32_16x16x32_bf16 v[6:9], v[130:133], v[170:173], v[6:9]
	v_mfma_f32_16x16x32_bf16 v[2:5], v[138:141], v[170:173], v[2:5]
	v_mfma_f32_16x16x32_bf16 v[34:37], v[134:137], v[150:153], v[34:37]
	v_mfma_f32_16x16x32_bf16 v[26:29], v[142:145], v[150:153], v[26:29]
	v_mfma_f32_16x16x32_bf16 v[22:25], v[134:137], v[158:161], v[22:25]
	v_mfma_f32_16x16x32_bf16 v[18:21], v[142:145], v[158:161], v[18:21]
	v_mfma_f32_16x16x32_bf16 v[14:17], v[134:137], v[166:169], v[14:17]
	v_mfma_f32_16x16x32_bf16 v[10:13], v[142:145], v[166:169], v[10:13]
	v_mfma_f32_16x16x32_bf16 v[6:9], v[134:137], v[174:177], v[6:9]
	v_mfma_f32_16x16x32_bf16 v[2:5], v[142:145], v[174:177], v[2:5]
	s_setprio 0
	s_barrier
; #define PG8_STAGE(bufoff, gbase, voff) do { _Pragma("unroll") for (int _i = 0; _i < 2; ++_i) \
;         __builtin_amdgcn_global_load_lds((const unsigned*)((const char*)(gbase) + (voff)[_i]), (LAS unsigned*)(lds + (bufoff) + ldsw + _i * 8192), 16, 0, 0); } while (0)
; #define PG8_LDA(dst, b, h) do { _Pragma("unroll") for (int m = 0; m < 4; ++m) _Pragma("unroll") for (int k = 0; k < 2; ++k) dst[m][k] = *(const LAS bf16x8*)(lds + PG8_SA(b, h) + aoff + m * 2048 + k * 1024); } while (0)
; #define PG8_LDB(dst, b, h) do { _Pragma("unroll") for (int n = 0; n < 2; ++n) _Pragma("unroll") for (int k = 0; k < 2; ++k) dst[n][k] = *(const LAS bf16x8*)(lds + PG8_SB(b, h) + boff + n * 2048 + k * 1024); } while (0)
; #define PG8_MMA(ai, bj, At, Bt) do { __builtin_amdgcn_s_setprio(1); _Pragma("unroll") for (int m = 0; m < 4; ++m) _Pragma("unroll") for (int n = 0; n < 2; ++n) _Pragma("unroll") for (int k = 0; k < 2; ++k) \
;         acc[ai][bj][m][n] = __builtin_amdgcn_mfma_f32_16x16x32_bf16(Bt[n][k], At[m][k], acc[ai][bj][m][n], 0, 0, 0); __builtin_amdgcn_s_setprio(0); } while (0)
; #define PG8_WAIT_V(n) asm volatile("s_waitcnt vmcnt(" #n ")" ::: "memory")
; #define PG8_WAIT_L(n) asm volatile("s_waitcnt lgkmcnt(" #n ")" ::: "memory")
; #define PG8_BAR __builtin_amdgcn_s_barrier()
; #define PG8_SCHED __builtin_amdgcn_sched_barrier(0)
; template <class Epi, bool DYN = false>
; __device__ __forceinline__ void gemm_phase(LAS unsigned char* lds, const Gemm g, const Epi& E, int wave, unsigned* ctr = nullptr) {
;     ...
;             PG8_STAGE(PG8_SB(0, 1), b2 + hstepB, voffB);
;             PG8_WAIT_V(6); PG8_BAR; PG8_MMA(1, 1, At, B1); PG8_BAR;
;             PG8_LDB(B0, 1, 0); PG8_SCHED; PG8_LDA(At, 1, 0); PG8_STAGE(PG8_SA(0, 1), a2 + hstepA, voffA);
;             PG8_WAIT_L(8); PG8_BAR; PG8_WAIT_L(0); PG8_MMA(0, 0, At, B0); PG8_BAR; PG8_SCHED;
;             PG8_LDB(B1, 1, 1); PG8_STAGE(PG8_SB(1, 0), b3, voffB);
;             PG8_BAR; PG8_WAIT_L(0); PG8_MMA(0, 1, At, B1); PG8_BAR;
	s_add_u32 s0, s70, 0x4000
	s_addc_u32 s1, s71, 0
	s_add_i32 s74, s74, s28
	v_lshl_add_u64 v[130:131], s[0:1], 0, v[0:1]
	s_mov_b32 m0, s74
	s_nop 0
	global_load_lds_dwordx4 v[130:131], off
	v_lshl_add_u64 v[130:131], s[0:1], 0, v[182:183]
	s_add_i32 m0, s74, 0x2000
	s_nop 0
	global_load_lds_dwordx4 v[130:131], off
	s_waitcnt vmcnt(6)
	s_barrier
	s_setprio 1
	v_mfma_f32_16x16x32_bf16 v[98:101], v[196:199], v[146:149], v[98:101]
	v_mfma_f32_16x16x32_bf16 v[86:89], v[208:211], v[146:149], v[86:89]
	v_mfma_f32_16x16x32_bf16 v[78:81], v[196:199], v[154:157], v[78:81]
	v_mfma_f32_16x16x32_bf16 v[70:73], v[208:211], v[154:157], v[70:73]
	v_mfma_f32_16x16x32_bf16 v[62:65], v[196:199], v[162:165], v[62:65]
	v_mfma_f32_16x16x32_bf16 v[54:57], v[208:211], v[162:165], v[54:57]
	v_mfma_f32_16x16x32_bf16 v[46:49], v[196:199], v[170:173], v[46:49]
	v_mfma_f32_16x16x32_bf16 v[30:33], v[208:211], v[170:173], v[30:33]
	v_mfma_f32_16x16x32_bf16 v[98:101], v[204:207], v[150:153], v[98:101]
	v_mfma_f32_16x16x32_bf16 v[86:89], v[212:215], v[150:153], v[86:89]
	v_mfma_f32_16x16x32_bf16 v[78:81], v[204:207], v[158:161], v[78:81]
	v_mfma_f32_16x16x32_bf16 v[70:73], v[212:215], v[158:161], v[70:73]
	v_mfma_f32_16x16x32_bf16 v[62:65], v[204:207], v[166:169], v[62:65]
	v_mfma_f32_16x16x32_bf16 v[54:57], v[212:215], v[166:169], v[54:57]
	v_mfma_f32_16x16x32_bf16 v[46:49], v[204:207], v[174:177], v[46:49]
	v_mfma_f32_16x16x32_bf16 v[30:33], v[212:215], v[174:177], v[30:33]
	s_setprio 0
	s_add_i32 s74, 0, 0x18000
	v_add_u32_e32 v130, s74, v200
	s_barrier
	ds_read_b128 v[196:199], v130
	ds_read_b128 v[204:207], v130 offset:1024
	ds_read_b128 v[208:211], v130 offset:2048
	ds_read_b128 v[212:215], v130 offset:3072
	s_add_u32 s0, s72, 0x4000
	s_addc_u32 s1, s73, 0
	s_mov_b32 m0, s86
	v_lshl_add_u64 v[130:131], s[0:1], 0, v[178:179]
	ds_read_b128 v[146:149], v202 offset:32768
	ds_read_b128 v[150:153], v202 offset:33792
	ds_read_b128 v[154:157], v202 offset:34816
	ds_read_b128 v[158:161], v202 offset:35840
	ds_read_b128 v[162:165], v202 offset:36864
	ds_read_b128 v[166:169], v202 offset:37888
	ds_read_b128 v[170:173], v202 offset:38912
	ds_read_b128 v[174:177], v202 offset:39936
	global_load_lds_dwordx4 v[130:131], off
	v_lshl_add_u64 v[130:131], s[0:1], 0, v[180:181]
	s_mov_b32 m0, s87
	s_nop 0
	global_load_lds_dwordx4 v[130:131], off
	s_waitcnt lgkmcnt(8)
	s_barrier
	s_waitcnt lgkmcnt(0)
	s_setprio 1
	s_waitcnt lgkmcnt(0)
	v_mfma_f32_16x16x32_bf16 v[126:129], v[196:199], v[146:149], v[126:129]
	v_mfma_f32_16x16x32_bf16 v[122:125], v[208:211], v[146:149], v[122:125]
	v_mfma_f32_16x16x32_bf16 v[118:121], v[196:199], v[154:157], v[118:121]
	v_mfma_f32_16x16x32_bf16 v[114:117], v[208:211], v[154:157], v[114:117]
	v_mfma_f32_16x16x32_bf16 v[110:113], v[196:199], v[162:165], v[110:113]
	v_mfma_f32_16x16x32_bf16 v[106:109], v[208:211], v[162:165], v[106:109]
	v_mfma_f32_16x16x32_bf16 v[102:105], v[196:199], v[170:173], v[102:105]
	v_mfma_f32_16x16x32_bf16 v[94:97], v[208:211], v[170:173], v[94:97]
	v_mfma_f32_16x16x32_bf16 v[126:129], v[204:207], v[150:153], v[126:129]
	v_mfma_f32_16x16x32_bf16 v[122:125], v[212:215], v[150:153], v[122:125]
	v_mfma_f32_16x16x32_bf16 v[118:121], v[204:207], v[158:161], v[118:121]
	v_mfma_f32_16x16x32_bf16 v[114:117], v[212:215], v[158:161], v[114:117]
	v_mfma_f32_16x16x32_bf16 v[110:113], v[204:207], v[166:169], v[110:113]
	v_mfma_f32_16x16x32_bf16 v[106:109], v[212:215], v[166:169], v[106:109]
	v_mfma_f32_16x16x32_bf16 v[102:105], v[204:207], v[174:177], v[102:105]
	v_mfma_f32_16x16x32_bf16 v[94:97], v[212:215], v[174:177], v[94:97]
	s_setprio 0
	s_barrier
	s_add_u32 s0, s70, 0x8000
	v_add_u32_e32 v130, 0, v200
	s_addc_u32 s1, s71, 0
	s_add_i32 s72, s74, s28
	v_add_u32_e32 v142, 0x1c000, v130
	v_lshl_add_u64 v[216:217], s[0:1], 0, v[0:1]
	s_mov_b32 m0, s72
	ds_read_b128 v[130:133], v142
	ds_read_b128 v[134:137], v142 offset:1024
	ds_read_b128 v[138:141], v142 offset:2048
	ds_read_b128 v[142:145], v142 offset:3072
	global_load_lds_dwordx4 v[216:217], off
	v_lshl_add_u64 v[216:217], s[0:1], 0, v[182:183]
	s_add_i32 m0, s72, 0x2000
	s_nop 0
	global_load_lds_dwordx4 v[216:217], off
	s_barrier
	s_waitcnt lgkmcnt(0)
	s_setprio 1
	s_waitcnt lgkmcnt(0)
	v_mfma_f32_16x16x32_bf16 v[90:93], v[130:133], v[146:149], v[90:93]
	v_mfma_f32_16x16x32_bf16 v[82:85], v[138:141], v[146:149], v[82:85]
	v_mfma_f32_16x16x32_bf16 v[74:77], v[130:133], v[154:157], v[74:77]
	v_mfma_f32_16x16x32_bf16 v[66:69], v[138:141], v[154:157], v[66:69]
	v_mfma_f32_16x16x32_bf16 v[58:61], v[130:133], v[162:165], v[58:61]
	v_mfma_f32_16x16x32_bf16 v[50:53], v[138:141], v[162:165], v[50:53]
	v_mfma_f32_16x16x32_bf16 v[42:45], v[130:133], v[170:173], v[42:45]
	v_mfma_f32_16x16x32_bf16 v[38:41], v[138:141], v[170:173], v[38:41]
	v_mfma_f32_16x16x32_bf16 v[90:93], v[134:137], v[150:153], v[90:93]
	v_mfma_f32_16x16x32_bf16 v[82:85], v[142:145], v[150:153], v[82:85]
	v_mfma_f32_16x16x32_bf16 v[74:77], v[134:137], v[158:161], v[74:77]
	v_mfma_f32_16x16x32_bf16 v[66:69], v[142:145], v[158:161], v[66:69]
	v_mfma_f32_16x16x32_bf16 v[58:61], v[134:137], v[166:169], v[58:61]
	v_mfma_f32_16x16x32_bf16 v[50:53], v[142:145], v[166:169], v[50:53]
	v_mfma_f32_16x16x32_bf16 v[42:45], v[134:137], v[174:177], v[42:45]
	v_mfma_f32_16x16x32_bf16 v[38:41], v[142:145], v[174:177], v[38:41]
	s_setprio 0
	s_mov_b32 m0, s88
	v_lshl_add_u64 v[216:217], s[38:39], 0, v[178:179]
	s_barrier
; #define PG8_STAGE(bufoff, gbase, voff) do { _Pragma("unroll") for (int _i = 0; _i < 2; ++_i) \
;         __builtin_amdgcn_global_load_lds((const unsigned*)((const char*)(gbase) + (voff)[_i]), (LAS unsigned*)(lds + (bufoff) + ldsw + _i * 8192), 16, 0, 0); } while (0)
; #define PG8_LDA(dst, b, h) do { _Pragma("unroll") for (int m = 0; m < 4; ++m) _Pragma("unroll") for (int k = 0; k < 2; ++k) dst[m][k] = *(const LAS bf16x8*)(lds + PG8_SA(b, h) + aoff + m * 2048 + k * 1024); } while (0)
; #define PG8_MMA(ai, bj, At, Bt) do { __builtin_amdgcn_s_setprio(1); _Pragma("unroll") for (int m = 0; m < 4; ++m) _Pragma("unroll") for (int n = 0; n < 2; ++n) _Pragma("unroll") for (int k = 0; k < 2; ++k) \
;         acc[ai][bj][m][n] = __builtin_amdgcn_mfma_f32_16x16x32_bf16(Bt[n][k], At[m][k], acc[ai][bj][m][n], 0, 0, 0); __builtin_amdgcn_s_setprio(0); } while (0)
; #define PG8_WAIT_L(n) asm volatile("s_waitcnt lgkmcnt(" #n ")" ::: "memory")
; #define PG8_BAR __builtin_amdgcn_s_barrier()
; #define PG8_SCHED __builtin_amdgcn_sched_barrier(0)
; template <class Epi, bool DYN = false>
; __device__ __forceinline__ void gemm_phase(LAS unsigned char* lds, const Gemm g, const Epi& E, int wave, unsigned* ctr = nullptr) {
;     ...
;     auto publish = [&](int si) { if (tid == 0) { int wg = -1;
;             if (ticket < rng_cnt(xcd)) wg = rng_start(xcd) + ticket;
;             else { for (int k = 1; k < 8; ++k) { const int x2 = (xcd + k) & 7; const int t2 = (int)__hip_atomic_fetch_add(ctr + x2 * 16, 1u, __ATOMIC_RELAXED, __HIP_MEMORY_SCOPE_AGENT); if (t2 < rng_cnt(x2)) { wg = rng_start(x2) + t2; break; } } }
;     ...
;             PG8_LDA(At, 1, 1); PG8_STAGE(PG8_SA(1, 0), a3, voffA);
;             PG8_BAR; PG8_WAIT_L(0); PG8_MMA(1, 0, At, B0); PG8_BAR; PG8_SCHED;
;             if (DYN && t == 0) publish((ui + 1) & 1);
	ds_read_b128 v[170:173], v202 offset:49152
	ds_read_b128 v[174:177], v202 offset:50176
	ds_read_b128 v[162:165], v202 offset:51200
	ds_read_b128 v[166:169], v202 offset:52224
	ds_read_b128 v[154:157], v202 offset:53248
	ds_read_b128 v[158:161], v202 offset:54272
	ds_read_b128 v[146:149], v202 offset:55296
	ds_read_b128 v[150:153], v202 offset:56320
	global_load_lds_dwordx4 v[216:217], off
	v_lshl_add_u64 v[216:217], s[38:39], 0, v[180:181]
	s_mov_b32 m0, s89
	s_nop 0
	global_load_lds_dwordx4 v[216:217], off
	s_barrier
	s_waitcnt lgkmcnt(0)
	s_setprio 1
	s_waitcnt lgkmcnt(0)
	v_mfma_f32_16x16x32_bf16 v[34:37], v[196:199], v[170:173], v[34:37]
	v_mfma_f32_16x16x32_bf16 v[26:29], v[208:211], v[170:173], v[26:29]
	v_mfma_f32_16x16x32_bf16 v[22:25], v[196:199], v[162:165], v[22:25]
	v_mfma_f32_16x16x32_bf16 v[18:21], v[208:211], v[162:165], v[18:21]
	v_mfma_f32_16x16x32_bf16 v[14:17], v[196:199], v[154:157], v[14:17]
	v_mfma_f32_16x16x32_bf16 v[10:13], v[208:211], v[154:157], v[10:13]
	v_mfma_f32_16x16x32_bf16 v[6:9], v[196:199], v[146:149], v[6:9]
	v_mfma_f32_16x16x32_bf16 v[2:5], v[208:211], v[146:149], v[2:5]
	v_mfma_f32_16x16x32_bf16 v[34:37], v[204:207], v[174:177], v[34:37]
	v_mfma_f32_16x16x32_bf16 v[26:29], v[212:215], v[174:177], v[26:29]
	v_mfma_f32_16x16x32_bf16 v[22:25], v[204:207], v[166:169], v[22:25]
	v_mfma_f32_16x16x32_bf16 v[18:21], v[212:215], v[166:169], v[18:21]
	v_mfma_f32_16x16x32_bf16 v[14:17], v[204:207], v[158:161], v[14:17]
	v_mfma_f32_16x16x32_bf16 v[10:13], v[212:215], v[158:161], v[10:13]
	v_mfma_f32_16x16x32_bf16 v[6:9], v[204:207], v[150:153], v[6:9]
	v_mfma_f32_16x16x32_bf16 v[2:5], v[212:215], v[150:153], v[2:5]
	s_setprio 0
	s_barrier
	v_or_b32_e32 v196, s10, v192
	v_cmp_eq_u32_e64 s[38:39], 0, v196
	s_and_saveexec_b64 s[72:73], s[38:39]
	s_cbranch_execz .LBB0_847
	v_cmp_lt_i32_e32 vcc, s91, v193
	v_add_u32_e32 v203, s61, v193
	v_mov_b32_e32 v204, v203
	s_and_saveexec_b64 s[74:75], vcc
	s_cbranch_execz .LBB0_846
	v_mov_b64_e32 v[196:197], s[40:41]
	s_waitcnt vmcnt(0)
	flat_atomic_add v196, v[196:197], v224 sc0
	s_waitcnt vmcnt(0) lgkmcnt(0)
	v_cmp_lt_i32_e64 s[38:39], s91, v196
	v_add_u32_e32 v204, s3, v196
	s_and_saveexec_b64 s[0:1], s[38:39]
	s_cbranch_execz .LBB0_845
	v_mov_b64_e32 v[196:197], s[42:43]
	flat_atomic_add v196, v[196:197], v224 sc0
	s_waitcnt vmcnt(0) lgkmcnt(0)
	v_cmp_lt_i32_e64 s[38:39], s91, v196
	v_add_u32_e32 v204, s2, v196
	s_and_saveexec_b64 s[76:77], s[38:39]
	s_cbranch_execz .LBB0_844
	v_mov_b64_e32 v[196:197], s[44:45]
	flat_atomic_add v196, v[196:197], v224 sc0
	s_waitcnt vmcnt(0) lgkmcnt(0)
	v_cmp_lt_i32_e64 s[38:39], s91, v196
	v_add_u32_e32 v204, s22, v196
	s_and_saveexec_b64 s[78:79], s[38:39]
	s_cbranch_execz .LBB0_843
	v_mov_b64_e32 v[196:197], s[50:51]
	flat_atomic_add v196, v[196:197], v224 sc0
	s_waitcnt vmcnt(0) lgkmcnt(0)
	v_cmp_lt_i32_e64 s[38:39], s91, v196
	v_add_u32_e32 v204, s23, v196
	s_and_saveexec_b64 s[80:81], s[38:39]
	s_cbranch_execz .LBB0_842
	v_mov_b64_e32 v[196:197], s[54:55]
	flat_atomic_add v196, v[196:197], v224 sc0
	s_movk_i32 s92, 0x60
	s_waitcnt vmcnt(0) lgkmcnt(0)
	v_cmp_lt_i32_e64 s[38:39], s91, v196
	v_add_u32_e32 v204, s60, v196
	s_and_saveexec_b64 s[82:83], s[38:39]
	s_cbranch_execz .LBB0_841
	v_mov_b64_e32 v[196:197], s[58:59]
	flat_atomic_add v196, v[196:197], v224 sc0
	v_readlane_b32 s84, v254, 52
	s_waitcnt vmcnt(0) lgkmcnt(0)
	v_cmp_lt_i32_e64 s[38:39], s91, v196
	v_add_u32_e32 v204, s84, v196
	s_and_saveexec_b64 s[84:85], s[38:39]
	s_cbranch_execz .LBB0_840
	v_readlane_b32 s38, v254, 54
	v_readlane_b32 s39, v254, 55
	s_nop 1
	v_mov_b64_e32 v[196:197], s[38:39]
	flat_atomic_add v196, v[196:197], v224 sc0
	v_readlane_b32 s38, v254, 56
	s_waitcnt vmcnt(0) lgkmcnt(0)
	s_nop 0
	v_add_u32_e32 v197, s38, v196
	v_cmp_gt_i32_e64 s[38:39], s92, v196
	s_nop 1
	v_cndmask_b32_e64 v204, -1, v197, s[38:39]
	s_branch .LBB0_840
; __device__ __forceinline__ u32x4 pack8(f32x4 v0, f32x4 v1) { u32x4 w; w.x = cvt_pk_bf16(v0[0], v0[1]); w.y = cvt_pk_bf16(v0[2], v0[3]); w.z = cvt_pk_bf16(v1[0], v1[1]); w.w = cvt_pk_bf16(v1[2], v1[3]); return w; }
; template <class Epi, bool DYN = false>
; __device__ __forceinline__ void gemm_phase(LAS unsigned char* lds, const Gemm g, const Epi& E, int wave, unsigned* ctr = nullptr) {
;     ...
;         if (!has_next) break;
; #pragma unroll
;         for (int a = 0; a < 2; ++a)
; #pragma unroll
;             for (int b = 0; b < 2; ++b)
; #pragma unroll
;                 for (int m = 0; m < 4; ++m)
; #pragma unroll
;                     for (int n = 0; n < 2; ++n) acc[a][b][m][n] = (f32x4){0.f, 0.f, 0.f, 0.f};
;         cur = nxt; cA = nA; cB = nB; ++ui;
;         if (DYN) issue();
;     __device__ __forceinline__ void operator()(AccRef acc, const Unit& u, int wr, int wc, int fr, int fq, const float (&pre)[8]) const {
;         const int row0 = u.pm * BM + wr * 64 + fr, col0 = u.pn * BM + wc * 32 + 8 * fq;
; #pragma unroll
;         for (int ai = 0; ai < 2; ++ai)
; #pragma unroll
;             for (int m = 0; m < 4; ++m)
; #pragma unroll
;                 for (int bj = 0; bj < 2; ++bj)
;                     gst16(O + (size_t)(row0 + ai * HALF + m * 16) * ldc + col0 + bj * HALF, pack8(acc[ai][bj][m][0], acc[ai][bj][m][1]));
;     }
.LBB0_861:
	v_lshl_add_u32 v136, s6, 8, v194
	v_lshl_or_b32 v130, s5, 8, v201
	v_ashrrev_i32_e32 v137, 31, v136
	v_readlane_b32 s0, v254, 39
	v_ashrrev_i32_e32 v131, 31, v130
	v_lshlrev_b64 v[132:133], 12, v[136:137]
	v_readlane_b32 s1, v254, 40
	v_lshlrev_b64 v[138:139], 1, v[130:131]
	v_cvt_pk_bf16_f32 v134, v122, v123
	v_cvt_pk_bf16_f32 v135, v124, v125
	s_add_u32 s68, s7, 0xffff0000
	v_lshl_add_u64 v[132:133], s[0:1], 0, v[132:133]
	v_lshl_add_u64 v[130:131], v[132:133], 0, v[138:139]
	v_cvt_pk_bf16_f32 v132, v126, v127
	v_cvt_pk_bf16_f32 v133, v128, v129
	global_store_dwordx4 v[130:131], v[132:135], off
	s_addc_u32 s69, s8, -1
	s_nop 0
	v_cvt_pk_bf16_f32 v132, v90, v91
	v_cvt_pk_bf16_f32 v133, v92, v93
	v_cvt_pk_bf16_f32 v134, v82, v83
	v_cvt_pk_bf16_f32 v135, v84, v85
	global_store_dwordx4 v[130:131], v[132:135], off offset:256
	s_nop 1
	v_or_b32_e32 v132, 16, v136
	v_ashrrev_i32_e32 v133, 31, v132
	v_lshlrev_b64 v[132:133], 12, v[132:133]
	v_lshl_add_u64 v[132:133], s[0:1], 0, v[132:133]
	v_lshl_add_u64 v[140:141], v[132:133], 0, v[138:139]
	v_cvt_pk_bf16_f32 v132, v118, v119
	v_cvt_pk_bf16_f32 v133, v120, v121
	v_cvt_pk_bf16_f32 v134, v114, v115
	v_cvt_pk_bf16_f32 v135, v116, v117
	global_store_dwordx4 v[140:141], v[132:135], off
	s_nop 1
	v_cvt_pk_bf16_f32 v132, v74, v75
	v_cvt_pk_bf16_f32 v133, v76, v77
	v_cvt_pk_bf16_f32 v134, v66, v67
	v_cvt_pk_bf16_f32 v135, v68, v69
	global_store_dwordx4 v[140:141], v[132:135], off offset:256
	s_nop 1
	v_or_b32_e32 v132, 32, v136
	v_ashrrev_i32_e32 v133, 31, v132
	v_lshlrev_b64 v[132:133], 12, v[132:133]
	v_lshl_add_u64 v[132:133], s[0:1], 0, v[132:133]
	v_lshl_add_u64 v[140:141], v[132:133], 0, v[138:139]
	v_cvt_pk_bf16_f32 v132, v110, v111
	v_cvt_pk_bf16_f32 v133, v112, v113
	v_cvt_pk_bf16_f32 v134, v106, v107
	v_cvt_pk_bf16_f32 v135, v108, v109
	global_store_dwordx4 v[140:141], v[132:135], off
	s_nop 1
	v_cvt_pk_bf16_f32 v132, v58, v59
	v_cvt_pk_bf16_f32 v133, v60, v61
	v_cvt_pk_bf16_f32 v134, v50, v51
	v_cvt_pk_bf16_f32 v135, v52, v53
	global_store_dwordx4 v[140:141], v[132:135], off offset:256
	s_nop 1
	v_or_b32_e32 v132, 48, v136
	v_ashrrev_i32_e32 v133, 31, v132
	v_lshlrev_b64 v[132:133], 12, v[132:133]
	v_lshl_add_u64 v[132:133], s[0:1], 0, v[132:133]
	v_lshl_add_u64 v[136:137], v[132:133], 0, v[138:139]
	v_cvt_pk_bf16_f32 v132, v102, v103
	v_cvt_pk_bf16_f32 v133, v104, v105
	v_cvt_pk_bf16_f32 v134, v94, v95
	v_cvt_pk_bf16_f32 v135, v96, v97
	s_mov_b64 s[0:1], 0x80000
	global_store_dwordx4 v[136:137], v[132:135], off
	s_nop 1
	v_cvt_pk_bf16_f32 v132, v42, v43
	v_cvt_pk_bf16_f32 v133, v44, v45
	v_cvt_pk_bf16_f32 v134, v38, v39
	v_cvt_pk_bf16_f32 v135, v40, v41
	global_store_dwordx4 v[136:137], v[132:135], off offset:256
	v_lshl_add_u64 v[136:137], v[130:131], 0, s[0:1]
	s_mov_b32 s0, 0x80000
	v_add_co_u32_e32 v138, vcc, s0, v130
	v_cvt_pk_bf16_f32 v132, v34, v35
	v_cvt_pk_bf16_f32 v133, v36, v37
	v_cvt_pk_bf16_f32 v134, v26, v27
	v_cvt_pk_bf16_f32 v135, v28, v29
	s_nop 1
	v_addc_co_u32_e32 v139, vcc, 0, v131, vcc
	s_mov_b64 s[0:1], 0x90000
	global_store_dwordx4 v[138:139], v[132:135], off
	s_nop 1
	v_cvt_pk_bf16_f32 v132, v98, v99
	v_cvt_pk_bf16_f32 v133, v100, v101
	v_cvt_pk_bf16_f32 v134, v86, v87
	v_cvt_pk_bf16_f32 v135, v88, v89
	global_store_dwordx4 v[136:137], v[132:135], off offset:256
	v_lshl_add_u64 v[136:137], v[130:131], 0, s[0:1]
	s_mov_b32 s0, 0x90000
	v_add_co_u32_e32 v138, vcc, s0, v130
	v_cvt_pk_bf16_f32 v132, v22, v23
	v_cvt_pk_bf16_f32 v133, v24, v25
	v_cvt_pk_bf16_f32 v134, v18, v19
	v_cvt_pk_bf16_f32 v135, v20, v21
	s_nop 1
	v_addc_co_u32_e32 v139, vcc, 0, v131, vcc
	s_mov_b64 s[0:1], 0xa0000
	global_store_dwordx4 v[138:139], v[132:135], off
	s_nop 1
	v_cvt_pk_bf16_f32 v132, v78, v79
	v_cvt_pk_bf16_f32 v133, v80, v81
	v_cvt_pk_bf16_f32 v134, v70, v71
	v_cvt_pk_bf16_f32 v135, v72, v73
	global_store_dwordx4 v[136:137], v[132:135], off offset:256
	v_lshl_add_u64 v[136:137], v[130:131], 0, s[0:1]
	s_mov_b32 s0, 0xa0000
	v_add_co_u32_e32 v138, vcc, s0, v130
	v_cvt_pk_bf16_f32 v132, v14, v15
	v_cvt_pk_bf16_f32 v133, v16, v17
	v_cvt_pk_bf16_f32 v134, v10, v11
	v_cvt_pk_bf16_f32 v135, v12, v13
	s_nop 1
	v_addc_co_u32_e32 v139, vcc, 0, v131, vcc
	s_mov_b64 s[0:1], 0xb0000
	global_store_dwordx4 v[138:139], v[132:135], off
	s_nop 1
	v_cvt_pk_bf16_f32 v132, v62, v63
	v_cvt_pk_bf16_f32 v133, v64, v65
	v_cvt_pk_bf16_f32 v134, v54, v55
	v_cvt_pk_bf16_f32 v135, v56, v57
	global_store_dwordx4 v[136:137], v[132:135], off offset:256
	v_lshl_add_u64 v[136:137], v[130:131], 0, s[0:1]
	s_mov_b32 s0, 0xb0000
	v_add_co_u32_e32 v130, vcc, s0, v130
	v_cvt_pk_bf16_f32 v132, v6, v7
	v_cvt_pk_bf16_f32 v133, v8, v9
	v_cvt_pk_bf16_f32 v134, v2, v3
	v_cvt_pk_bf16_f32 v135, v4, v5
	s_nop 1
	v_addc_co_u32_e32 v131, vcc, 0, v131, vcc
	s_andn2_b64 vcc, exec, s[66:67]
	global_store_dwordx4 v[130:131], v[132:135], off
	v_cvt_pk_bf16_f32 v130, v46, v47
	v_cvt_pk_bf16_f32 v131, v48, v49
	s_nop 1
	v_cvt_pk_bf16_f32 v132, v30, v31
	v_cvt_pk_bf16_f32 v133, v32, v33
	global_store_dwordx4 v[136:137], v[130:133], off offset:256
	s_cbranch_vccnz .LBB0_864
	s_and_saveexec_b64 s[0:1], s[36:37]
	s_cbranch_execz .LBB0_838
	v_mov_b64_e32 v[2:3], s[64:65]
	global_atomic_add v193, v[2:3], v224, off sc0
	s_branch .LBB0_838

; __device__ __forceinline__ unsigned hw_xcc_id() { return (unsigned)__builtin_amdgcn_s_getreg((3 << 11) | 20) & 0xFu; }
; template <class Epi, bool DYN = false>
; __device__ __forceinline__ void gemm_phase(LAS unsigned char* lds, const Gemm g, const Epi& E, int wave, unsigned* ctr = nullptr) {
;     ...
;     const int xcd = (int)(hw_xcc_id() & 7u); int ticket = 0;
;     auto rng_cnt = [&](int x) { const int q = S.nwg / NXCD, r = S.nwg % NXCD; return q + (x < r ? 1 : 0); };
;     auto rng_start = [&](int x) { const int q = S.nwg / NXCD, r = S.nwg % NXCD; return x < r ? x * (q + 1) : r * (q + 1) + (x - r) * q; };
;     auto decode = [&](int wgid, Unit& u) { const int nig = WGM * S.nN, gid = wgid / nig, fm = gid * WGM, gsz = (S.nM - fm) < WGM ? (S.nM - fm) : WGM; u.pm = fm + ((wgid % nig) % gsz); u.pn = (wgid % nig) / gsz; u.b = 0; };
;     auto issue = [&]() { if (tid == 0) ticket = (int)__hip_atomic_fetch_add(ctr + xcd * 16, 1u, __ATOMIC_RELAXED, __HIP_MEMORY_SCOPE_AGENT); };
;     auto publish = [&](int si) { if (tid == 0) { int wg = -1;
;             if (ticket < rng_cnt(xcd)) wg = rng_start(xcd) + ticket;
;             else { for (int k = 1; k < 8; ++k) { const int x2 = (xcd + k) & 7; const int t2 = (int)__hip_atomic_fetch_add(ctr + x2 * 16, 1u, __ATOMIC_RELAXED, __HIP_MEMORY_SCOPE_AGENT); if (t2 < rng_cnt(x2)) { wg = rng_start(x2) + t2; break; } } }
;             slot[si] = wg; } };
;     if (DYN) { issue(); publish(0); __syncthreads(); const int w0 = __builtin_amdgcn_readfirstlane(slot[0]); if (w0 < 0) return; decode(w0, cur); issue(); }
.LBB0_869:
	s_nop 0
	v_readlane_b32 s0, v254, 54
	v_readlane_b32 s1, v254, 55
	s_and_b64 vcc, exec, s[0:1]
	s_cbranch_vccz .LBB0_994
	v_readlane_b32 s0, v254, 51
	s_cmp_eq_u32 s0, 1
	s_cselect_b32 s0, 0, 4
	s_add_i32 s0, s0, s5
	s_lshl_b32 s0, s0, 7
	s_ashr_i32 s1, s0, 31
	s_lshl_b64 s[0:1], s[0:1], 2
	v_readlane_b32 s2, v254, 47
	v_mbcnt_hi_u32_b32 v0, -1, v222
	s_add_u32 s4, s2, s0
	v_readlane_b32 s0, v254, 48
	v_or_b32_e32 v194, s92, v0
	s_addc_u32 s5, s0, s1
	s_mov_b32 s0, s80
	v_mov_b32_e32 v202, v194
	s_getreg_b32 s7, hwreg(HW_REG_XCC_ID, 0, 4)
	v_readfirstlane_b32 s18, v202
	s_and_b32 s6, s7, 7
	v_cmp_eq_u32_e64 s[36:37], 0, v202
	v_mov_b32_e32 v203, 0
	s_and_saveexec_b64 s[0:1], s[36:37]
	s_cbranch_execz .LBB0_872
	s_lshl_b32 s2, s6, 6
	s_add_u32 s2, s4, s2
	s_addc_u32 s3, s5, 0
	s_waitcnt lgkmcnt(0)
	v_mov_b64_e32 v[2:3], s[2:3]
	s_waitcnt vmcnt(0)
	global_atomic_add v203, v[2:3], v224, off sc0

; template <class Epi, bool DYN = false>
; __device__ __forceinline__ void gemm_phase(LAS unsigned char* lds, const Gemm g, const Epi& E, int wave, unsigned* ctr = nullptr) {
;     ...
;     auto issue = [&]() { if (tid == 0) ticket = (int)__hip_atomic_fetch_add(ctr + xcd * 16, 1u, __ATOMIC_RELAXED, __HIP_MEMORY_SCOPE_AGENT); };
;     auto publish = [&](int si) { if (tid == 0) { int wg = -1;
;             if (ticket < rng_cnt(xcd)) wg = rng_start(xcd) + ticket;
;             else { for (int k = 1; k < 8; ++k) { const int x2 = (xcd + k) & 7; const int t2 = (int)__hip_atomic_fetch_add(ctr + x2 * 16, 1u, __ATOMIC_RELAXED, __HIP_MEMORY_SCOPE_AGENT); if (t2 < rng_cnt(x2)) { wg = rng_start(x2) + t2; break; } } }
;             slot[si] = wg; } };
;     if (DYN) { issue(); publish(0); __syncthreads(); const int w0 = __builtin_amdgcn_readfirstlane(slot[0]); if (w0 < 0) return; decode(w0, cur); issue(); }
.LBB0_904:
	s_or_b64 exec, exec, s[22:23]
	v_readlane_b32 s0, v254, 3
	s_waitcnt vmcnt(0) lgkmcnt(0)
	s_barrier
	v_mov_b32_e32 v0, s0
	ds_read_b32 v0, v0
	s_waitcnt lgkmcnt(0)
	v_readfirstlane_b32 s2, v0
	s_cmp_lt_i32 s2, 0
	s_cbranch_scc1 .LBB0_940
	s_and_saveexec_b64 s[0:1], s[36:37]
	s_cbranch_execz .LBB0_907
	s_lshl_b32 s3, s6, 6
	s_add_u32 s8, s4, s3
	s_addc_u32 s9, s5, 0
	v_mov_b64_e32 v[2:3], s[8:9]
	global_atomic_add v203, v[2:3], v224, off sc0

; template <class Epi, bool DYN = false>
; __device__ __forceinline__ void gemm_phase(LAS unsigned char* lds, const Gemm g, const Epi& E, int wave, unsigned* ctr = nullptr) {
;     ...
;     for (;;) {
;         bool has_next = DYN ? false : S.next(ui + 1, nxt);
;         const char* nA = has_next ? (const char*)(g.A + (size_t)nxt.b * g.sA) + (size_t)nxt.pm * tstepA : cA; const char* nB = has_next ? (const char*)(g.Bt + (size_t)nxt.b * g.sB) + (size_t)nxt.pn * tstepB : cB;
;         for (int t = 0; t < nt; t += 2) {
;             const bool last = (t == nt - 2);
;             if (DYN && last) { const int nw = __builtin_amdgcn_readfirstlane(slot[(ui + 1) & 1]); has_next = nw >= 0;
;                 if (has_next) { decode(nw, nxt); nA = (const char*)g.A + (size_t)nxt.pm * tstepA; nB = (const char*)g.Bt + (size_t)nxt.pn * tstepB; } }
;             const char* a1 = cA + (size_t)(t + 1) * kstepA;
;             const char* a2 = last ? nA : cA + (size_t)(t + 2) * kstepA; const char* b2 = last ? nB : cB + (size_t)(t + 2) * kstepB;
;             const char* a3 = a2 + kstepA; const char* b3 = b2 + kstepB;
.LBB0_911:
	s_add_u32 s4, s64, 0x10000
	s_addc_u32 s5, s65, 0
	s_andn2_b32 s0, 1, s33
	s_lshl_b32 s0, s0, 2
	s_add_i32 s6, s0, 0
	s_add_i32 s6, s6, 0x20040
	s_movk_i32 s0, 0x20f
	s_waitcnt lgkmcnt(0)
	s_add_u32 s0, s68, 0xc000
	s_addc_u32 s1, s69, 0
	v_lshl_add_u64 v[192:193], s[0:1], 0, v[186:187]
	v_lshl_add_u64 v[200:201], s[0:1], 0, v[188:189]
	s_mov_b64 s[72:73], 0
	s_mov_b32 s7, -2
	s_mov_b64 s[46:47], 0
	s_branch .LBB0_920

; #define PG8_STAGE(bufoff, gbase, voff) do { _Pragma("unroll") for (int _i = 0; _i < 2; ++_i) \
;         __builtin_amdgcn_global_load_lds((const unsigned*)((const char*)(gbase) + (voff)[_i]), (LAS unsigned*)(lds + (bufoff) + ldsw + _i * 8192), 16, 0, 0); } while (0)
; #define PG8_LDA(dst, b, h) do { _Pragma("unroll") for (int m = 0; m < 4; ++m) _Pragma("unroll") for (int k = 0; k < 2; ++k) dst[m][k] = *(const LAS bf16x8*)(lds + PG8_SA(b, h) + aoff + m * 2048 + k * 1024); } while (0)
; #define PG8_LDB(dst, b, h) do { _Pragma("unroll") for (int n = 0; n < 2; ++n) _Pragma("unroll") for (int k = 0; k < 2; ++k) dst[n][k] = *(const LAS bf16x8*)(lds + PG8_SB(b, h) + boff + n * 2048 + k * 1024); } while (0)
; #define PG8_MMA(ai, bj, At, Bt) do { __builtin_amdgcn_s_setprio(1); _Pragma("unroll") for (int m = 0; m < 4; ++m) _Pragma("unroll") for (int n = 0; n < 2; ++n) _Pragma("unroll") for (int k = 0; k < 2; ++k) \
;         acc[ai][bj][m][n] = __builtin_amdgcn_mfma_f32_16x16x32_bf16(Bt[n][k], At[m][k], acc[ai][bj][m][n], 0, 0, 0); __builtin_amdgcn_s_setprio(0); } while (0)
; #define PG8_WAIT_L(n) asm volatile("s_waitcnt lgkmcnt(" #n ")" ::: "memory")
; #define PG8_BAR __builtin_amdgcn_s_barrier()
; #define PG8_SCHED __builtin_amdgcn_sched_barrier(0)
; template <class Epi, bool DYN = false>
; __device__ __forceinline__ void gemm_phase(LAS unsigned char* lds, const Gemm g, const Epi& E, int wave, unsigned* ctr = nullptr) {
;     ...
;             const char* a1 = cA + (size_t)(t + 1) * kstepA;
;             const char* a2 = last ? nA : cA + (size_t)(t + 2) * kstepA; const char* b2 = last ? nB : cB + (size_t)(t + 2) * kstepB;
;             const char* a3 = a2 + kstepA; const char* b3 = b2 + kstepB;
;             PG8_LDB(B0, 0, 0); PG8_SCHED; PG8_LDA(At, 0, 0); PG8_STAGE(PG8_SA(1, 1), a1 + hstepA, voffA);
;             PG8_WAIT_L(8); PG8_BAR; PG8_WAIT_L(0); PG8_MMA(0, 0, At, B0); PG8_BAR; PG8_SCHED;
;             PG8_LDB(B1, 0, 1); PG8_STAGE(PG8_SB(0, 0), b2, voffB);
;             PG8_BAR; PG8_WAIT_L(0); PG8_MMA(0, 1, At, B1); PG8_BAR;
;             PG8_LDA(At, 0, 1); PG8_STAGE(PG8_SA(0, 0), a2, voffA);
;             PG8_BAR; PG8_WAIT_L(0); PG8_MMA(1, 0, At, B0); PG8_BAR; PG8_SCHED;
.LBB0_924:
	s_add_i32 s7, s7, 2
	s_add_u32 s0, s68, s46
	s_addc_u32 s1, s69, s47
	s_add_u32 s8, s0, 0x10000
	s_addc_u32 s9, s1, 0
	s_and_b64 s[0:1], s[74:75], exec
	s_cselect_b32 s77, s71, s9
	s_cselect_b32 s76, s70, s8
	s_add_u32 s8, s4, s46
	s_addc_u32 s9, s5, s47
	s_add_u32 s38, s76, 0x8000
	s_addc_u32 s39, s77, 0
	s_add_i32 s10, 0, 0x10000
	v_add_u32_e32 v0, s10, v214
	ds_read_b128 v[130:133], v0
	ds_read_b128 v[134:137], v0 offset:1024
	ds_read_b128 v[138:141], v0 offset:2048
	ds_read_b128 v[142:145], v0 offset:3072
	s_and_b64 s[0:1], s[74:75], exec
	s_cselect_b32 s75, s65, s9
	s_cselect_b32 s74, s64, s8
	v_lshl_add_u64 v[196:197], v[200:201], 0, s[46:47]
	s_add_i32 m0, s19, 0xc000
	ds_read_b128 v[146:149], v215
	ds_read_b128 v[150:153], v215 offset:1024
	ds_read_b128 v[154:157], v215 offset:2048
	ds_read_b128 v[158:161], v215 offset:3072
	ds_read_b128 v[162:165], v215 offset:4096
	ds_read_b128 v[166:169], v215 offset:5120
	ds_read_b128 v[170:173], v215 offset:6144
	ds_read_b128 v[174:177], v215 offset:7168
	global_load_lds_dwordx4 v[196:197], off
	v_lshl_add_u64 v[196:197], v[192:193], 0, s[46:47]
	s_add_i32 m0, s19, 0xe000
	s_nop 0
	global_load_lds_dwordx4 v[196:197], off
	s_waitcnt lgkmcnt(8)
	s_barrier
	s_waitcnt lgkmcnt(0)
	s_setprio 1
	s_waitcnt lgkmcnt(0)
	v_mfma_f32_16x16x32_bf16 v[2:5], v[130:133], v[146:149], v[2:5]
	v_mfma_f32_16x16x32_bf16 v[30:33], v[138:141], v[146:149], v[30:33]
	v_mfma_f32_16x16x32_bf16 v[26:29], v[130:133], v[154:157], v[26:29]
	v_mfma_f32_16x16x32_bf16 v[22:25], v[138:141], v[154:157], v[22:25]
	v_mfma_f32_16x16x32_bf16 v[18:21], v[130:133], v[162:165], v[18:21]
	v_mfma_f32_16x16x32_bf16 v[14:17], v[138:141], v[162:165], v[14:17]
	v_mfma_f32_16x16x32_bf16 v[10:13], v[130:133], v[170:173], v[10:13]
	v_mfma_f32_16x16x32_bf16 v[6:9], v[138:141], v[170:173], v[6:9]
	v_mfma_f32_16x16x32_bf16 v[2:5], v[134:137], v[150:153], v[2:5]
	v_mfma_f32_16x16x32_bf16 v[30:33], v[142:145], v[150:153], v[30:33]
	v_mfma_f32_16x16x32_bf16 v[26:29], v[134:137], v[158:161], v[26:29]
	v_mfma_f32_16x16x32_bf16 v[22:25], v[142:145], v[158:161], v[22:25]
	v_mfma_f32_16x16x32_bf16 v[18:21], v[134:137], v[166:169], v[18:21]
	v_mfma_f32_16x16x32_bf16 v[14:17], v[142:145], v[166:169], v[14:17]
	v_mfma_f32_16x16x32_bf16 v[10:13], v[134:137], v[174:177], v[10:13]
	v_mfma_f32_16x16x32_bf16 v[6:9], v[142:145], v[174:177], v[6:9]
	s_setprio 0
	s_barrier
	s_add_i32 s8, 0, 0x14000
	s_add_i32 s0, s10, s17
	v_add_u32_e32 v0, s8, v214
	v_lshl_add_u64 v[220:221], s[74:75], 0, v[180:181]
	s_mov_b32 m0, s0
	ds_read_b128 v[216:219], v0
	ds_read_b128 v[244:247], v0 offset:1024
	ds_read_b128 v[232:235], v0 offset:2048
	ds_read_b128 v[196:199], v0 offset:3072
	global_load_lds_dwordx4 v[220:221], off
	v_lshl_add_u64 v[220:221], s[74:75], 0, v[184:185]
	s_add_i32 m0, s0, 0x2000
	s_nop 0
	global_load_lds_dwordx4 v[220:221], off
	s_barrier
	s_waitcnt lgkmcnt(0)
	s_setprio 1
	s_waitcnt lgkmcnt(0)
	v_mfma_f32_16x16x32_bf16 v[94:97], v[216:219], v[146:149], v[94:97]
	v_mfma_f32_16x16x32_bf16 v[90:93], v[232:235], v[146:149], v[90:93]
	v_mfma_f32_16x16x32_bf16 v[86:89], v[216:219], v[154:157], v[86:89]
	v_mfma_f32_16x16x32_bf16 v[82:85], v[232:235], v[154:157], v[82:85]
	v_mfma_f32_16x16x32_bf16 v[78:81], v[216:219], v[162:165], v[78:81]
	v_mfma_f32_16x16x32_bf16 v[74:77], v[232:235], v[162:165], v[74:77]
	v_mfma_f32_16x16x32_bf16 v[70:73], v[216:219], v[170:173], v[70:73]
	v_mfma_f32_16x16x32_bf16 v[66:69], v[232:235], v[170:173], v[66:69]
	v_mfma_f32_16x16x32_bf16 v[94:97], v[244:247], v[150:153], v[94:97]
	v_mfma_f32_16x16x32_bf16 v[90:93], v[196:199], v[150:153], v[90:93]
	v_mfma_f32_16x16x32_bf16 v[86:89], v[244:247], v[158:161], v[86:89]
	v_mfma_f32_16x16x32_bf16 v[82:85], v[196:199], v[158:161], v[82:85]
	v_mfma_f32_16x16x32_bf16 v[78:81], v[244:247], v[166:169], v[78:81]
	v_mfma_f32_16x16x32_bf16 v[74:77], v[196:199], v[166:169], v[74:77]
	v_mfma_f32_16x16x32_bf16 v[70:73], v[244:247], v[174:177], v[70:73]
	v_mfma_f32_16x16x32_bf16 v[66:69], v[196:199], v[174:177], v[66:69]
	s_setprio 0
	s_mov_b32 m0, s19
	v_lshl_add_u64 v[220:221], s[76:77], 0, v[178:179]
	s_barrier
	ds_read_b128 v[146:149], v215 offset:16384
	ds_read_b128 v[150:153], v215 offset:17408
	ds_read_b128 v[154:157], v215 offset:18432
	ds_read_b128 v[158:161], v215 offset:19456
	ds_read_b128 v[162:165], v215 offset:20480
	ds_read_b128 v[166:169], v215 offset:21504
	ds_read_b128 v[170:173], v215 offset:22528
	ds_read_b128 v[174:177], v215 offset:23552
	global_load_lds_dwordx4 v[220:221], off
	v_lshl_add_u64 v[220:221], s[76:77], 0, v[182:183]
	s_mov_b32 m0, s23
	s_nop 0
	global_load_lds_dwordx4 v[220:221], off
	s_barrier
	s_waitcnt lgkmcnt(0)
	s_setprio 1
	s_waitcnt lgkmcnt(0)
	v_mfma_f32_16x16x32_bf16 v[62:65], v[130:133], v[146:149], v[62:65]
	v_mfma_f32_16x16x32_bf16 v[58:61], v[138:141], v[146:149], v[58:61]
	v_mfma_f32_16x16x32_bf16 v[54:57], v[130:133], v[154:157], v[54:57]
	v_mfma_f32_16x16x32_bf16 v[50:53], v[138:141], v[154:157], v[50:53]
	v_mfma_f32_16x16x32_bf16 v[46:49], v[130:133], v[162:165], v[46:49]
	v_mfma_f32_16x16x32_bf16 v[42:45], v[138:141], v[162:165], v[42:45]
	v_mfma_f32_16x16x32_bf16 v[38:41], v[130:133], v[170:173], v[38:41]
	v_mfma_f32_16x16x32_bf16 v[34:37], v[138:141], v[170:173], v[34:37]
	v_mfma_f32_16x16x32_bf16 v[62:65], v[134:137], v[150:153], v[62:65]
	v_mfma_f32_16x16x32_bf16 v[58:61], v[142:145], v[150:153], v[58:61]
	v_mfma_f32_16x16x32_bf16 v[54:57], v[134:137], v[158:161], v[54:57]
	v_mfma_f32_16x16x32_bf16 v[50:53], v[142:145], v[158:161], v[50:53]
	v_mfma_f32_16x16x32_bf16 v[46:49], v[134:137], v[166:169], v[46:49]
	v_mfma_f32_16x16x32_bf16 v[42:45], v[142:145], v[166:169], v[42:45]
	v_mfma_f32_16x16x32_bf16 v[38:41], v[134:137], v[174:177], v[38:41]
	v_mfma_f32_16x16x32_bf16 v[34:37], v[142:145], v[174:177], v[34:37]
	s_setprio 0
	s_barrier
; #define PG8_STAGE(bufoff, gbase, voff) do { _Pragma("unroll") for (int _i = 0; _i < 2; ++_i) \
;         __builtin_amdgcn_global_load_lds((const unsigned*)((const char*)(gbase) + (voff)[_i]), (LAS unsigned*)(lds + (bufoff) + ldsw + _i * 8192), 16, 0, 0); } while (0)
; #define PG8_LDA(dst, b, h) do { _Pragma("unroll") for (int m = 0; m < 4; ++m) _Pragma("unroll") for (int k = 0; k < 2; ++k) dst[m][k] = *(const LAS bf16x8*)(lds + PG8_SA(b, h) + aoff + m * 2048 + k * 1024); } while (0)
; #define PG8_LDB(dst, b, h) do { _Pragma("unroll") for (int n = 0; n < 2; ++n) _Pragma("unroll") for (int k = 0; k < 2; ++k) dst[n][k] = *(const LAS bf16x8*)(lds + PG8_SB(b, h) + boff + n * 2048 + k * 1024); } while (0)
; #define PG8_MMA(ai, bj, At, Bt) do { __builtin_amdgcn_s_setprio(1); _Pragma("unroll") for (int m = 0; m < 4; ++m) _Pragma("unroll") for (int n = 0; n < 2; ++n) _Pragma("unroll") for (int k = 0; k < 2; ++k) \
;         acc[ai][bj][m][n] = __builtin_amdgcn_mfma_f32_16x16x32_bf16(Bt[n][k], At[m][k], acc[ai][bj][m][n], 0, 0, 0); __builtin_amdgcn_s_setprio(0); } while (0)
; #define PG8_WAIT_V(n) asm volatile("s_waitcnt vmcnt(" #n ")" ::: "memory")
; #define PG8_WAIT_L(n) asm volatile("s_waitcnt lgkmcnt(" #n ")" ::: "memory")
; #define PG8_BAR __builtin_amdgcn_s_barrier()
; #define PG8_SCHED __builtin_amdgcn_sched_barrier(0)
; template <class Epi, bool DYN = false>
; __device__ __forceinline__ void gemm_phase(LAS unsigned char* lds, const Gemm g, const Epi& E, int wave, unsigned* ctr = nullptr) {
;     ...
;             PG8_STAGE(PG8_SB(0, 1), b2 + hstepB, voffB);
;             PG8_WAIT_V(6); PG8_BAR; PG8_MMA(1, 1, At, B1); PG8_BAR;
;             PG8_LDB(B0, 1, 0); PG8_SCHED; PG8_LDA(At, 1, 0); PG8_STAGE(PG8_SA(0, 1), a2 + hstepA, voffA);
;             PG8_WAIT_L(8); PG8_BAR; PG8_WAIT_L(0); PG8_MMA(0, 0, At, B0); PG8_BAR; PG8_SCHED;
;             PG8_LDB(B1, 1, 1); PG8_STAGE(PG8_SB(1, 0), b3, voffB);
;             PG8_BAR; PG8_WAIT_L(0); PG8_MMA(0, 1, At, B1); PG8_BAR;
;             PG8_LDA(At, 1, 1); PG8_STAGE(PG8_SA(1, 0), a3, voffA);
	s_add_u32 s0, s74, 0x4000
	s_addc_u32 s1, s75, 0
	s_add_i32 s8, s8, s17
	v_lshl_add_u64 v[130:131], s[0:1], 0, v[180:181]
	s_mov_b32 m0, s8
	s_nop 0
	global_load_lds_dwordx4 v[130:131], off
	v_lshl_add_u64 v[130:131], s[0:1], 0, v[184:185]
	s_add_i32 m0, s8, 0x2000
	s_nop 0
	global_load_lds_dwordx4 v[130:131], off
	s_waitcnt vmcnt(6)
	s_barrier
	s_setprio 1
	v_mfma_f32_16x16x32_bf16 v[126:129], v[216:219], v[146:149], v[126:129]
	v_mfma_f32_16x16x32_bf16 v[122:125], v[232:235], v[146:149], v[122:125]
	v_mfma_f32_16x16x32_bf16 v[118:121], v[216:219], v[154:157], v[118:121]
	v_mfma_f32_16x16x32_bf16 v[114:117], v[232:235], v[154:157], v[114:117]
	v_mfma_f32_16x16x32_bf16 v[110:113], v[216:219], v[162:165], v[110:113]
	v_mfma_f32_16x16x32_bf16 v[106:109], v[232:235], v[162:165], v[106:109]
	v_mfma_f32_16x16x32_bf16 v[102:105], v[216:219], v[170:173], v[102:105]
	v_mfma_f32_16x16x32_bf16 v[98:101], v[232:235], v[170:173], v[98:101]
	v_mfma_f32_16x16x32_bf16 v[126:129], v[244:247], v[150:153], v[126:129]
	v_mfma_f32_16x16x32_bf16 v[122:125], v[196:199], v[150:153], v[122:125]
	v_mfma_f32_16x16x32_bf16 v[118:121], v[244:247], v[158:161], v[118:121]
	v_mfma_f32_16x16x32_bf16 v[114:117], v[196:199], v[158:161], v[114:117]
	v_mfma_f32_16x16x32_bf16 v[110:113], v[244:247], v[166:169], v[110:113]
	v_mfma_f32_16x16x32_bf16 v[106:109], v[196:199], v[166:169], v[106:109]
	v_mfma_f32_16x16x32_bf16 v[102:105], v[244:247], v[174:177], v[102:105]
	v_mfma_f32_16x16x32_bf16 v[98:101], v[196:199], v[174:177], v[98:101]
	s_setprio 0
	s_add_i32 s8, 0, 0x18000
	v_add_u32_e32 v0, s8, v214
	s_barrier
	ds_read_b128 v[196:199], v0
	ds_read_b128 v[216:219], v0 offset:1024
	ds_read_b128 v[232:235], v0 offset:2048
	ds_read_b128 v[244:247], v0 offset:3072
	s_add_u32 s0, s76, 0x4000
	s_addc_u32 s1, s77, 0
	s_mov_b32 m0, s27
	v_lshl_add_u64 v[130:131], s[0:1], 0, v[178:179]
	ds_read_b128 v[146:149], v215 offset:32768
	ds_read_b128 v[150:153], v215 offset:33792
	ds_read_b128 v[154:157], v215 offset:34816
	ds_read_b128 v[158:161], v215 offset:35840
	ds_read_b128 v[162:165], v215 offset:36864
	ds_read_b128 v[166:169], v215 offset:37888
	ds_read_b128 v[170:173], v215 offset:38912
	ds_read_b128 v[174:177], v215 offset:39936
	global_load_lds_dwordx4 v[130:131], off
	v_lshl_add_u64 v[130:131], s[0:1], 0, v[182:183]
	s_mov_b32 m0, s15
	s_nop 0
	global_load_lds_dwordx4 v[130:131], off
	s_waitcnt lgkmcnt(8)
	s_barrier
	s_waitcnt lgkmcnt(0)
	s_setprio 1
	s_waitcnt lgkmcnt(0)
	v_mfma_f32_16x16x32_bf16 v[2:5], v[196:199], v[146:149], v[2:5]
	v_mfma_f32_16x16x32_bf16 v[30:33], v[232:235], v[146:149], v[30:33]
	v_mfma_f32_16x16x32_bf16 v[26:29], v[196:199], v[154:157], v[26:29]
	v_mfma_f32_16x16x32_bf16 v[22:25], v[232:235], v[154:157], v[22:25]
	v_mfma_f32_16x16x32_bf16 v[18:21], v[196:199], v[162:165], v[18:21]
	v_mfma_f32_16x16x32_bf16 v[14:17], v[232:235], v[162:165], v[14:17]
	v_mfma_f32_16x16x32_bf16 v[10:13], v[196:199], v[170:173], v[10:13]
	v_mfma_f32_16x16x32_bf16 v[6:9], v[232:235], v[170:173], v[6:9]
	v_mfma_f32_16x16x32_bf16 v[2:5], v[216:219], v[150:153], v[2:5]
	v_mfma_f32_16x16x32_bf16 v[30:33], v[244:247], v[150:153], v[30:33]
	v_mfma_f32_16x16x32_bf16 v[26:29], v[216:219], v[158:161], v[26:29]
	v_mfma_f32_16x16x32_bf16 v[22:25], v[244:247], v[158:161], v[22:25]
	v_mfma_f32_16x16x32_bf16 v[18:21], v[216:219], v[166:169], v[18:21]
	v_mfma_f32_16x16x32_bf16 v[14:17], v[244:247], v[166:169], v[14:17]
	v_mfma_f32_16x16x32_bf16 v[10:13], v[216:219], v[174:177], v[10:13]
	v_mfma_f32_16x16x32_bf16 v[6:9], v[244:247], v[174:177], v[6:9]
	s_setprio 0
	s_barrier
	s_add_u32 s0, s74, 0x8000
	v_add_u32_e32 v0, 0, v214
	s_addc_u32 s1, s75, 0
	s_add_i32 s8, s8, s17
	v_add_u32_e32 v0, 0x1c000, v0
	v_lshl_add_u64 v[220:221], s[0:1], 0, v[180:181]
	s_mov_b32 m0, s8
	ds_read_b128 v[130:133], v0
	ds_read_b128 v[134:137], v0 offset:1024
	ds_read_b128 v[138:141], v0 offset:2048
	ds_read_b128 v[142:145], v0 offset:3072
	global_load_lds_dwordx4 v[220:221], off
	v_lshl_add_u64 v[220:221], s[0:1], 0, v[184:185]
	s_add_i32 m0, s8, 0x2000
	s_nop 0
	global_load_lds_dwordx4 v[220:221], off
	s_barrier
	s_waitcnt lgkmcnt(0)
	s_setprio 1
	s_waitcnt lgkmcnt(0)
	v_mfma_f32_16x16x32_bf16 v[94:97], v[130:133], v[146:149], v[94:97]
	v_mfma_f32_16x16x32_bf16 v[90:93], v[138:141], v[146:149], v[90:93]
	v_mfma_f32_16x16x32_bf16 v[86:89], v[130:133], v[154:157], v[86:89]
	v_mfma_f32_16x16x32_bf16 v[82:85], v[138:141], v[154:157], v[82:85]
	v_mfma_f32_16x16x32_bf16 v[78:81], v[130:133], v[162:165], v[78:81]
	v_mfma_f32_16x16x32_bf16 v[74:77], v[138:141], v[162:165], v[74:77]
	v_mfma_f32_16x16x32_bf16 v[70:73], v[130:133], v[170:173], v[70:73]
	v_mfma_f32_16x16x32_bf16 v[66:69], v[138:141], v[170:173], v[66:69]
	v_mfma_f32_16x16x32_bf16 v[94:97], v[134:137], v[150:153], v[94:97]
	v_mfma_f32_16x16x32_bf16 v[90:93], v[142:145], v[150:153], v[90:93]
	v_mfma_f32_16x16x32_bf16 v[86:89], v[134:137], v[158:161], v[86:89]
	v_mfma_f32_16x16x32_bf16 v[82:85], v[142:145], v[158:161], v[82:85]
	v_mfma_f32_16x16x32_bf16 v[78:81], v[134:137], v[166:169], v[78:81]
	v_mfma_f32_16x16x32_bf16 v[74:77], v[142:145], v[166:169], v[74:77]
	v_mfma_f32_16x16x32_bf16 v[70:73], v[134:137], v[174:177], v[70:73]
	v_mfma_f32_16x16x32_bf16 v[66:69], v[142:145], v[174:177], v[66:69]
	s_setprio 0
	s_mov_b32 m0, s61
	v_lshl_add_u64 v[220:221], s[38:39], 0, v[178:179]
	s_barrier
	ds_read_b128 v[170:173], v215 offset:49152
	ds_read_b128 v[174:177], v215 offset:50176
	ds_read_b128 v[162:165], v215 offset:51200
	ds_read_b128 v[166:169], v215 offset:52224
	ds_read_b128 v[154:157], v215 offset:53248
	ds_read_b128 v[158:161], v215 offset:54272
	ds_read_b128 v[146:149], v215 offset:55296
	ds_read_b128 v[150:153], v215 offset:56320
	global_load_lds_dwordx4 v[220:221], off
	v_lshl_add_u64 v[220:221], s[38:39], 0, v[182:183]
	s_mov_b32 m0, s58
	s_nop 0
	global_load_lds_dwordx4 v[220:221], off
	s_barrier
; __device__ __forceinline__ f32x2 swiglu2(f32x2 a, f32x2 b, float rn, float r2) { const f32x2 q = rcp_2(exp2_2(a * rn) + 1.0f); return (a * b) * (q * r2); }
; __device__ __forceinline__ void gst16nt(void* p, u32x4 v) { __builtin_nontemporal_store(v, (GAS u32x4*)(unsigned long long)p); }
; template <class Epi, bool DYN = false>
; __device__ __forceinline__ void gemm_phase(LAS unsigned char* lds, const Gemm g, const Epi& E, int wave, unsigned* ctr = nullptr) {
;     ...
;     auto publish = [&](int si) { if (tid == 0) { int wg = -1;
;             if (ticket < rng_cnt(xcd)) wg = rng_start(xcd) + ticket;
;             else { for (int k = 1; k < 8; ++k) { const int x2 = (xcd + k) & 7; const int t2 = (int)__hip_atomic_fetch_add(ctr + x2 * 16, 1u, __ATOMIC_RELAXED, __HIP_MEMORY_SCOPE_AGENT); if (t2 < rng_cnt(x2)) { wg = rng_start(x2) + t2; break; } } }
;     __device__ __forceinline__ void prefetch(float (&pre)[8], const Unit& u, int wr, int fr) const {
; #pragma unroll
;         for (int i = 0; i < 8; ++i) pre[i] = rs[u.pm * BM + wr * 64 + fr + (i >> 2) * HALF + (i & 3) * 16]; }
;     __device__ __forceinline__ void operator()(AccRef acc, const Unit& u, int wr, int wc, int fr, int fq, const float (&pre)[8]) const {
;         const int row0 = u.pm * BM + wr * 64 + fr, col = u.pn * 128 + wc * 32 + 8 * fq;
; #pragma unroll
;         for (int ai = 0; ai < 2; ++ai)
; #pragma unroll
;             for (int m = 0; m < 4; ++m) {
;                 f32x4 v0, v1; const float r = pre[ai * 4 + m], rn = r * -1.4426950408889634f, r2 = r * r;
;                 { const f32x4 a0 = acc[ai][0][m][0], a1 = acc[ai][0][m][1], b0 = acc[ai][1][m][0], b1 = acc[ai][1][m][1];
;                   const f32x2 o0 = swiglu2((f32x2){a0[0], a0[1]}, (f32x2){b0[0], b0[1]}, rn, r2), o1 = swiglu2((f32x2){a0[2], a0[3]}, (f32x2){b0[2], b0[3]}, rn, r2);
;                   const f32x2 o2 = swiglu2((f32x2){a1[0], a1[1]}, (f32x2){b1[0], b1[1]}, rn, r2), o3 = swiglu2((f32x2){a1[2], a1[3]}, (f32x2){b1[2], b1[3]}, rn, r2);
;                   v0 = (f32x4){o0.x, o0.y, o1.x, o1.y}; v1 = (f32x4){o2.x, o2.y, o3.x, o3.y}; }
;                 { const int row = row0 + ai * HALF + m * 16;
;                   gst16nt(O + ((size_t)((row >> 8) * (DFF / 64) + (col >> 6)) * 256 + (row & 255)) * 64 + (col & 63), pack8(v0, v1)); }
	s_waitcnt lgkmcnt(0)
	s_setprio 1
	s_waitcnt lgkmcnt(0)
	v_mfma_f32_16x16x32_bf16 v[62:65], v[196:199], v[170:173], v[62:65]
	v_mfma_f32_16x16x32_bf16 v[58:61], v[232:235], v[170:173], v[58:61]
	v_mfma_f32_16x16x32_bf16 v[54:57], v[196:199], v[162:165], v[54:57]
	v_mfma_f32_16x16x32_bf16 v[50:53], v[232:235], v[162:165], v[50:53]
	v_mfma_f32_16x16x32_bf16 v[46:49], v[196:199], v[154:157], v[46:49]
	v_mfma_f32_16x16x32_bf16 v[42:45], v[232:235], v[154:157], v[42:45]
	v_mfma_f32_16x16x32_bf16 v[38:41], v[196:199], v[146:149], v[38:41]
	v_mfma_f32_16x16x32_bf16 v[34:37], v[232:235], v[146:149], v[34:37]
	v_mfma_f32_16x16x32_bf16 v[62:65], v[216:219], v[174:177], v[62:65]
	v_mfma_f32_16x16x32_bf16 v[58:61], v[244:247], v[174:177], v[58:61]
	v_mfma_f32_16x16x32_bf16 v[54:57], v[216:219], v[166:169], v[54:57]
	v_mfma_f32_16x16x32_bf16 v[50:53], v[244:247], v[166:169], v[50:53]
	v_mfma_f32_16x16x32_bf16 v[46:49], v[216:219], v[158:161], v[46:49]
	v_mfma_f32_16x16x32_bf16 v[42:45], v[244:247], v[158:161], v[42:45]
	v_mfma_f32_16x16x32_bf16 v[38:41], v[216:219], v[150:153], v[38:41]
	v_mfma_f32_16x16x32_bf16 v[34:37], v[244:247], v[150:153], v[34:37]
	s_setprio 0
	s_barrier
	v_or_b32_e32 v0, s7, v202
	v_cmp_eq_u32_e64 s[38:39], 0, v0
	s_and_saveexec_b64 s[76:77], s[38:39]
	s_cbranch_execz .LBB0_919
	v_cmp_lt_i32_e32 vcc, 0x20f, v203
	v_add_u32_e32 v0, s90, v203
	s_and_saveexec_b64 s[78:79], vcc
	s_cbranch_execz .LBB0_918
	v_mov_b64_e32 v[196:197], s[40:41]
	s_waitcnt vmcnt(0)
	flat_atomic_add v0, v[196:197], v224 sc0
	s_movk_i32 s0, 0x20f
	s_waitcnt vmcnt(0) lgkmcnt(0)
	v_cmp_lt_i32_e64 s[38:39], s0, v0
	v_add_u32_e32 v0, s63, v0
	s_and_saveexec_b64 s[0:1], s[38:39]
	s_cbranch_execz .LBB0_917
	v_mov_b64_e32 v[196:197], s[42:43]
	flat_atomic_add v0, v[196:197], v224 sc0
	s_movk_i32 s8, 0x20f
	s_waitcnt vmcnt(0) lgkmcnt(0)
	v_cmp_lt_i32_e64 s[38:39], s8, v0
	v_add_u32_e32 v0, s2, v0
	s_and_saveexec_b64 s[80:81], s[38:39]
	s_cbranch_execz .LBB0_916
	v_mov_b64_e32 v[196:197], s[44:45]
	flat_atomic_add v0, v[196:197], v224 sc0
	s_waitcnt vmcnt(0) lgkmcnt(0)
	v_cmp_lt_i32_e64 s[38:39], s8, v0
	v_add_u32_e32 v0, s3, v0
	s_and_saveexec_b64 s[82:83], s[38:39]
	s_cbranch_execz .LBB0_915
	v_mov_b64_e32 v[196:197], s[50:51]
	flat_atomic_add v0, v[196:197], v224 sc0
	s_waitcnt vmcnt(0) lgkmcnt(0)
	v_cmp_lt_i32_e64 s[38:39], s8, v0
	v_add_u32_e32 v0, s95, v0
	s_and_saveexec_b64 s[84:85], s[38:39]
	s_cbranch_execz .LBB0_914
	v_mov_b64_e32 v[196:197], s[54:55]
	flat_atomic_add v0, v[196:197], v224 sc0
	s_waitcnt vmcnt(0) lgkmcnt(0)
	v_cmp_lt_i32_e64 s[38:39], s8, v0
	v_add_u32_e32 v0, s28, v0
	s_and_saveexec_b64 s[86:87], s[38:39]
	s_cbranch_execz .LBB0_913
	v_readlane_b32 s8, v254, 54
	v_readlane_b32 s9, v254, 55
	s_nop 1
	v_mov_b64_e32 v[196:197], s[8:9]
	flat_atomic_add v0, v[196:197], v224 sc0
	s_movk_i32 s8, 0x20f
	s_waitcnt vmcnt(0) lgkmcnt(0)
	v_cmp_lt_i32_e64 s[38:39], s8, v0
	v_readlane_b32 s8, v254, 39
	s_nop 1
	v_add_u32_e32 v0, s8, v0
	s_and_saveexec_b64 s[88:89], s[38:39]
	s_cbranch_execz .LBB0_912
	v_readlane_b32 s8, v254, 56
	v_readlane_b32 s9, v254, 57
	s_nop 1
	v_mov_b64_e32 v[196:197], s[8:9]
	flat_atomic_add v0, v[196:197], v224 sc0
	v_readlane_b32 s8, v254, 43
	s_waitcnt vmcnt(0) lgkmcnt(0)
	v_cmp_gt_i32_e64 s[38:39], s91, v0
	v_add_u32_e32 v191, s8, v0
	s_nop 0
	v_cndmask_b32_e64 v0, -1, v191, s[38:39]
	s_branch .LBB0_912
.LBB0_933:
	v_mul_f32_e32 v0, 0xbfb8aa3b, v205
	v_pk_mul_f32 v[134:135], v[0:1], v[2:3] op_sel_hi:[0,1]
	v_exp_f32_e32 v134, v134
	v_exp_f32_e32 v135, v135
	v_mul_f32_e32 v130, v205, v205
	v_pk_mul_f32 v[138:139], v[2:3], v[94:95]
	v_pk_mul_f32 v[136:137], v[4:5], v[96:97]
	v_pk_add_f32 v[134:135], v[134:135], 1.0 op_sel_hi:[1,0]
	v_pk_mul_f32 v[142:143], v[30:31], v[90:91]
	v_rcp_f32_e32 v134, v134
	v_rcp_f32_e32 v135, v135
	s_add_u32 s74, s4, 0xffff0000
	s_addc_u32 s75, s5, -1
	s_lshl_b32 s0, s26, 8
	v_pk_mul_f32 v[134:135], v[130:131], v[134:135] op_sel_hi:[0,1]
	v_pk_mul_f32 v[134:135], v[134:135], v[138:139]
	v_pk_mul_f32 v[138:139], v[0:1], v[4:5] op_sel_hi:[0,1]
	v_exp_f32_e32 v138, v138
	v_exp_f32_e32 v139, v139
	s_add_i32 s1, s0, s18
	s_lshl_b32 s0, s22, 7
	v_or_b32_e32 v132, s1, v204
	v_pk_add_f32 v[138:139], v[138:139], 1.0 op_sel_hi:[1,0]
	s_or_b32 s0, s0, s60
	v_rcp_f32_e32 v138, v138
	v_rcp_f32_e32 v139, v139
	s_ashr_i32 s1, s1, 8
	s_ashr_i32 s0, s0, 6
	s_mulk_i32 s1, 0x58
	v_pk_mul_f32 v[138:139], v[130:131], v[138:139] op_sel_hi:[0,1]
	v_pk_mul_f32 v[136:137], v[138:139], v[136:137]
	v_pk_mul_f32 v[138:139], v[0:1], v[30:31] op_sel_hi:[0,1]
	v_exp_f32_e32 v138, v138
	v_exp_f32_e32 v139, v139
	s_add_i32 s4, s1, s0
	s_ashr_i32 s5, s4, 31
	s_lshl_b64 s[46:47], s[4:5], 15
	v_pk_add_f32 v[138:139], v[138:139], 1.0 op_sel_hi:[1,0]
	s_add_u32 s4, s24, s46
	v_rcp_f32_e32 v138, v138
	v_rcp_f32_e32 v139, v139
	v_pk_mul_f32 v[140:141], v[32:33], v[92:93]
	s_addc_u32 s5, s25, s47
	v_mov_b32_e32 v191, v1
	v_pk_mul_f32 v[138:139], v[130:131], v[138:139] op_sel_hi:[0,1]
	v_pk_mul_f32 v[138:139], v[138:139], v[142:143]
	v_pk_mul_f32 v[142:143], v[0:1], v[32:33] op_sel_hi:[0,1]
	v_exp_f32_e32 v142, v142
	v_exp_f32_e32 v143, v143
	v_lshlrev_b32_e32 v0, 7, v132
	v_and_b32_e32 v0, 0x6780, v0
	v_cvt_pk_bf16_f32 v134, v134, v135
	v_pk_add_f32 v[142:143], v[142:143], 1.0 op_sel_hi:[1,0]
	v_cvt_pk_bf16_f32 v135, v136, v137
	v_cvt_pk_bf16_f32 v136, v138, v139
	v_pk_mul_f32 v[138:139], v[28:29], v[88:89]
	v_rcp_f32_e32 v142, v142
	v_rcp_f32_e32 v143, v143
	v_pk_mul_f32 v[144:145], v[22:23], v[82:83]
	v_pk_mul_f32 v[130:131], v[130:131], v[142:143] op_sel_hi:[0,1]
	v_pk_mul_f32 v[140:141], v[130:131], v[140:141]
; __device__ __forceinline__ f32x2 swiglu2(f32x2 a, f32x2 b, float rn, float r2) { const f32x2 q = rcp_2(exp2_2(a * rn) + 1.0f); return (a * b) * (q * r2); }
; __device__ __forceinline__ void gst16nt(void* p, u32x4 v) { __builtin_nontemporal_store(v, (GAS u32x4*)(unsigned long long)p); }
; __device__ __forceinline__ u32x4 pack8(f32x4 v0, f32x4 v1) { u32x4 w; w.x = cvt_pk_bf16(v0[0], v0[1]); w.y = cvt_pk_bf16(v0[2], v0[3]); w.z = cvt_pk_bf16(v1[0], v1[1]); w.w = cvt_pk_bf16(v1[2], v1[3]); return w; }
;     __device__ __forceinline__ void operator()(AccRef acc, const Unit& u, int wr, int wc, int fr, int fq, const float (&pre)[8]) const {
;         const int row0 = u.pm * BM + wr * 64 + fr, col = u.pn * 128 + wc * 32 + 8 * fq;
; #pragma unroll
;         for (int ai = 0; ai < 2; ++ai)
; #pragma unroll
;             for (int m = 0; m < 4; ++m) {
;                 f32x4 v0, v1; const float r = pre[ai * 4 + m], rn = r * -1.4426950408889634f, r2 = r * r;
;                 { const f32x4 a0 = acc[ai][0][m][0], a1 = acc[ai][0][m][1], b0 = acc[ai][1][m][0], b1 = acc[ai][1][m][1];
;                   const f32x2 o0 = swiglu2((f32x2){a0[0], a0[1]}, (f32x2){b0[0], b0[1]}, rn, r2), o1 = swiglu2((f32x2){a0[2], a0[3]}, (f32x2){b0[2], b0[3]}, rn, r2);
;                   const f32x2 o2 = swiglu2((f32x2){a1[0], a1[1]}, (f32x2){b1[0], b1[1]}, rn, r2), o3 = swiglu2((f32x2){a1[2], a1[3]}, (f32x2){b1[2], b1[3]}, rn, r2);
;                   v0 = (f32x4){o0.x, o0.y, o1.x, o1.y}; v1 = (f32x4){o2.x, o2.y, o3.x, o3.y}; }
;                 { const int row = row0 + ai * HALF + m * 16;
;                   gst16nt(O + ((size_t)((row >> 8) * (DFF / 64) + (col >> 6)) * 256 + (row & 255)) * 64 + (col & 63), pack8(v0, v1)); }
	v_lshl_add_u64 v[130:131], s[4:5], 0, v[0:1]
	v_lshl_add_u64 v[130:131], v[130:131], 0, v[190:191]
	v_cvt_pk_bf16_f32 v137, v140, v141
	v_mul_f32_e32 v0, 0xbfb8aa3b, v206
	global_store_dwordx4 v[130:131], v[134:137], off nt
	v_pk_mul_f32 v[140:141], v[26:27], v[86:87]
	v_pk_mul_f32 v[142:143], v[24:25], v[84:85]
	v_pk_mul_f32 v[136:137], v[0:1], v[26:27] op_sel_hi:[0,1]
	v_exp_f32_e32 v136, v136
	v_exp_f32_e32 v137, v137
	v_mul_f32_e32 v134, v206, v206
	v_pk_add_f32 v[136:137], v[136:137], 1.0 op_sel_hi:[1,0]
	s_nop 0
	v_rcp_f32_e32 v136, v136
	v_rcp_f32_e32 v137, v137
	s_nop 0
	v_pk_mul_f32 v[136:137], v[134:135], v[136:137] op_sel_hi:[0,1]
	v_pk_mul_f32 v[136:137], v[136:137], v[140:141]
	v_pk_mul_f32 v[140:141], v[0:1], v[28:29] op_sel_hi:[0,1]
	v_exp_f32_e32 v140, v140
	v_exp_f32_e32 v141, v141
	s_nop 0
	v_pk_add_f32 v[140:141], v[140:141], 1.0 op_sel_hi:[1,0]
	s_nop 0
	v_rcp_f32_e32 v140, v140
	v_rcp_f32_e32 v141, v141
	s_nop 0
	v_pk_mul_f32 v[140:141], v[134:135], v[140:141] op_sel_hi:[0,1]
	v_pk_mul_f32 v[138:139], v[140:141], v[138:139]
	v_pk_mul_f32 v[140:141], v[0:1], v[22:23] op_sel_hi:[0,1]
	v_exp_f32_e32 v140, v140
	v_exp_f32_e32 v141, v141
	s_nop 0
	v_pk_add_f32 v[140:141], v[140:141], 1.0 op_sel_hi:[1,0]
	s_nop 0
	v_rcp_f32_e32 v140, v140
	v_rcp_f32_e32 v141, v141
	s_nop 0
	v_pk_mul_f32 v[140:141], v[134:135], v[140:141] op_sel_hi:[0,1]
	v_pk_mul_f32 v[140:141], v[140:141], v[144:145]
	v_pk_mul_f32 v[144:145], v[0:1], v[24:25] op_sel_hi:[0,1]
	v_exp_f32_e32 v144, v144
	v_exp_f32_e32 v145, v145
	v_mul_f32_e32 v0, 0xbfb8aa3b, v207
	v_pk_add_f32 v[144:145], v[144:145], 1.0 op_sel_hi:[1,0]
	s_nop 0
	v_rcp_f32_e32 v144, v144
	v_rcp_f32_e32 v145, v145
	s_nop 0
	v_pk_mul_f32 v[134:135], v[134:135], v[144:145] op_sel_hi:[0,1]
	v_pk_mul_f32 v[142:143], v[134:135], v[142:143]
	v_cvt_pk_bf16_f32 v134, v136, v137
	v_cvt_pk_bf16_f32 v136, v140, v141
	v_cvt_pk_bf16_f32 v135, v138, v139
	v_pk_mul_f32 v[140:141], v[18:19], v[78:79]
	v_cvt_pk_bf16_f32 v137, v142, v143
	global_store_dwordx4 v[130:131], v[134:137], off offset:2048 nt
	v_pk_mul_f32 v[138:139], v[20:21], v[80:81]
	v_pk_mul_f32 v[144:145], v[14:15], v[74:75]
	v_pk_mul_f32 v[136:137], v[0:1], v[18:19] op_sel_hi:[0,1]
	v_exp_f32_e32 v136, v136
	v_exp_f32_e32 v137, v137
	v_mul_f32_e32 v134, v207, v207
	v_pk_mul_f32 v[142:143], v[16:17], v[76:77]
	v_add_co_u32_e32 v130, vcc, s94, v130
	v_pk_add_f32 v[136:137], v[136:137], 1.0 op_sel_hi:[1,0]
	s_nop 0
	v_addc_co_u32_e32 v131, vcc, 0, v131, vcc
	v_rcp_f32_e32 v136, v136
	v_rcp_f32_e32 v137, v137
	s_nop 0
	v_pk_mul_f32 v[136:137], v[134:135], v[136:137] op_sel_hi:[0,1]
	v_pk_mul_f32 v[136:137], v[136:137], v[140:141]
	v_pk_mul_f32 v[140:141], v[0:1], v[20:21] op_sel_hi:[0,1]
	v_exp_f32_e32 v140, v140
	v_exp_f32_e32 v141, v141
	s_nop 0
	v_pk_add_f32 v[140:141], v[140:141], 1.0 op_sel_hi:[1,0]
	s_nop 0
	v_rcp_f32_e32 v140, v140
	v_rcp_f32_e32 v141, v141
	s_nop 0
	v_pk_mul_f32 v[140:141], v[134:135], v[140:141] op_sel_hi:[0,1]
	v_pk_mul_f32 v[138:139], v[140:141], v[138:139]
	v_pk_mul_f32 v[140:141], v[0:1], v[14:15] op_sel_hi:[0,1]
	v_exp_f32_e32 v140, v140
	v_exp_f32_e32 v141, v141
	s_nop 0
	v_pk_add_f32 v[140:141], v[140:141], 1.0 op_sel_hi:[1,0]
	s_nop 0
	v_rcp_f32_e32 v140, v140
	v_rcp_f32_e32 v141, v141
	s_nop 0
	v_pk_mul_f32 v[140:141], v[134:135], v[140:141] op_sel_hi:[0,1]
	v_pk_mul_f32 v[140:141], v[140:141], v[144:145]
	v_pk_mul_f32 v[144:145], v[0:1], v[16:17] op_sel_hi:[0,1]
	v_exp_f32_e32 v144, v144
	v_exp_f32_e32 v145, v145
	v_mul_f32_e32 v0, 0xbfb8aa3b, v208
	v_pk_add_f32 v[144:145], v[144:145], 1.0 op_sel_hi:[1,0]
	s_nop 0
	v_rcp_f32_e32 v144, v144
	v_rcp_f32_e32 v145, v145
	s_nop 0
	v_pk_mul_f32 v[134:135], v[134:135], v[144:145] op_sel_hi:[0,1]
	v_pk_mul_f32 v[142:143], v[134:135], v[142:143]
	v_cvt_pk_bf16_f32 v134, v136, v137
	v_cvt_pk_bf16_f32 v136, v140, v141
	v_cvt_pk_bf16_f32 v135, v138, v139
	v_pk_mul_f32 v[140:141], v[10:11], v[70:71]
	v_cvt_pk_bf16_f32 v137, v142, v143
	global_store_dwordx4 v[130:131], v[134:137], off nt
	v_pk_mul_f32 v[138:139], v[12:13], v[72:73]
	v_pk_mul_f32 v[144:145], v[6:7], v[66:67]
	v_pk_mul_f32 v[136:137], v[0:1], v[10:11] op_sel_hi:[0,1]
	v_exp_f32_e32 v136, v136
	v_exp_f32_e32 v137, v137
	v_mul_f32_e32 v134, v208, v208
	v_pk_mul_f32 v[142:143], v[8:9], v[68:69]
	v_pk_add_f32 v[136:137], v[136:137], 1.0 op_sel_hi:[1,0]
	s_nop 0
	v_rcp_f32_e32 v136, v136
	v_rcp_f32_e32 v137, v137
	s_nop 0
	v_pk_mul_f32 v[136:137], v[134:135], v[136:137] op_sel_hi:[0,1]
	v_pk_mul_f32 v[136:137], v[136:137], v[140:141]
	v_pk_mul_f32 v[140:141], v[0:1], v[12:13] op_sel_hi:[0,1]
	v_exp_f32_e32 v140, v140
	v_exp_f32_e32 v141, v141
	s_nop 0
	v_pk_add_f32 v[140:141], v[140:141], 1.0 op_sel_hi:[1,0]
	s_nop 0
	v_rcp_f32_e32 v140, v140
	v_rcp_f32_e32 v141, v141
	s_nop 0
	v_pk_mul_f32 v[140:141], v[134:135], v[140:141] op_sel_hi:[0,1]
	v_pk_mul_f32 v[138:139], v[140:141], v[138:139]
	v_pk_mul_f32 v[140:141], v[0:1], v[6:7] op_sel_hi:[0,1]
	v_exp_f32_e32 v140, v140
	v_exp_f32_e32 v141, v141
	s_nop 0
	v_pk_add_f32 v[140:141], v[140:141], 1.0 op_sel_hi:[1,0]
	s_nop 0
	v_rcp_f32_e32 v140, v140
	v_rcp_f32_e32 v141, v141
	s_nop 0
	v_pk_mul_f32 v[140:141], v[134:135], v[140:141] op_sel_hi:[0,1]
	v_pk_mul_f32 v[140:141], v[140:141], v[144:145]
	v_pk_mul_f32 v[144:145], v[0:1], v[8:9] op_sel_hi:[0,1]
	v_exp_f32_e32 v144, v144
	v_exp_f32_e32 v145, v145
	s_nop 0
	v_pk_add_f32 v[144:145], v[144:145], 1.0 op_sel_hi:[1,0]
	s_nop 0
	v_rcp_f32_e32 v144, v144
	v_rcp_f32_e32 v145, v145
	s_nop 0
	v_pk_mul_f32 v[134:135], v[134:135], v[144:145] op_sel_hi:[0,1]
	v_add_u32_e32 v144, 0x80, v132
	v_pk_mul_f32 v[142:143], v[134:135], v[142:143]
; __device__ __forceinline__ f32x2 swiglu2(f32x2 a, f32x2 b, float rn, float r2) { const f32x2 q = rcp_2(exp2_2(a * rn) + 1.0f); return (a * b) * (q * r2); }
; __device__ __forceinline__ void gst16nt(void* p, u32x4 v) { __builtin_nontemporal_store(v, (GAS u32x4*)(unsigned long long)p); }
; __device__ __forceinline__ u32x4 pack8(f32x4 v0, f32x4 v1) { u32x4 w; w.x = cvt_pk_bf16(v0[0], v0[1]); w.y = cvt_pk_bf16(v0[2], v0[3]); w.z = cvt_pk_bf16(v1[0], v1[1]); w.w = cvt_pk_bf16(v1[2], v1[3]); return w; }
;     __device__ __forceinline__ void operator()(AccRef acc, const Unit& u, int wr, int wc, int fr, int fq, const float (&pre)[8]) const {
;         const int row0 = u.pm * BM + wr * 64 + fr, col = u.pn * 128 + wc * 32 + 8 * fq;
; #pragma unroll
;         for (int ai = 0; ai < 2; ++ai)
; #pragma unroll
;             for (int m = 0; m < 4; ++m) {
;                 f32x4 v0, v1; const float r = pre[ai * 4 + m], rn = r * -1.4426950408889634f, r2 = r * r;
;                 { const f32x4 a0 = acc[ai][0][m][0], a1 = acc[ai][0][m][1], b0 = acc[ai][1][m][0], b1 = acc[ai][1][m][1];
;                   const f32x2 o0 = swiglu2((f32x2){a0[0], a0[1]}, (f32x2){b0[0], b0[1]}, rn, r2), o1 = swiglu2((f32x2){a0[2], a0[3]}, (f32x2){b0[2], b0[3]}, rn, r2);
;                   const f32x2 o2 = swiglu2((f32x2){a1[0], a1[1]}, (f32x2){b1[0], b1[1]}, rn, r2), o3 = swiglu2((f32x2){a1[2], a1[3]}, (f32x2){b1[2], b1[3]}, rn, r2);
;                   v0 = (f32x4){o0.x, o0.y, o1.x, o1.y}; v1 = (f32x4){o2.x, o2.y, o3.x, o3.y}; }
;                 { const int row = row0 + ai * HALF + m * 16;
;                   gst16nt(O + ((size_t)((row >> 8) * (DFF / 64) + (col >> 6)) * 256 + (row & 255)) * 64 + (col & 63), pack8(v0, v1)); }
	v_cvt_pk_bf16_f32 v134, v136, v137
	v_cvt_pk_bf16_f32 v135, v138, v139
	v_cvt_pk_bf16_f32 v136, v140, v141
	v_lshrrev_b32_e32 v0, 8, v144
	v_cvt_pk_bf16_f32 v137, v142, v143
	global_store_dwordx4 v[130:131], v[134:137], off offset:2048 nt
	v_mov_b32_e32 v130, s0
	s_movk_i32 s0, 0x58
	v_mad_i32_i24 v130, v0, s0, v130
	v_mul_f32_e32 v0, 0xbfb8aa3b, v209
	v_pk_mul_f32 v[134:135], v[0:1], v[62:63] op_sel_hi:[0,1]
	v_exp_f32_e32 v134, v134
	v_exp_f32_e32 v135, v135
	v_mul_f32_e32 v132, v209, v209
	v_pk_mul_f32 v[138:139], v[62:63], v[126:127]
	v_pk_mul_f32 v[136:137], v[64:65], v[128:129]
	v_pk_add_f32 v[134:135], v[134:135], 1.0 op_sel_hi:[1,0]
	v_pk_mul_f32 v[142:143], v[58:59], v[122:123]
	v_rcp_f32_e32 v134, v134
	v_rcp_f32_e32 v135, v135
	v_ashrrev_i32_e32 v131, 31, v130
	v_lshlrev_b64 v[130:131], 15, v[130:131]
	v_lshl_add_u64 v[130:131], s[24:25], 0, v[130:131]
	v_pk_mul_f32 v[134:135], v[132:133], v[134:135] op_sel_hi:[0,1]
	v_pk_mul_f32 v[134:135], v[134:135], v[138:139]
	v_pk_mul_f32 v[138:139], v[0:1], v[64:65] op_sel_hi:[0,1]
	v_exp_f32_e32 v138, v138
	v_exp_f32_e32 v139, v139
	v_pk_mul_f32 v[140:141], v[60:61], v[124:125]
	v_pk_add_f32 v[138:139], v[138:139], 1.0 op_sel_hi:[1,0]
	s_nop 0
	v_rcp_f32_e32 v138, v138
	v_rcp_f32_e32 v139, v139
	s_nop 0
	v_pk_mul_f32 v[138:139], v[132:133], v[138:139] op_sel_hi:[0,1]
	v_pk_mul_f32 v[136:137], v[138:139], v[136:137]
	v_pk_mul_f32 v[138:139], v[0:1], v[58:59] op_sel_hi:[0,1]
	v_exp_f32_e32 v138, v138
	v_exp_f32_e32 v139, v139
	s_nop 0
	v_pk_add_f32 v[138:139], v[138:139], 1.0 op_sel_hi:[1,0]
	s_nop 0
	v_rcp_f32_e32 v138, v138
	v_rcp_f32_e32 v139, v139
	s_nop 0
	v_pk_mul_f32 v[138:139], v[132:133], v[138:139] op_sel_hi:[0,1]
	v_pk_mul_f32 v[138:139], v[138:139], v[142:143]
	v_pk_mul_f32 v[142:143], v[0:1], v[60:61] op_sel_hi:[0,1]
	v_exp_f32_e32 v142, v142
	v_exp_f32_e32 v143, v143
	v_lshlrev_b32_e32 v0, 7, v144
	v_and_b32_e32 v0, 0x6780, v0
	v_lshl_add_u64 v[130:131], v[130:131], 0, v[0:1]
	v_pk_add_f32 v[142:143], v[142:143], 1.0 op_sel_hi:[1,0]
	v_lshl_add_u64 v[130:131], v[130:131], 0, v[190:191]
	v_rcp_f32_e32 v142, v142
	v_rcp_f32_e32 v143, v143
	v_mul_f32_e32 v0, 0xbfb8aa3b, v210
	v_pk_mul_f32 v[132:133], v[132:133], v[142:143] op_sel_hi:[0,1]
	v_pk_mul_f32 v[140:141], v[132:133], v[140:141]
	v_cvt_pk_bf16_f32 v132, v134, v135
	v_cvt_pk_bf16_f32 v134, v138, v139
	v_cvt_pk_bf16_f32 v133, v136, v137
	v_pk_mul_f32 v[138:139], v[54:55], v[118:119]
	v_cvt_pk_bf16_f32 v135, v140, v141
	global_store_dwordx4 v[130:131], v[132:135], off nt
	v_pk_mul_f32 v[136:137], v[56:57], v[120:121]
	v_pk_mul_f32 v[142:143], v[50:51], v[114:115]
	v_pk_mul_f32 v[134:135], v[0:1], v[54:55] op_sel_hi:[0,1]
	v_exp_f32_e32 v134, v134
	v_exp_f32_e32 v135, v135
	v_mul_f32_e32 v132, v210, v210
	v_pk_mul_f32 v[140:141], v[52:53], v[116:117]
	v_pk_add_f32 v[134:135], v[134:135], 1.0 op_sel_hi:[1,0]
	s_nop 0
	v_rcp_f32_e32 v134, v134
	v_rcp_f32_e32 v135, v135
	s_nop 0
	v_pk_mul_f32 v[134:135], v[132:133], v[134:135] op_sel_hi:[0,1]
	v_pk_mul_f32 v[134:135], v[134:135], v[138:139]
	v_pk_mul_f32 v[138:139], v[0:1], v[56:57] op_sel_hi:[0,1]
	v_exp_f32_e32 v138, v138
	v_exp_f32_e32 v139, v139
	s_nop 0
	v_pk_add_f32 v[138:139], v[138:139], 1.0 op_sel_hi:[1,0]
	s_nop 0
	v_rcp_f32_e32 v138, v138
	v_rcp_f32_e32 v139, v139
	s_nop 0
	v_pk_mul_f32 v[138:139], v[132:133], v[138:139] op_sel_hi:[0,1]
	v_pk_mul_f32 v[136:137], v[138:139], v[136:137]
	v_pk_mul_f32 v[138:139], v[0:1], v[50:51] op_sel_hi:[0,1]
	v_exp_f32_e32 v138, v138
	v_exp_f32_e32 v139, v139
	s_nop 0
	v_pk_add_f32 v[138:139], v[138:139], 1.0 op_sel_hi:[1,0]
	s_nop 0
	v_rcp_f32_e32 v138, v138
	v_rcp_f32_e32 v139, v139
	s_nop 0
	v_pk_mul_f32 v[138:139], v[132:133], v[138:139] op_sel_hi:[0,1]
	v_pk_mul_f32 v[138:139], v[138:139], v[142:143]
	v_pk_mul_f32 v[142:143], v[0:1], v[52:53] op_sel_hi:[0,1]
	v_exp_f32_e32 v142, v142
	v_exp_f32_e32 v143, v143
	v_mul_f32_e32 v0, 0xbfb8aa3b, v211
	v_pk_add_f32 v[142:143], v[142:143], 1.0 op_sel_hi:[1,0]
	s_nop 0
	v_rcp_f32_e32 v142, v142
	v_rcp_f32_e32 v143, v143
	s_nop 0
	v_pk_mul_f32 v[132:133], v[132:133], v[142:143] op_sel_hi:[0,1]
	v_pk_mul_f32 v[140:141], v[132:133], v[140:141]
	v_cvt_pk_bf16_f32 v132, v134, v135
; __device__ __forceinline__ f32x2 swiglu2(f32x2 a, f32x2 b, float rn, float r2) { const f32x2 q = rcp_2(exp2_2(a * rn) + 1.0f); return (a * b) * (q * r2); }
; __device__ __forceinline__ void gst16nt(void* p, u32x4 v) { __builtin_nontemporal_store(v, (GAS u32x4*)(unsigned long long)p); }
; __device__ __forceinline__ u32x4 pack8(f32x4 v0, f32x4 v1) { u32x4 w; w.x = cvt_pk_bf16(v0[0], v0[1]); w.y = cvt_pk_bf16(v0[2], v0[3]); w.z = cvt_pk_bf16(v1[0], v1[1]); w.w = cvt_pk_bf16(v1[2], v1[3]); return w; }
; template <class Epi, bool DYN = false>
; __device__ __forceinline__ void gemm_phase(LAS unsigned char* lds, const Gemm g, const Epi& E, int wave, unsigned* ctr = nullptr) {
;     ...
;         if (!has_next) break;
; #pragma unroll
;         for (int a = 0; a < 2; ++a)
; #pragma unroll
;             for (int b = 0; b < 2; ++b)
; #pragma unroll
;                 for (int m = 0; m < 4; ++m)
; #pragma unroll
;                     for (int n = 0; n < 2; ++n) acc[a][b][m][n] = (f32x4){0.f, 0.f, 0.f, 0.f};
;         cur = nxt; cA = nA; cB = nB; ++ui;
;         if (DYN) issue();
;     __device__ __forceinline__ void operator()(AccRef acc, const Unit& u, int wr, int wc, int fr, int fq, const float (&pre)[8]) const {
;         const int row0 = u.pm * BM + wr * 64 + fr, col = u.pn * 128 + wc * 32 + 8 * fq;
; #pragma unroll
;         for (int ai = 0; ai < 2; ++ai)
; #pragma unroll
;             for (int m = 0; m < 4; ++m) {
;                 f32x4 v0, v1; const float r = pre[ai * 4 + m], rn = r * -1.4426950408889634f, r2 = r * r;
;                 { const f32x4 a0 = acc[ai][0][m][0], a1 = acc[ai][0][m][1], b0 = acc[ai][1][m][0], b1 = acc[ai][1][m][1];
;                   const f32x2 o0 = swiglu2((f32x2){a0[0], a0[1]}, (f32x2){b0[0], b0[1]}, rn, r2), o1 = swiglu2((f32x2){a0[2], a0[3]}, (f32x2){b0[2], b0[3]}, rn, r2);
;                   const f32x2 o2 = swiglu2((f32x2){a1[0], a1[1]}, (f32x2){b1[0], b1[1]}, rn, r2), o3 = swiglu2((f32x2){a1[2], a1[3]}, (f32x2){b1[2], b1[3]}, rn, r2);
;                   v0 = (f32x4){o0.x, o0.y, o1.x, o1.y}; v1 = (f32x4){o2.x, o2.y, o3.x, o3.y}; }
;                 { const int row = row0 + ai * HALF + m * 16;
;                   gst16nt(O + ((size_t)((row >> 8) * (DFF / 64) + (col >> 6)) * 256 + (row & 255)) * 64 + (col & 63), pack8(v0, v1)); }
	v_cvt_pk_bf16_f32 v134, v138, v139
	v_cvt_pk_bf16_f32 v133, v136, v137
	v_pk_mul_f32 v[138:139], v[46:47], v[110:111]
	v_cvt_pk_bf16_f32 v135, v140, v141
	global_store_dwordx4 v[130:131], v[132:135], off offset:2048 nt
	v_pk_mul_f32 v[136:137], v[48:49], v[112:113]
	v_pk_mul_f32 v[142:143], v[42:43], v[106:107]
	v_pk_mul_f32 v[134:135], v[0:1], v[46:47] op_sel_hi:[0,1]
	v_exp_f32_e32 v134, v134
	v_exp_f32_e32 v135, v135
	v_mul_f32_e32 v132, v211, v211
	v_pk_mul_f32 v[140:141], v[44:45], v[108:109]
	v_pk_add_f32 v[134:135], v[134:135], 1.0 op_sel_hi:[1,0]
	s_nop 0
	v_rcp_f32_e32 v134, v134
	v_rcp_f32_e32 v135, v135
	s_nop 0
	v_pk_mul_f32 v[134:135], v[132:133], v[134:135] op_sel_hi:[0,1]
	v_pk_mul_f32 v[134:135], v[134:135], v[138:139]
	v_pk_mul_f32 v[138:139], v[0:1], v[48:49] op_sel_hi:[0,1]
	v_exp_f32_e32 v138, v138
	v_exp_f32_e32 v139, v139
	s_nop 0
	v_pk_add_f32 v[138:139], v[138:139], 1.0 op_sel_hi:[1,0]
	s_nop 0
	v_rcp_f32_e32 v138, v138
	v_rcp_f32_e32 v139, v139
	s_nop 0
	v_pk_mul_f32 v[138:139], v[132:133], v[138:139] op_sel_hi:[0,1]
	v_pk_mul_f32 v[136:137], v[138:139], v[136:137]
	v_pk_mul_f32 v[138:139], v[0:1], v[42:43] op_sel_hi:[0,1]
	v_exp_f32_e32 v138, v138
	v_exp_f32_e32 v139, v139
	s_nop 0
	v_pk_add_f32 v[138:139], v[138:139], 1.0 op_sel_hi:[1,0]
	s_nop 0
	v_rcp_f32_e32 v138, v138
	v_rcp_f32_e32 v139, v139
	s_nop 0
	v_pk_mul_f32 v[138:139], v[132:133], v[138:139] op_sel_hi:[0,1]
	v_pk_mul_f32 v[138:139], v[138:139], v[142:143]
	v_pk_mul_f32 v[142:143], v[0:1], v[44:45] op_sel_hi:[0,1]
	v_exp_f32_e32 v142, v142
	v_exp_f32_e32 v143, v143
	v_mul_f32_e32 v0, 0xbfb8aa3b, v212
	v_pk_add_f32 v[142:143], v[142:143], 1.0 op_sel_hi:[1,0]
	s_nop 0
	v_rcp_f32_e32 v142, v142
	v_rcp_f32_e32 v143, v143
	s_nop 0
	v_pk_mul_f32 v[132:133], v[132:133], v[142:143] op_sel_hi:[0,1]
	v_pk_mul_f32 v[140:141], v[132:133], v[140:141]
	v_cvt_pk_bf16_f32 v133, v136, v137
	v_add_co_u32_e32 v136, vcc, s94, v130
	v_cvt_pk_bf16_f32 v132, v134, v135
	v_cvt_pk_bf16_f32 v134, v138, v139
	v_cvt_pk_bf16_f32 v135, v140, v141
	v_mul_f32_e32 v130, v212, v212
	s_nop 0
	v_addc_co_u32_e32 v137, vcc, 0, v131, vcc
	global_store_dwordx4 v[136:137], v[132:135], off nt
	v_pk_mul_f32 v[138:139], v[38:39], v[102:103]
	v_pk_mul_f32 v[142:143], v[34:35], v[98:99]
	v_pk_mul_f32 v[132:133], v[0:1], v[38:39] op_sel_hi:[0,1]
	v_exp_f32_e32 v132, v132
	v_exp_f32_e32 v133, v133
	v_pk_mul_f32 v[134:135], v[40:41], v[104:105]
	v_pk_mul_f32 v[140:141], v[36:37], v[100:101]
	s_andn2_b64 vcc, exec, s[72:73]
	v_pk_add_f32 v[132:133], v[132:133], 1.0 op_sel_hi:[1,0]
	s_nop 0
	v_rcp_f32_e32 v132, v132
	v_rcp_f32_e32 v133, v133
	s_nop 0
	v_pk_mul_f32 v[132:133], v[130:131], v[132:133] op_sel_hi:[0,1]
	v_pk_mul_f32 v[132:133], v[132:133], v[138:139]
	v_pk_mul_f32 v[138:139], v[0:1], v[40:41] op_sel_hi:[0,1]
	v_exp_f32_e32 v138, v138
	v_exp_f32_e32 v139, v139
	s_nop 0
	v_pk_add_f32 v[138:139], v[138:139], 1.0 op_sel_hi:[1,0]
	s_nop 0
	v_rcp_f32_e32 v138, v138
	v_rcp_f32_e32 v139, v139
	s_nop 0
	v_pk_mul_f32 v[138:139], v[130:131], v[138:139] op_sel_hi:[0,1]
	v_pk_mul_f32 v[134:135], v[138:139], v[134:135]
	v_pk_mul_f32 v[138:139], v[0:1], v[34:35] op_sel_hi:[0,1]
	v_exp_f32_e32 v138, v138
	v_exp_f32_e32 v139, v139
	s_nop 0
	v_pk_add_f32 v[138:139], v[138:139], 1.0 op_sel_hi:[1,0]
	s_nop 0
	v_rcp_f32_e32 v138, v138
	v_rcp_f32_e32 v139, v139
	s_nop 0
	v_pk_mul_f32 v[138:139], v[130:131], v[138:139] op_sel_hi:[0,1]
	v_pk_mul_f32 v[138:139], v[138:139], v[142:143]
	v_pk_mul_f32 v[142:143], v[0:1], v[36:37] op_sel_hi:[0,1]
	v_exp_f32_e32 v142, v142
	v_exp_f32_e32 v143, v143
	s_nop 0
	v_pk_add_f32 v[142:143], v[142:143], 1.0 op_sel_hi:[1,0]
	s_nop 0
	v_rcp_f32_e32 v142, v142
	v_rcp_f32_e32 v143, v143
	s_nop 0
	v_pk_mul_f32 v[130:131], v[130:131], v[142:143] op_sel_hi:[0,1]
	v_pk_mul_f32 v[140:141], v[130:131], v[140:141]
	v_cvt_pk_bf16_f32 v130, v132, v133
	v_cvt_pk_bf16_f32 v131, v134, v135
	v_cvt_pk_bf16_f32 v132, v138, v139
	s_nop 0
	v_cvt_pk_bf16_f32 v133, v140, v141
	global_store_dwordx4 v[136:137], v[130:133], off offset:2048 nt
	s_cbranch_vccnz .LBB0_936
	s_and_saveexec_b64 s[0:1], s[36:37]
	s_cbranch_execz .LBB0_910
	v_mov_b64_e32 v[2:3], s[92:93]
	global_atomic_add v203, v[2:3], v224, off sc0
	s_branch .LBB0_910

; __device__ __forceinline__ bf16_t f2bf(float f) { return (bf16_t)(cvt_pk_bf16(f, 0.f) & 0xffffu); }
; __device__ __forceinline__ int ltid(int wave) { int t = (wave << 6) | (int)__builtin_amdgcn_mbcnt_hi(~0u, __builtin_amdgcn_mbcnt_lo(~0u, 0u)); asm volatile("" : "+v"(t)); return t; }
; __device__ __forceinline__ int lbid() { int b = blockIdx.x; asm volatile("" : "+s"(b)); return b; }
; __device__ __forceinline__ void cvt_tile(unsigned char* shm, int tid, const float* src, bf16_t* dst, int K, int N, int mode, const float* kscale, int ldd, int t) {
;     bf16_t* T = (bf16_t*)shm;
;     const int nnt = N / 256, nti = t % nnt, kt = t / nnt;
;     { const int k = tid >> 3, n8 = (tid & 7) * 8;
;       const float* s = src + (size_t)(kt * 64 + k) * N + nti * 256 + n8; const float ks = kscale ? kscale[kt * 64 + k] : 1.0f;
;       f32x4 v[8];
; #pragma unroll
;       for (int q = 0; q < 4; ++q) { v[2 * q] = *(const f32x4*)(s + q * 64); v[2 * q + 1] = *(const f32x4*)(s + q * 64 + 4); }
;       asm volatile("" ::: "memory");
; #pragma unroll
;       for (int q = 0; q < 4; ++q)
; #pragma unroll
;           for (int j = 0; j < 4; ++j) { T[(q * 64 + n8 + j) * 72 + k] = f2bf(v[2 * q][j] * ks); T[(q * 64 + n8 + 4 + j) * 72 + k] = f2bf(v[2 * q + 1][j] * ks); } }
;     __syncthreads();
; #pragma unroll
;     for (int q = 0; q < 4; ++q) { const int n = q * 64 + (tid >> 3), k8 = (tid & 7) * 8; const int nn = nti * 256 + n;
;       const int drow = mode == 0 ? nn : ((nn >> 7) * 256 + (nn & 127) + (mode == 2 ? 128 : 0));
;       *(u32x4*)(dst + ((size_t)((drow >> 8) * (K / 64) + kt) * 256 + (drow & 255)) * 64 + k8) = *(const u32x4*)(T + n * 72 + k8); }
; __device__ void cvt_set(const Params& p, unsigned char* shm, bf16_t* W, int l, int sub  , unsigned* ctr) {
;     const int tid = ltid(p.wave), total = sub == 1 ? CVT_MIXER_TILES : CVT_FFN_TILES;
;     volatile int* tk = (volatile int*)(shm + 131072 + 128);
;     if (ctr == nullptr) {
;         for (int t = lbid(); t < total; t += gridDim.x) { if (sub == 1) cvt_mixer_tile(p, shm, tid, W, l, t); else cvt_ffn_tile(p, shm, tid, W, l, sub == 2 ? 1 : 0, t); }
;         return;
;     }
;     for (;;) {
;         if (tid == 0) *tk = (int)__hip_atomic_fetch_add(ctr, 1u, __ATOMIC_RELAXED, __HIP_MEMORY_SCOPE_AGENT);
;         __syncthreads();
;         const int t = __builtin_amdgcn_readfirstlane(*tk);
.LBB0_940:
	v_readlane_b32 s0, v251, 12
	v_readlane_b32 s6, v251, 18
	v_readlane_b32 s1, v251, 13
	s_cmp_lt_i32 s6, 15
	s_cselect_b64 s[0:1], -1, 0
	s_cmp_gt_i32 s6, 14
	v_readlane_b32 s2, v251, 14
	v_readlane_b32 s3, v251, 15
	s_cselect_b64 s[24:25], -1, 0
	s_and_b64 s[2:3], s[24:25], exec
	s_cselect_b32 s2, -14, 0
	s_cselect_b32 s3, 3, 0
	s_add_i32 s2, s2, s6
	v_readlane_b32 s4, v251, 16
	s_cmp_eq_u32 s2, 1
	s_cselect_b32 s4, 0, 2
	v_readlane_b32 s5, v251, 17
	s_add_i32 s4, s4, s3
	s_andn2_b32 s3, 1, s3
	s_mul_i32 s3, s3, 0x5000000
	v_readlane_b32 s5, v252, 27
	s_add_u32 s26, s5, s3
	v_readlane_b32 s3, v252, 28
	s_addc_u32 s27, s3, 0
	s_lshl_b32 s3, s4, 6
	v_readlane_b32 s4, v252, 33
	s_add_u32 s22, s4, s3
	v_readlane_b32 s3, v252, 34
	s_addc_u32 s23, s3, 0
	s_cmp_lg_u32 s2, 1
	s_mov_b64 s[36:37], -1
	s_waitcnt vmcnt(0) lgkmcnt(0)
	s_barrier
	v_readlane_b32 s7, v251, 19
	s_cbranch_scc0 .LBB0_965
	v_readlane_b32 s6, v252, 35
	v_readlane_b32 s8, v252, 41
	s_andn2_b64 vcc, exec, s[0:1]
	v_readlane_b32 s7, v252, 36
	v_readlane_b32 s9, v252, 42
	s_cbranch_vccnz .LBB0_964
	v_mov_b32_e32 v0, v194
	s_add_u32 s0, s26, 0x2d60000
	v_cmp_eq_u32_e64 s[36:37], 0, v0
	v_ashrrev_i32_e32 v3, 3, v0
	v_lshlrev_b32_e32 v0, 3, v0
	v_and_b32_e32 v2, 56, v0
	v_mul_u32_u24_e32 v4, 0x48, v2
	v_lshlrev_b32_e32 v0, 1, v3
	v_lshlrev_b32_e32 v26, 1, v2
	v_xor_b32_e32 v0, v0, v26
	v_lshlrev_b32_e32 v4, 1, v4
	v_add_u32_e32 v30, 64, v3
	v_add_u32_e32 v31, 0x80, v3
	v_add_u32_e32 v32, 0xc0, v3
	v_add3_u32 v26, 0, v0, v4
	v_add_u32_e32 v4, 0, v4
	v_lshlrev_b32_e32 v12, 7, v3
	v_lshlrev_b32_e32 v14, 7, v30
	v_lshlrev_b32_e32 v8, 7, v31
	v_lshlrev_b32_e32 v16, 7, v32
	s_addc_u32 s1, s27, 0
	v_add_u32_e32 v27, v4, v0
	s_movk_i32 s2, 0xff72
	v_and_b32_e32 v0, 0x7f80, v12
	v_and_b32_e32 v6, 0x7f80, v14
	v_mov_b32_e32 v7, v1
	v_and_b32_e32 v8, 0x7f80, v8
	v_mov_b32_e32 v9, v1
	v_and_b32_e32 v10, 0x7f80, v16
	v_mov_b32_e32 v11, v1
	v_and_b32_e32 v12, 0x3f80, v12
	v_mov_b32_e32 v13, v1
	v_and_b32_e32 v14, 0x3f80, v14
	v_mov_b32_e32 v15, v1
	v_and_b32_e32 v16, 0x3f80, v16
	v_mov_b32_e32 v17, v1
	v_mad_i32_i24 v28, v2, s2, v4
	v_lshlrev_b32_e32 v33, 1, v3
	v_and_b32_e32 v33, 0x70, v33
	v_xor_b32_e32 v28, v28, v33
	s_movk_i32 s2, 0x90
	v_lshl_add_u64 v[4:5], s[0:1], 0, v[0:1]
	v_lshlrev_b32_e32 v0, 1, v2
	v_lshl_add_u64 v[6:7], s[0:1], 0, v[6:7]
	v_lshl_add_u64 v[8:9], s[0:1], 0, v[8:9]
	v_lshl_add_u64 v[10:11], s[0:1], 0, v[10:11]
	v_lshl_add_u64 v[12:13], s[26:27], 0, v[12:13]
	v_lshl_add_u64 v[14:15], s[26:27], 0, v[14:15]
	v_lshl_add_u64 v[16:17], s[26:27], 0, v[16:17]
	v_mul_lo_u32 v29, v3, s2
	v_lshl_add_u64 v[4:5], v[4:5], 0, v[0:1]
	v_lshl_add_u64 v[6:7], v[6:7], 0, v[0:1]
	v_lshl_add_u64 v[8:9], v[8:9], 0, v[0:1]
	v_lshl_add_u64 v[10:11], v[10:11], 0, v[0:1]
	v_lshl_add_u64 v[18:19], v[12:13], 0, v[0:1]
	v_lshl_add_u64 v[20:21], v[14:15], 0, v[0:1]
	v_lshl_add_u64 v[22:23], v[16:17], 0, v[0:1]
	s_and_saveexec_b64 s[0:1], s[36:37]
	global_atomic_add v100, v1, v224, s[22:23] sc0
	s_or_b64 exec, exec, s[0:1]
	s_waitcnt vmcnt(0)
	s_branch .LBB0_947

; __device__ __forceinline__ bf16_t f2bf(float f) { return (bf16_t)(cvt_pk_bf16(f, 0.f) & 0xffffu); }
; __device__ __forceinline__ void cvt_tile(unsigned char* shm, int tid, const float* src, bf16_t* dst, int K, int N, int mode, const float* kscale, int ldd, int t) {
;     bf16_t* T = (bf16_t*)shm;
;     const int nnt = N / 256, nti = t % nnt, kt = t / nnt;
;     { const int k = tid >> 3, n8 = (tid & 7) * 8;
;       const float* s = src + (size_t)(kt * 64 + k) * N + nti * 256 + n8; const float ks = kscale ? kscale[kt * 64 + k] : 1.0f;
;       f32x4 v[8];
; #pragma unroll
;       for (int q = 0; q < 4; ++q) { v[2 * q] = *(const f32x4*)(s + q * 64); v[2 * q + 1] = *(const f32x4*)(s + q * 64 + 4); }
;       asm volatile("" ::: "memory");
; #pragma unroll
;       for (int q = 0; q < 4; ++q)
; #pragma unroll
;           for (int j = 0; j < 4; ++j) { T[(q * 64 + n8 + j) * 72 + k] = f2bf(v[2 * q][j] * ks); T[(q * 64 + n8 + 4 + j) * 72 + k] = f2bf(v[2 * q + 1][j] * ks); } }
;     __syncthreads();
; #pragma unroll
;     for (int q = 0; q < 4; ++q) { const int n = q * 64 + (tid >> 3), k8 = (tid & 7) * 8; const int nn = nti * 256 + n;
;       const int drow = mode == 0 ? nn : ((nn >> 7) * 256 + (nn & 127) + (mode == 2 ? 128 : 0));
;       *(u32x4*)(dst + ((size_t)((drow >> 8) * (K / 64) + kt) * 256 + (drow & 255)) * 64 + k8) = *(const u32x4*)(T + n * 72 + k8); }
;     __syncthreads();
; __device__ void cvt_set(const Params& p, unsigned char* shm, bf16_t* W, int l, int sub  , unsigned* ctr) {
;     ...
;     for (;;) {
;         if (tid == 0) *tk = (int)__hip_atomic_fetch_add(ctr, 1u, __ATOMIC_RELAXED, __HIP_MEMORY_SCOPE_AGENT);
;         __syncthreads();
;         const int t = __builtin_amdgcn_readfirstlane(*tk);
;         __syncthreads();
;         if (t >= total) break;
;         if (sub == 1) cvt_mixer_tile(p, shm, tid, W, l, t); else cvt_ffn_tile(p, shm, tid, W, l, sub == 2 ? 1 : 0, t);
.LBB0_950:
	s_or_b64 exec, exec, s[38:39]
	s_mov_b64 s[2:3], src_shared_base
	s_waitcnt vmcnt(4)
	v_readfirstlane_b32 s2, v100
	s_nop 1
	v_add_u32_e32 v0, s2, v0
	s_add_i32 s2, 0, 0x20080
	s_cmp_lg_u32 s2, -1
	s_cselect_b32 s2, s2, 0
	s_cselect_b32 s3, s3, 0
	v_mov_b32_e32 v24, s2
	v_mov_b32_e32 v25, s3
	ds_write_b32 v24, v0
	global_atomic_add v100, v1, v224, s[22:23] sc0
.LBB0_951:
	s_or_b64 exec, exec, s[0:1]
	s_mov_b64 s[0:1], src_shared_base
	s_add_i32 s0, 0, 0x20080
	s_cmp_lg_u32 s0, -1
	s_cselect_b32 s0, s0, 0
	s_cselect_b32 s1, s1, 0
	v_mov_b32_e32 v24, s0
	v_mov_b32_e32 v25, s1
	s_waitcnt lgkmcnt(0)
	s_barrier
	ds_read_b32 v0, v24
	s_mov_b64 s[0:1], -1
	s_waitcnt lgkmcnt(0)
	s_barrier
	v_readfirstlane_b32 s2, v0
	s_cmpk_gt_i32 s2, 0x83f
	s_cbranch_scc1 .LBB0_946
	s_cmpk_gt_i32 s2, 0x2bf
	s_cbranch_scc0 .LBB0_961
	s_cmpk_gt_u32 s2, 0x57f
	s_cbranch_scc0 .LBB0_955
	s_add_i32 s0, s2, 0xfa80
	s_bfe_u32 s1, s0, 0xd0003
	v_lshl_add_u32 v24, s1, 6, v3
	v_ashrrev_i32_e32 v25, 31, v24
	v_readlane_b32 s4, v252, 37
	s_lshl_b32 s0, s2, 8
	v_lshlrev_b64 v[24:25], 13, v[24:25]
	v_readlane_b32 s5, v252, 38
	s_and_b32 s0, s0, 0x700
	s_lshl_b32 s48, s0, 2
	v_lshl_add_u64 v[24:25], s[4:5], 0, v[24:25]
	v_lshl_add_u64 v[24:25], v[24:25], 0, s[48:49]
	v_lshlrev_b32_e32 v0, 2, v2
	v_lshl_add_u64 v[24:25], v[24:25], 0, v[0:1]
	global_load_dwordx4 v[34:37], v[24:25], off offset:16
	global_load_dwordx4 v[38:41], v[24:25], off
	global_load_dwordx4 v[42:45], v[24:25], off offset:272
	global_load_dwordx4 v[46:49], v[24:25], off offset:256
	global_load_dwordx4 v[50:53], v[24:25], off offset:528
	global_load_dwordx4 v[54:57], v[24:25], off offset:512
	global_load_dwordx4 v[58:61], v[24:25], off offset:784
	global_load_dwordx4 v[62:65], v[24:25], off offset:768
	v_add_u32_e32 v33, v28, v29
	s_waitcnt vmcnt(6)
	v_cvt_pk_bf16_f32 v0, v38, v1
	ds_write_b16 v26, v0
	v_cvt_pk_bf16_f32 v0, v34, v1
	ds_write_b16 v27, v0 offset:576
	v_cvt_pk_bf16_f32 v0, v39, v1
	ds_write_b16 v26, v0 offset:144
	v_cvt_pk_bf16_f32 v0, v35, v1
	ds_write_b16 v27, v0 offset:720
	v_cvt_pk_bf16_f32 v0, v40, v1
	ds_write_b16 v26, v0 offset:288
	v_cvt_pk_bf16_f32 v0, v36, v1
	ds_write_b16 v27, v0 offset:864
	v_cvt_pk_bf16_f32 v0, v41, v1
	ds_write_b16 v26, v0 offset:432
	v_cvt_pk_bf16_f32 v0, v37, v1
	ds_write_b16 v27, v0 offset:1008
	s_waitcnt vmcnt(4)
	v_cvt_pk_bf16_f32 v0, v46, v1
	ds_write_b16 v26, v0 offset:9216
	v_cvt_pk_bf16_f32 v0, v42, v1
	ds_write_b16 v27, v0 offset:9792
	v_cvt_pk_bf16_f32 v0, v47, v1
	ds_write_b16 v26, v0 offset:9360
	v_cvt_pk_bf16_f32 v0, v43, v1
	ds_write_b16 v27, v0 offset:9936
	v_cvt_pk_bf16_f32 v0, v48, v1
	ds_write_b16 v26, v0 offset:9504
	v_cvt_pk_bf16_f32 v0, v44, v1
	ds_write_b16 v27, v0 offset:10080
	v_cvt_pk_bf16_f32 v0, v49, v1
	ds_write_b16 v26, v0 offset:9648
	v_cvt_pk_bf16_f32 v0, v45, v1
	ds_write_b16 v27, v0 offset:10224
	s_waitcnt vmcnt(2)
	v_cvt_pk_bf16_f32 v0, v54, v1
	ds_write_b16 v26, v0 offset:18432
	v_cvt_pk_bf16_f32 v0, v50, v1
	ds_write_b16 v27, v0 offset:19008
	v_cvt_pk_bf16_f32 v0, v55, v1
	ds_write_b16 v26, v0 offset:18576
	v_cvt_pk_bf16_f32 v0, v51, v1
	ds_write_b16 v27, v0 offset:19152
	v_cvt_pk_bf16_f32 v0, v56, v1
	ds_write_b16 v26, v0 offset:18720
	v_cvt_pk_bf16_f32 v0, v52, v1
	ds_write_b16 v27, v0 offset:19296
	v_cvt_pk_bf16_f32 v0, v57, v1
	ds_write_b16 v26, v0 offset:18864
	v_cvt_pk_bf16_f32 v0, v53, v1
	ds_write_b16 v27, v0 offset:19440
	s_waitcnt vmcnt(0)
	v_cvt_pk_bf16_f32 v0, v62, v1
	ds_write_b16 v26, v0 offset:27648
	v_cvt_pk_bf16_f32 v0, v58, v1
	ds_write_b16 v27, v0 offset:28224
	v_cvt_pk_bf16_f32 v0, v63, v1
	ds_write_b16 v26, v0 offset:27792
	v_cvt_pk_bf16_f32 v0, v59, v1
	ds_write_b16 v27, v0 offset:28368
	v_cvt_pk_bf16_f32 v0, v64, v1
	ds_write_b16 v26, v0 offset:27936
	v_cvt_pk_bf16_f32 v0, v60, v1
	ds_write_b16 v27, v0 offset:28512
	v_cvt_pk_bf16_f32 v0, v65, v1
	ds_write_b16 v26, v0 offset:28080
	v_cvt_pk_bf16_f32 v0, v61, v1
	ds_write_b16 v27, v0 offset:28656
	v_add_u32_e32 v0, s0, v3
	s_waitcnt lgkmcnt(0)
	s_barrier
	ds_read_b128 v[34:37], v33
	v_lshrrev_b32_e32 v0, 8, v0
	v_mov_b32_e32 v38, s1
	s_movk_i32 s1, 0x58
	v_mad_i32_i24 v24, v0, s1, v38
	v_ashrrev_i32_e32 v25, 31, v24
	v_lshlrev_b64 v[24:25], 15, v[24:25]
	v_lshl_add_u64 v[24:25], v[4:5], 0, v[24:25]
	v_add_u32_e32 v0, s0, v30
	s_waitcnt lgkmcnt(0)
	global_store_dwordx4 v[24:25], v[34:37], off
	ds_read_b128 v[34:37], v33 offset:9216
	v_lshrrev_b32_e32 v0, 8, v0
	v_mad_i32_i24 v24, v0, s1, v38
	v_ashrrev_i32_e32 v25, 31, v24
	v_lshlrev_b64 v[24:25], 15, v[24:25]
	v_lshl_add_u64 v[24:25], v[6:7], 0, v[24:25]
	v_add_u32_e32 v0, s0, v31
	s_waitcnt lgkmcnt(0)
	global_store_dwordx4 v[24:25], v[34:37], off
	ds_read_b128 v[34:37], v33 offset:18432
	v_lshrrev_b32_e32 v0, 8, v0
	v_mad_i32_i24 v24, v0, s1, v38
	v_ashrrev_i32_e32 v25, 31, v24
	v_lshlrev_b64 v[24:25], 15, v[24:25]
	v_lshl_add_u64 v[24:25], v[8:9], 0, v[24:25]
	v_add_u32_e32 v0, s0, v32
	s_waitcnt lgkmcnt(0)
	global_store_dwordx4 v[24:25], v[34:37], off
	ds_read_b128 v[34:37], v33 offset:27648
	v_lshrrev_b32_e32 v0, 8, v0
	v_mad_i32_i24 v24, v0, s1, v38
	v_ashrrev_i32_e32 v25, 31, v24
	v_lshlrev_b64 v[24:25], 15, v[24:25]
	v_lshl_add_u64 v[24:25], v[10:11], 0, v[24:25]
	s_waitcnt lgkmcnt(0)
	global_store_dwordx4 v[24:25], v[34:37], off
	s_barrier
	s_mov_b64 s[0:1], 0

; __device__ __forceinline__ void cvt_tile(unsigned char* shm, int tid, const float* src, bf16_t* dst, int K, int N, int mode, const float* kscale, int ldd, int t) {
;     bf16_t* T = (bf16_t*)shm;
;     const int nnt = N / 256, nti = t % nnt, kt = t / nnt;
;     { const int k = tid >> 3, n8 = (tid & 7) * 8;
;       const float* s = src + (size_t)(kt * 64 + k) * N + nti * 256 + n8; const float ks = kscale ? kscale[kt * 64 + k] : 1.0f;
;       f32x4 v[8];
; #pragma unroll
;       for (int q = 0; q < 4; ++q) { v[2 * q] = *(const f32x4*)(s + q * 64); v[2 * q + 1] = *(const f32x4*)(s + q * 64 + 4); }
;       asm volatile("" ::: "memory");
; #pragma unroll
;       for (int q = 0; q < 4; ++q)
; #pragma unroll
;           for (int j = 0; j < 4; ++j) { T[(q * 64 + n8 + j) * 72 + k] = f2bf(v[2 * q][j] * ks); T[(q * 64 + n8 + 4 + j) * 72 + k] = f2bf(v[2 * q + 1][j] * ks); } }
;     __syncthreads();
; #pragma unroll
;     for (int q = 0; q < 4; ++q) { const int n = q * 64 + (tid >> 3), k8 = (tid & 7) * 8; const int nn = nti * 256 + n;
;       const int drow = mode == 0 ? nn : ((nn >> 7) * 256 + (nn & 127) + (mode == 2 ? 128 : 0));
;       *(u32x4*)(dst + ((size_t)((drow >> 8) * (K / 64) + kt) * 256 + (drow & 255)) * 64 + k8) = *(const u32x4*)(T + n * 72 + k8); }
; __device__ __forceinline__ void cvt_mixer_tile(const Params& p, unsigned char* shm, int tid, bf16_t* W, int l, int t) {
;     if (t < 1728) cvt_tile(shm, tid, p.in[3] + (size_t)l * DM * 13824, W + W_IN, DM, 13824, 0, p.in[2] + (l * 6 + 2) * DM, LDX, t);
;     else if (t < 1792) cvt_tile(shm, tid, p.in[19] + (size_t)l * 1024 * 1024, W + W_GLU, 1024, 1024, 0, nullptr, 1024, t - 1728);
;     else if (t < 1920) cvt_tile(shm, tid, p.in[22] + (size_t)l * 1024 * DM, W + W_BRL, 1024, DM, 0, nullptr, 1024, t - 1792);
;     else if (t < 2048) cvt_tile(shm, tid, p.in[23] + (size_t)l * 1024 * DM, W + W_BRS, 1024, DM, 0, nullptr, 1024, t - 1920);
;     else if (t < 2112) cvt_tile(shm, tid, p.in[24] + (size_t)l * 512 * DM, W + W_BRA, 512, DM, 0, nullptr, 512, t - 2048);
;     else cvt_tile(shm, tid, p.in[25] + (size_t)l * DM * DM, W + W_OUT, DM, DM, 0, nullptr, DM, t - 2112);
; }
; __device__ void cvt_set(const Params& p, unsigned char* shm, bf16_t* W, int l, int sub  , unsigned* ctr) {
;     const int tid = ltid(p.wave), total = sub == 1 ? CVT_MIXER_TILES : CVT_FFN_TILES;
.LBB0_965:
	v_readlane_b32 s0, v254, 59
	s_mov_b32 s44, s0
	v_readlane_b32 s0, v254, 60
	s_mov_b32 s58, s0
	v_readlane_b32 s0, v254, 61
	s_mov_b32 s40, s0
	v_readlane_b32 s0, v254, 62
	s_mov_b32 s62, s0
	v_readlane_b32 s0, v254, 63
	s_andn2_b64 vcc, exec, s[36:37]
	s_mov_b32 s60, s0
	s_cbranch_vccnz .LBB0_994
	s_movk_i32 s0, 0xff72
	v_lshlrev_b32_e32 v0, 3, v194
	v_and_b32_e32 v2, 56, v0
	v_ashrrev_i32_e32 v3, 3, v194
	v_mul_u32_u24_e32 v4, 0x48, v2
	v_lshlrev_b32_e32 v0, 1, v3
	v_lshlrev_b32_e32 v52, 1, v2
	v_xor_b32_e32 v0, v0, v52
	v_lshlrev_b32_e32 v4, 1, v4
	v_add3_u32 v52, 0, v0, v4
	v_add_u32_e32 v4, 0, v4
	v_mad_i32_i24 v54, v2, s0, v4
	v_lshlrev_b32_e32 v59, 1, v3
	v_and_b32_e32 v59, 0x70, v59
	v_xor_b32_e32 v54, v54, v59
	s_movk_i32 s0, 0x90
	v_mul_lo_u32 v55, v3, s0
	v_add_u32_e32 v56, 64, v3
	v_add_u32_e32 v57, 0x80, v3
	v_add_u32_e32 v58, 0xc0, v3
	s_and_b64 s[0:1], s[24:25], exec
	v_add_u32_e32 v53, v4, v0
	s_cselect_b32 s2, 0x400000, 0
	s_add_u32 s0, s26, 0x43b0000
	v_lshlrev_b32_e32 v0, 7, v3
	v_lshlrev_b32_e32 v6, 7, v56
	v_lshlrev_b32_e32 v8, 7, v57
	v_lshlrev_b32_e32 v10, 7, v58
	s_addc_u32 s1, s27, 0
	v_and_b32_e32 v0, 0x7f80, v0
	v_and_b32_e32 v46, 0x7f80, v6
	v_mov_b32_e32 v47, v1
	v_and_b32_e32 v48, 0x7f80, v8
	v_mov_b32_e32 v49, v1
	v_and_b32_e32 v60, 0x7f80, v10
	v_mov_b32_e32 v61, v1
	v_lshl_add_u64 v[4:5], s[0:1], 0, v[0:1]
	v_lshl_add_u64 v[6:7], s[0:1], 0, v[46:47]
	v_lshl_add_u64 v[8:9], s[0:1], 0, v[48:49]
	v_lshl_add_u64 v[10:11], s[0:1], 0, v[60:61]
	s_add_u32 s0, s26, 0x41b0000
	s_addc_u32 s1, s27, 0
	v_lshl_add_u64 v[12:13], s[0:1], 0, v[0:1]
	v_lshl_add_u64 v[14:15], s[0:1], 0, v[46:47]
	v_lshl_add_u64 v[16:17], s[0:1], 0, v[48:49]
	v_lshl_add_u64 v[18:19], s[0:1], 0, v[60:61]
	s_and_b64 s[0:1], s[24:25], exec
	s_cselect_b32 s3, 0x800000, 0
	s_add_u32 s0, s26, 0x3db0000
	s_addc_u32 s1, s27, 0
	v_lshl_add_u64 v[20:21], s[0:1], 0, v[0:1]
	v_lshl_add_u64 v[22:23], s[0:1], 0, v[46:47]
	v_lshl_add_u64 v[24:25], s[0:1], 0, v[48:49]
	v_lshl_add_u64 v[26:27], s[0:1], 0, v[60:61]
	s_add_u32 s0, s26, 0x39b0000
	s_addc_u32 s1, s27, 0
	v_lshl_add_u64 v[28:29], s[0:1], 0, v[0:1]
	v_lshl_add_u64 v[30:31], s[0:1], 0, v[46:47]
	v_lshl_add_u64 v[32:33], s[0:1], 0, v[48:49]
	v_lshl_add_u64 v[34:35], s[0:1], 0, v[60:61]
	s_add_u32 s0, s26, 0x37b0000
	s_addc_u32 s1, s27, 0
	v_lshl_add_u64 v[36:37], s[0:1], 0, v[0:1]
	v_lshl_add_u64 v[38:39], s[0:1], 0, v[46:47]
	v_lshl_add_u64 v[40:41], s[0:1], 0, v[48:49]
	v_lshl_add_u64 v[42:43], s[0:1], 0, v[60:61]
	s_and_b64 s[0:1], s[24:25], exec
	v_readlane_b32 s40, v251, 0
	s_cselect_b32 s0, 0x6c00000, 0
	s_cselect_b32 s1, 0xc000, 0
	s_lshl_b32 s4, s2, 2
	v_readlane_b32 s42, v251, 2
	v_readlane_b32 s43, v251, 3
	s_add_u32 s24, s42, s4
	s_addc_u32 s25, s43, 0
	v_lshl_add_u64 v[44:45], s[26:27], 0, v[0:1]
	v_lshl_add_u64 v[46:47], s[26:27], 0, v[46:47]
	v_lshl_add_u64 v[48:49], s[26:27], 0, v[48:49]
	v_lshl_add_u64 v[60:61], s[26:27], 0, v[60:61]
	v_readlane_b32 s41, v251, 1
	s_add_u32 s26, s40, s2
	v_readlane_b32 s60, v251, 52
	s_addc_u32 s27, s41, 0
	v_readlane_b32 s74, v252, 2
	v_readlane_b32 s75, v252, 3
	s_add_u32 s38, s74, s3
	v_readlane_b32 s72, v252, 0
	s_addc_u32 s39, s75, 0
	v_readlane_b32 s73, v252, 1
	s_add_u32 s42, s72, s3
	v_readlane_b32 s66, v251, 58
	s_addc_u32 s43, s73, 0
	v_readlane_b32 s61, v251, 53
	v_readlane_b32 s62, v251, 54
	v_readlane_b32 s63, v251, 55
	v_readlane_b32 s64, v251, 56
	v_readlane_b32 s65, v251, 57
	v_readlane_b32 s67, v251, 59
	v_readlane_b32 s68, v251, 60
	v_readlane_b32 s69, v251, 61
	v_readlane_b32 s70, v251, 62
	v_readlane_b32 s71, v251, 63
	s_add_u32 s50, s66, s2
	s_addc_u32 s51, s67, 0
	v_readlane_b32 s60, v251, 20
	v_readlane_b32 s66, v251, 26
	v_readlane_b32 s67, v251, 27
	s_add_u32 s54, s66, s0
	v_readlane_b32 s64, v251, 24
	s_addc_u32 s55, s67, 0
	v_readlane_b32 s65, v251, 25
	s_add_u32 s0, s64, s1
	s_addc_u32 s1, s65, 0
	v_lshlrev_b32_e32 v50, 1, v2
	v_mov_b32_e32 v51, v1
	s_add_u32 s64, s0, 0x4000
	v_cmp_eq_u32_e64 s[36:37], 0, v194
	v_lshl_add_u64 v[4:5], v[4:5], 0, v[50:51]
	v_lshl_add_u64 v[6:7], v[6:7], 0, v[50:51]
	v_lshl_add_u64 v[8:9], v[8:9], 0, v[50:51]
	v_lshl_add_u64 v[10:11], v[10:11], 0, v[50:51]
	v_lshl_add_u64 v[12:13], v[12:13], 0, v[50:51]
	v_lshl_add_u64 v[14:15], v[14:15], 0, v[50:51]
	v_lshl_add_u64 v[16:17], v[16:17], 0, v[50:51]
	v_lshl_add_u64 v[18:19], v[18:19], 0, v[50:51]
	v_lshl_add_u64 v[20:21], v[20:21], 0, v[50:51]
	v_lshl_add_u64 v[22:23], v[22:23], 0, v[50:51]
	v_lshl_add_u64 v[24:25], v[24:25], 0, v[50:51]
	v_lshl_add_u64 v[26:27], v[26:27], 0, v[50:51]
	v_lshl_add_u64 v[28:29], v[28:29], 0, v[50:51]
	v_lshl_add_u64 v[30:31], v[30:31], 0, v[50:51]
	v_lshl_add_u64 v[32:33], v[32:33], 0, v[50:51]
	v_lshl_add_u64 v[34:35], v[34:35], 0, v[50:51]
	v_lshl_add_u64 v[36:37], v[36:37], 0, v[50:51]
	v_lshl_add_u64 v[38:39], v[38:39], 0, v[50:51]
	v_lshl_add_u64 v[40:41], v[40:41], 0, v[50:51]
	v_lshl_add_u64 v[42:43], v[42:43], 0, v[50:51]
	v_lshl_add_u64 v[44:45], v[44:45], 0, v[50:51]
	v_lshl_add_u64 v[46:47], v[46:47], 0, v[50:51]
	v_lshl_add_u64 v[48:49], v[48:49], 0, v[50:51]
	v_lshl_add_u64 v[50:51], v[60:61], 0, v[50:51]
	s_addc_u32 s65, s1, 0
	v_readlane_b32 s44, v251, 4
	v_readlane_b32 s45, v251, 5
	v_readlane_b32 s46, v251, 6
	v_readlane_b32 s47, v251, 7
	v_readlane_b32 s61, v251, 21
	v_readlane_b32 s62, v251, 22
	v_readlane_b32 s63, v251, 23
	v_readlane_b32 s68, v251, 28
	v_readlane_b32 s69, v251, 29
	v_readlane_b32 s70, v251, 30
	v_readlane_b32 s71, v251, 31
	v_readlane_b32 s72, v251, 32
	v_readlane_b32 s73, v251, 33
	v_readlane_b32 s74, v251, 34
	v_readlane_b32 s75, v251, 35
	s_and_saveexec_b64 s[0:1], s[36:37]
	global_atomic_add v100, v1, v224, s[22:23] sc0
	s_or_b64 exec, exec, s[0:1]
	s_waitcnt vmcnt(0)
	s_branch .LBB0_969

; __device__ __forceinline__ void cvt_tile(unsigned char* shm, int tid, const float* src, bf16_t* dst, int K, int N, int mode, const float* kscale, int ldd, int t) {
;     bf16_t* T = (bf16_t*)shm;
;     const int nnt = N / 256, nti = t % nnt, kt = t / nnt;
;     { const int k = tid >> 3, n8 = (tid & 7) * 8;
;       const float* s = src + (size_t)(kt * 64 + k) * N + nti * 256 + n8; const float ks = kscale ? kscale[kt * 64 + k] : 1.0f;
;       f32x4 v[8];
; #pragma unroll
;       for (int q = 0; q < 4; ++q) { v[2 * q] = *(const f32x4*)(s + q * 64); v[2 * q + 1] = *(const f32x4*)(s + q * 64 + 4); }
;       asm volatile("" ::: "memory");
; #pragma unroll
;       for (int q = 0; q < 4; ++q)
; #pragma unroll
;           for (int j = 0; j < 4; ++j) { T[(q * 64 + n8 + j) * 72 + k] = f2bf(v[2 * q][j] * ks); T[(q * 64 + n8 + 4 + j) * 72 + k] = f2bf(v[2 * q + 1][j] * ks); } }
;     __syncthreads();
; #pragma unroll
;     for (int q = 0; q < 4; ++q) { const int n = q * 64 + (tid >> 3), k8 = (tid & 7) * 8; const int nn = nti * 256 + n;
;       const int drow = mode == 0 ? nn : ((nn >> 7) * 256 + (nn & 127) + (mode == 2 ? 128 : 0));
;       *(u32x4*)(dst + ((size_t)((drow >> 8) * (K / 64) + kt) * 256 + (drow & 255)) * 64 + k8) = *(const u32x4*)(T + n * 72 + k8); }
;     __syncthreads();
; }
; __device__ __forceinline__ void cvt_ffn_tile(const Params& p, unsigned char* shm, int tid, bf16_t* W, int l, int sub, int t) {
;     const size_t wo = (size_t)(l * 2 + sub) * DM * DFF; const float* gk = p.in[2] + (l * 6 + (sub ? 4 : 0)) * DM;
;     if (t < 704) cvt_tile(shm, tid, p.in[26] + wo, W + W_13, DM, DFF, 1, gk, LDX, t);
;     else if (t < 1408) cvt_tile(shm, tid, p.in[27] + wo, W + W_13, DM, DFF, 2, gk, LDX, t - 704);
;     else cvt_tile(shm, tid, p.in[28] + wo, W + W_2, DFF, DM, 0, nullptr, DFF, t - 1408);
; }
; __device__ __forceinline__ void cvt_mixer_tile(const Params& p, unsigned char* shm, int tid, bf16_t* W, int l, int t) {
;     if (t < 1728) cvt_tile(shm, tid, p.in[3] + (size_t)l * DM * 13824, W + W_IN, DM, 13824, 0, p.in[2] + (l * 6 + 2) * DM, LDX, t);
;     else if (t < 1792) cvt_tile(shm, tid, p.in[19] + (size_t)l * 1024 * 1024, W + W_GLU, 1024, 1024, 0, nullptr, 1024, t - 1728);
;     else if (t < 1920) cvt_tile(shm, tid, p.in[22] + (size_t)l * 1024 * DM, W + W_BRL, 1024, DM, 0, nullptr, 1024, t - 1792);
.LBB0_972:
	s_or_b64 exec, exec, s[40:41]
	s_mov_b64 s[2:3], src_shared_base
	s_waitcnt vmcnt(4)
	v_readfirstlane_b32 s2, v100
	s_nop 1
	v_add_u32_e32 v0, s2, v0
	s_add_i32 s2, 0, 0x20080
	s_cmp_lg_u32 s2, -1
	s_cselect_b32 s2, s2, 0
	s_cselect_b32 s3, s3, 0
	v_mov_b32_e32 v60, s2
	v_mov_b32_e32 v61, s3
	ds_write_b32 v60, v0
	global_atomic_add v100, v1, v224, s[22:23] sc0
.LBB0_973:
	s_or_b64 exec, exec, s[0:1]
	s_mov_b64 s[0:1], src_shared_base
	s_add_i32 s0, 0, 0x20080
	s_cmp_lg_u32 s0, -1
	s_cselect_b32 s0, s0, 0
	s_cselect_b32 s1, s1, 0
	v_mov_b32_e32 v60, s0
	v_mov_b32_e32 v61, s1
	s_waitcnt lgkmcnt(0)
	s_barrier
	ds_read_b32 v0, v60
	s_mov_b64 s[0:1], -1
	s_waitcnt lgkmcnt(0)
	s_barrier
	v_readfirstlane_b32 s2, v0
	s_cmpk_gt_i32 s2, 0x93f
	s_cbranch_scc1 .LBB0_968
	s_cmpk_gt_i32 s2, 0x6bf
	s_cbranch_scc0 .LBB0_992
	s_cmpk_gt_u32 s2, 0x6ff
	s_cbranch_scc0 .LBB0_989
	s_cmpk_gt_u32 s2, 0x77f
	s_cbranch_scc0 .LBB0_986
	s_cmpk_gt_u32 s2, 0x7ff
	s_cbranch_scc0 .LBB0_983
	s_cmpk_gt_u32 s2, 0x83f
	s_cbranch_scc0 .LBB0_980
	s_add_i32 s1, s2, 0xc0
	s_bfe_u32 s0, s1, 0x50003
	v_lshl_add_u32 v60, s0, 6, v3
	v_ashrrev_i32_e32 v61, 31, v60
	s_lshl_b32 s0, s2, 8
	v_lshlrev_b64 v[60:61], 13, v[60:61]
	s_and_b32 s0, s0, 0x700
	v_lshl_add_u64 v[60:61], s[24:25], 0, v[60:61]
	s_lshl_b32 s48, s0, 2
	v_lshl_add_u64 v[60:61], v[60:61], 0, s[48:49]
	v_lshlrev_b32_e32 v0, 2, v2
	v_lshl_add_u64 v[88:89], v[60:61], 0, v[0:1]
	global_load_dwordx4 v[60:63], v[88:89], off
	global_load_dwordx4 v[64:67], v[88:89], off offset:16
	global_load_dwordx4 v[68:71], v[88:89], off offset:256
	global_load_dwordx4 v[72:75], v[88:89], off offset:272
	global_load_dwordx4 v[76:79], v[88:89], off offset:512
	global_load_dwordx4 v[80:83], v[88:89], off offset:528
	global_load_dwordx4 v[84:87], v[88:89], off offset:768
	s_nop 0
	global_load_dwordx4 v[88:91], v[88:89], off offset:784
	s_lshr_b32 s1, s1, 3
	v_add_u32_e32 v0, s0, v3
	v_ashrrev_i32_e32 v0, 3, v0
	s_waitcnt vmcnt(7)
	v_cvt_pk_bf16_f32 v59, v60, v1
	s_waitcnt vmcnt(6)
	v_cvt_pk_bf16_f32 v60, v64, v1
	v_cvt_pk_bf16_f32 v61, v61, v1
	v_cvt_pk_bf16_f32 v64, v65, v1
	v_cvt_pk_bf16_f32 v62, v62, v1
	v_cvt_pk_bf16_f32 v65, v66, v1
	v_cvt_pk_bf16_f32 v63, v63, v1
	v_cvt_pk_bf16_f32 v66, v67, v1
	s_waitcnt vmcnt(5)
	v_cvt_pk_bf16_f32 v67, v68, v1
	s_waitcnt vmcnt(4)
	v_cvt_pk_bf16_f32 v68, v72, v1
	v_cvt_pk_bf16_f32 v69, v69, v1
	v_cvt_pk_bf16_f32 v72, v73, v1
	v_cvt_pk_bf16_f32 v70, v70, v1
	v_cvt_pk_bf16_f32 v73, v74, v1
	v_cvt_pk_bf16_f32 v71, v71, v1
	v_cvt_pk_bf16_f32 v74, v75, v1
	s_waitcnt vmcnt(3)
	v_cvt_pk_bf16_f32 v75, v76, v1
	s_waitcnt vmcnt(2)
	v_cvt_pk_bf16_f32 v76, v80, v1
	v_cvt_pk_bf16_f32 v77, v77, v1
	v_cvt_pk_bf16_f32 v80, v81, v1
	v_cvt_pk_bf16_f32 v78, v78, v1
	v_cvt_pk_bf16_f32 v81, v82, v1
	v_cvt_pk_bf16_f32 v79, v79, v1
	v_cvt_pk_bf16_f32 v82, v83, v1
	s_waitcnt vmcnt(1)
	v_cvt_pk_bf16_f32 v83, v84, v1
	s_waitcnt vmcnt(0)
	v_cvt_pk_bf16_f32 v84, v88, v1
	v_cvt_pk_bf16_f32 v85, v85, v1
	v_cvt_pk_bf16_f32 v88, v89, v1
	v_cvt_pk_bf16_f32 v86, v86, v1
	v_cvt_pk_bf16_f32 v89, v90, v1
	v_cvt_pk_bf16_f32 v87, v87, v1
	v_cvt_pk_bf16_f32 v90, v91, v1
	ds_write_b16 v52, v59
	ds_write_b16 v53, v60 offset:576
	ds_write_b16 v52, v61 offset:144
	ds_write_b16 v53, v64 offset:720
	ds_write_b16 v52, v62 offset:288
	ds_write_b16 v53, v65 offset:864
	ds_write_b16 v52, v63 offset:432
	ds_write_b16 v53, v66 offset:1008
	ds_write_b16 v52, v67 offset:9216
	ds_write_b16 v53, v68 offset:9792
	ds_write_b16 v52, v69 offset:9360
	ds_write_b16 v53, v72 offset:9936
	ds_write_b16 v52, v70 offset:9504
	ds_write_b16 v53, v73 offset:10080
	ds_write_b16 v52, v71 offset:9648
	ds_write_b16 v53, v74 offset:10224
	ds_write_b16 v52, v75 offset:18432
	ds_write_b16 v53, v76 offset:19008
	ds_write_b16 v52, v77 offset:18576
	ds_write_b16 v53, v80 offset:19152
	ds_write_b16 v52, v78 offset:18720
	ds_write_b16 v53, v81 offset:19296
	ds_write_b16 v52, v79 offset:18864
	ds_write_b16 v53, v82 offset:19440
	ds_write_b16 v52, v83 offset:27648
	ds_write_b16 v53, v84 offset:28224
	ds_write_b16 v52, v85 offset:27792
	ds_write_b16 v53, v88 offset:28368
	ds_write_b16 v52, v86 offset:27936
	ds_write_b16 v53, v89 offset:28512
	ds_write_b16 v52, v87 offset:28080
	ds_write_b16 v53, v90 offset:28656
	v_add_u32_e32 v59, v54, v55
	s_waitcnt lgkmcnt(0)
	s_barrier
	ds_read_b128 v[60:63], v59
	v_mov_b32_e32 v70, s1
	s_movk_i32 s1, 0xffe0
	v_bfi_b32 v64, s1, v0, v70
	v_ashrrev_i32_e32 v65, 31, v64
	v_lshlrev_b64 v[64:65], 15, v[64:65]
	v_add_u32_e32 v0, s0, v56
	v_lshl_add_u64 v[68:69], v[4:5], 0, v[64:65]
	ds_read_b128 v[64:67], v59 offset:9216
	v_ashrrev_i32_e32 v0, 3, v0
	s_waitcnt lgkmcnt(1)
	global_store_dwordx4 v[68:69], v[60:63], off
	s_nop 1
	v_bfi_b32 v60, s1, v0, v70
	v_ashrrev_i32_e32 v61, 31, v60
	v_lshlrev_b64 v[60:61], 15, v[60:61]
	v_lshl_add_u64 v[60:61], v[6:7], 0, v[60:61]
	v_add_u32_e32 v0, s0, v57
	s_waitcnt lgkmcnt(0)
	global_store_dwordx4 v[60:61], v[64:67], off
	ds_read_b128 v[60:63], v59 offset:18432
	v_ashrrev_i32_e32 v0, 3, v0
	v_bfi_b32 v64, s1, v0, v70
	v_ashrrev_i32_e32 v65, 31, v64
	v_lshlrev_b64 v[64:65], 15, v[64:65]
	v_add_u32_e32 v0, s0, v58
	v_lshl_add_u64 v[68:69], v[8:9], 0, v[64:65]
	ds_read_b128 v[64:67], v59 offset:27648
	v_ashrrev_i32_e32 v0, 3, v0
	s_waitcnt lgkmcnt(1)
	global_store_dwordx4 v[68:69], v[60:63], off
	s_nop 1
	v_bfi_b32 v60, s1, v0, v70
	v_ashrrev_i32_e32 v61, 31, v60
	v_lshlrev_b64 v[60:61], 15, v[60:61]
	v_lshl_add_u64 v[60:61], v[10:11], 0, v[60:61]
	s_waitcnt lgkmcnt(0)
	global_store_dwordx4 v[60:61], v[64:67], off
	s_barrier
	s_mov_b64 s[0:1], 0

; __device__ __forceinline__ bf16_t f2bf(float f) { return (bf16_t)(cvt_pk_bf16(f, 0.f) & 0xffffu); }
; __device__ __forceinline__ void cvt_tile(unsigned char* shm, int tid, const float* src, bf16_t* dst, int K, int N, int mode, const float* kscale, int ldd, int t) {
;     bf16_t* T = (bf16_t*)shm;
;     const int nnt = N / 256, nti = t % nnt, kt = t / nnt;
;     { const int k = tid >> 3, n8 = (tid & 7) * 8;
;       const float* s = src + (size_t)(kt * 64 + k) * N + nti * 256 + n8; const float ks = kscale ? kscale[kt * 64 + k] : 1.0f;
;       f32x4 v[8];
; #pragma unroll
;       for (int q = 0; q < 4; ++q) { v[2 * q] = *(const f32x4*)(s + q * 64); v[2 * q + 1] = *(const f32x4*)(s + q * 64 + 4); }
;       asm volatile("" ::: "memory");
; #pragma unroll
;       for (int q = 0; q < 4; ++q)
; #pragma unroll
;           for (int j = 0; j < 4; ++j) { T[(q * 64 + n8 + j) * 72 + k] = f2bf(v[2 * q][j] * ks); T[(q * 64 + n8 + 4 + j) * 72 + k] = f2bf(v[2 * q + 1][j] * ks); } }
;     __syncthreads();
; #pragma unroll
;     for (int q = 0; q < 4; ++q) { const int n = q * 64 + (tid >> 3), k8 = (tid & 7) * 8; const int nn = nti * 256 + n;
;       const int drow = mode == 0 ? nn : ((nn >> 7) * 256 + (nn & 127) + (mode == 2 ? 128 : 0));
;       *(u32x4*)(dst + ((size_t)((drow >> 8) * (K / 64) + kt) * 256 + (drow & 255)) * 64 + k8) = *(const u32x4*)(T + n * 72 + k8); }
;     __syncthreads();
.LBB0_1020:
	s_and_b64 vcc, exec, s[0:1]
	s_cbranch_vccz .LBB0_1053
	v_mov_b32_e32 v0, v229
	s_mov_b32 s2, s80
	s_cmpk_gt_i32 s2, 0x83f
	s_cbranch_scc1 .LBB0_1038
	v_ashrrev_i32_e32 v3, 3, v0
	v_lshlrev_b32_e32 v0, 3, v0
	s_waitcnt lgkmcnt(0)
	v_and_b32_e32 v2, 56, v0
	s_waitcnt vmcnt(0)
	v_mul_u32_u24_e32 v4, 0x48, v2
	v_lshlrev_b32_e32 v0, 1, v3
	v_lshlrev_b32_e32 v26, 1, v2
	v_xor_b32_e32 v0, v0, v26
	v_lshlrev_b32_e32 v4, 1, v4
	v_add_u32_e32 v30, 64, v3
	v_add_u32_e32 v31, 0x80, v3
	v_add_u32_e32 v32, 0xc0, v3
	s_add_u32 s0, s20, 0x2d60000
	v_add3_u32 v26, 0, v0, v4
	v_add_u32_e32 v4, 0, v4
	v_lshlrev_b32_e32 v12, 7, v3
	v_lshlrev_b32_e32 v14, 7, v30
	v_lshlrev_b32_e32 v8, 7, v31
	v_lshlrev_b32_e32 v16, 7, v32
	s_addc_u32 s1, s21, 0
	v_add_u32_e32 v27, v4, v0
	s_movk_i32 s3, 0xff72
	v_and_b32_e32 v0, 0x7f80, v12
	v_and_b32_e32 v6, 0x7f80, v14
	v_mov_b32_e32 v7, v1
	v_and_b32_e32 v8, 0x7f80, v8
	v_mov_b32_e32 v9, v1
	v_and_b32_e32 v10, 0x7f80, v16
	v_mov_b32_e32 v11, v1
	v_and_b32_e32 v12, 0x3f80, v12
	v_mov_b32_e32 v13, v1
	v_and_b32_e32 v14, 0x3f80, v14
	v_mov_b32_e32 v15, v1
	v_and_b32_e32 v16, 0x3f80, v16
	v_mov_b32_e32 v17, v1
	v_mad_i32_i24 v28, v2, s3, v4
	v_lshlrev_b32_e32 v33, 1, v3
	v_and_b32_e32 v33, 0x70, v33
	v_xor_b32_e32 v28, v28, v33
	s_movk_i32 s3, 0x90
	v_lshl_add_u64 v[4:5], s[0:1], 0, v[0:1]
	v_lshlrev_b32_e32 v0, 1, v2
	v_lshl_add_u64 v[6:7], s[0:1], 0, v[6:7]
	v_lshl_add_u64 v[8:9], s[0:1], 0, v[8:9]
	v_lshl_add_u64 v[10:11], s[0:1], 0, v[10:11]
	v_lshl_add_u64 v[12:13], s[20:21], 0, v[12:13]
	v_lshl_add_u64 v[14:15], s[20:21], 0, v[14:15]
	v_lshl_add_u64 v[16:17], s[20:21], 0, v[16:17]
	v_readlane_b32 s0, v251, 10
	v_mul_lo_u32 v29, v3, s3
	v_lshl_add_u64 v[4:5], v[4:5], 0, v[0:1]
	v_lshl_add_u64 v[6:7], v[6:7], 0, v[0:1]
	v_lshl_add_u64 v[8:9], v[8:9], 0, v[0:1]
	v_lshl_add_u64 v[10:11], v[10:11], 0, v[0:1]
	v_lshl_add_u64 v[18:19], v[12:13], 0, v[0:1]
	v_lshl_add_u64 v[20:21], v[14:15], 0, v[0:1]
	v_lshl_add_u64 v[22:23], v[16:17], 0, v[0:1]
	s_lshl_b32 s3, s2, 8
	s_lshl_b32 s4, s0, 8
	v_readlane_b32 s1, v251, 11
	s_branch .LBB0_1026
